# remove mid-MFMA-block setprio 0/1 flip pairs and redundant post-barrier lgkmcnt(0) in all GEMM K-loops
# speedup vs baseline: 1.0008x; 1.0008x over previous
.LBB0_91:
	ds_read_b128 v[150:153], v158
	ds_read_b128 v[162:165], v158 offset:1024
	ds_read_b128 v[166:169], v158 offset:2048
	ds_read_b128 v[170:173], v158 offset:3072
	ds_read_b128 v[174:177], v159
	ds_read_b128 v[178:181], v159 offset:1024
	ds_read_b128 v[182:185], v159 offset:2048
	ds_read_b128 v[186:189], v159 offset:3072
	s_add_u32 s36, s34, 0xfff00080
	s_addc_u32 s37, s35, -1
	s_cmp_eq_u32 s57, 60
	s_cselect_b32 s39, s2, s37
	s_cselect_b32 s38, s25, s36
	s_cselect_b32 s37, s23, s56
	s_cselect_b32 s36, s54, s55
	v_lshl_add_u64 v[146:147], s[34:35], 0, v[138:139]
	s_add_i32 m0, s43, 0xc000
	ds_read_b128 v[190:193], v160
	ds_read_b128 v[194:197], v160 offset:1024
	ds_read_b128 v[198:201], v160 offset:2048
	ds_read_b128 v[202:205], v160 offset:3072
	ds_read_b128 v[206:209], v160 offset:4096
	ds_read_b128 v[210:213], v160 offset:5120
	ds_read_b128 v[214:217], v160 offset:6144
	ds_read_b128 v[218:221], v160 offset:7168
	global_load_lds_dwordx4 v[146:147], off
	v_lshl_add_u64 v[146:147], s[34:35], 0, v[140:141]
	s_add_i32 m0, s43, 0xe000
	s_nop 0
	global_load_lds_dwordx4 v[146:147], off
	s_waitcnt vmcnt(8)
	s_waitcnt lgkmcnt(0)
	s_barrier
	s_setprio 1
	v_mfma_f32_16x16x32_bf16 v[78:81], v[150:153], v[190:193], v[78:81]
	v_mfma_f32_16x16x32_bf16 v[70:73], v[166:169], v[190:193], v[70:73]
	v_mfma_f32_16x16x32_bf16 v[62:65], v[150:153], v[198:201], v[62:65]
	v_mfma_f32_16x16x32_bf16 v[58:61], v[166:169], v[198:201], v[58:61]
	v_mfma_f32_16x16x32_bf16 v[54:57], v[150:153], v[206:209], v[54:57]
	v_mfma_f32_16x16x32_bf16 v[50:53], v[166:169], v[206:209], v[50:53]
	v_mfma_f32_16x16x32_bf16 v[46:49], v[150:153], v[214:217], v[46:49]
	v_mfma_f32_16x16x32_bf16 v[42:45], v[166:169], v[214:217], v[42:45]
	v_mfma_f32_16x16x32_bf16 v[78:81], v[162:165], v[194:197], v[78:81]
	v_mfma_f32_16x16x32_bf16 v[70:73], v[170:173], v[194:197], v[70:73]
	v_mfma_f32_16x16x32_bf16 v[62:65], v[162:165], v[202:205], v[62:65]
	v_mfma_f32_16x16x32_bf16 v[58:61], v[170:173], v[202:205], v[58:61]
	v_mfma_f32_16x16x32_bf16 v[54:57], v[162:165], v[210:213], v[54:57]
	v_mfma_f32_16x16x32_bf16 v[50:53], v[170:173], v[210:213], v[50:53]
	v_mfma_f32_16x16x32_bf16 v[46:49], v[162:165], v[218:221], v[46:49]
	v_mfma_f32_16x16x32_bf16 v[42:45], v[170:173], v[218:221], v[42:45]
	v_mfma_f32_16x16x32_bf16 v[126:129], v[174:177], v[190:193], v[126:129]
	v_mfma_f32_16x16x32_bf16 v[122:125], v[182:185], v[190:193], v[122:125]
	v_mfma_f32_16x16x32_bf16 v[118:121], v[174:177], v[198:201], v[118:121]
	v_mfma_f32_16x16x32_bf16 v[114:117], v[182:185], v[198:201], v[114:117]
	v_mfma_f32_16x16x32_bf16 v[110:113], v[174:177], v[206:209], v[110:113]
	v_mfma_f32_16x16x32_bf16 v[106:109], v[182:185], v[206:209], v[106:109]
	v_mfma_f32_16x16x32_bf16 v[102:105], v[174:177], v[214:217], v[102:105]
	v_mfma_f32_16x16x32_bf16 v[98:101], v[182:185], v[214:217], v[98:101]
	v_mfma_f32_16x16x32_bf16 v[126:129], v[178:181], v[194:197], v[126:129]
	v_mfma_f32_16x16x32_bf16 v[122:125], v[186:189], v[194:197], v[122:125]
	v_mfma_f32_16x16x32_bf16 v[118:121], v[178:181], v[202:205], v[118:121]
	v_mfma_f32_16x16x32_bf16 v[114:117], v[186:189], v[202:205], v[114:117]
	v_mfma_f32_16x16x32_bf16 v[110:113], v[178:181], v[210:213], v[110:113]
	v_mfma_f32_16x16x32_bf16 v[106:109], v[186:189], v[210:213], v[106:109]
	v_mfma_f32_16x16x32_bf16 v[102:105], v[178:181], v[218:221], v[102:105]
	v_mfma_f32_16x16x32_bf16 v[98:101], v[186:189], v[218:221], v[98:101]
	s_setprio 0
	s_barrier
	s_add_i32 s58, s51, s40
	v_lshl_add_u64 v[146:147], s[36:37], 0, v[134:135]
	s_mov_b32 m0, s58
	ds_read_b128 v[190:193], v160 offset:16384
	ds_read_b128 v[194:197], v160 offset:17408
	ds_read_b128 v[198:201], v160 offset:18432
	ds_read_b128 v[202:205], v160 offset:19456
	ds_read_b128 v[206:209], v160 offset:20480
	ds_read_b128 v[210:213], v160 offset:21504
	ds_read_b128 v[214:217], v160 offset:22528
	ds_read_b128 v[218:221], v160 offset:23552
	global_load_lds_dwordx4 v[146:147], off
	s_add_i32 m0, s58, 0x2000
	s_add_u32 s58, s36, 0x100000
	v_lshl_add_u64 v[222:223], s[36:37], 0, v[130:131]
	s_addc_u32 s59, s37, 0
	s_add_i32 s60, s52, s40
	global_load_lds_dwordx4 v[222:223], off
	v_lshl_add_u64 v[224:225], s[58:59], 0, v[134:135]
	s_mov_b32 m0, s60
	v_lshl_add_u64 v[226:227], s[38:39], 0, v[132:133]
	global_load_lds_dwordx4 v[224:225], off
	v_lshl_add_u64 v[224:225], s[58:59], 0, v[130:131]
	s_add_i32 m0, s60, 0x2000
	s_nop 0
	global_load_lds_dwordx4 v[224:225], off
	v_lshl_add_u64 v[224:225], s[38:39], 0, v[136:137]
	s_mov_b32 m0, s43
	s_nop 0
	global_load_lds_dwordx4 v[224:225], off
	s_mov_b32 m0, s44
	s_nop 0
	global_load_lds_dwordx4 v[226:227], off
	s_waitcnt vmcnt(8)
	s_waitcnt lgkmcnt(0)
	s_barrier
	s_setprio 1
	v_mfma_f32_16x16x32_bf16 v[30:33], v[150:153], v[190:193], v[30:33]
	v_mfma_f32_16x16x32_bf16 v[26:29], v[166:169], v[190:193], v[26:29]
	v_mfma_f32_16x16x32_bf16 v[22:25], v[150:153], v[198:201], v[22:25]
	v_mfma_f32_16x16x32_bf16 v[18:21], v[166:169], v[198:201], v[18:21]
	v_mfma_f32_16x16x32_bf16 v[14:17], v[150:153], v[206:209], v[14:17]
	v_mfma_f32_16x16x32_bf16 v[10:13], v[166:169], v[206:209], v[10:13]
	v_mfma_f32_16x16x32_bf16 v[6:9], v[150:153], v[214:217], v[6:9]
	v_mfma_f32_16x16x32_bf16 v[2:5], v[166:169], v[214:217], v[2:5]
	v_mfma_f32_16x16x32_bf16 v[30:33], v[162:165], v[194:197], v[30:33]
	v_mfma_f32_16x16x32_bf16 v[26:29], v[170:173], v[194:197], v[26:29]
	v_mfma_f32_16x16x32_bf16 v[22:25], v[162:165], v[202:205], v[22:25]
	v_mfma_f32_16x16x32_bf16 v[18:21], v[170:173], v[202:205], v[18:21]
	v_mfma_f32_16x16x32_bf16 v[14:17], v[162:165], v[210:213], v[14:17]
	v_mfma_f32_16x16x32_bf16 v[10:13], v[170:173], v[210:213], v[10:13]
	v_mfma_f32_16x16x32_bf16 v[6:9], v[162:165], v[218:221], v[6:9]
	v_mfma_f32_16x16x32_bf16 v[2:5], v[170:173], v[218:221], v[2:5]
	v_mfma_f32_16x16x32_bf16 v[94:97], v[174:177], v[190:193], v[94:97]
	v_mfma_f32_16x16x32_bf16 v[90:93], v[182:185], v[190:193], v[90:93]
	v_mfma_f32_16x16x32_bf16 v[86:89], v[174:177], v[198:201], v[86:89]
	v_mfma_f32_16x16x32_bf16 v[82:85], v[182:185], v[198:201], v[82:85]
	v_mfma_f32_16x16x32_bf16 v[74:77], v[174:177], v[206:209], v[74:77]
	v_mfma_f32_16x16x32_bf16 v[66:69], v[182:185], v[206:209], v[66:69]
	v_mfma_f32_16x16x32_bf16 v[38:41], v[174:177], v[214:217], v[38:41]
	v_mfma_f32_16x16x32_bf16 v[34:37], v[182:185], v[214:217], v[34:37]
	v_mfma_f32_16x16x32_bf16 v[94:97], v[178:181], v[194:197], v[94:97]
	v_mfma_f32_16x16x32_bf16 v[90:93], v[186:189], v[194:197], v[90:93]
	v_mfma_f32_16x16x32_bf16 v[86:89], v[178:181], v[202:205], v[86:89]
	v_mfma_f32_16x16x32_bf16 v[82:85], v[186:189], v[202:205], v[82:85]
	v_mfma_f32_16x16x32_bf16 v[74:77], v[178:181], v[210:213], v[74:77]
	v_mfma_f32_16x16x32_bf16 v[66:69], v[186:189], v[210:213], v[66:69]
	v_mfma_f32_16x16x32_bf16 v[38:41], v[178:181], v[218:221], v[38:41]
	v_mfma_f32_16x16x32_bf16 v[34:37], v[186:189], v[218:221], v[34:37]
	s_setprio 0
	s_barrier
	s_add_i32 s58, 0, 0x18000
	v_add_u32_e32 v148, s58, v156
	s_add_i32 s59, 0, 0x1c000
	ds_read_b128 v[150:153], v148
	ds_read_b128 v[162:165], v148 offset:1024
	ds_read_b128 v[166:169], v148 offset:2048
	ds_read_b128 v[170:173], v148 offset:3072
	v_add_u32_e32 v148, s59, v156
	ds_read_b128 v[174:177], v148
	ds_read_b128 v[178:181], v148 offset:1024
	ds_read_b128 v[182:185], v148 offset:2048
	ds_read_b128 v[186:189], v148 offset:3072
	s_add_u32 s38, s38, 0x100000
	s_addc_u32 s39, s39, 0
	s_mov_b32 m0, s45
	v_lshl_add_u64 v[228:229], s[38:39], 0, v[136:137]
	ds_read_b128 v[190:193], v160 offset:32768
	ds_read_b128 v[194:197], v160 offset:33792
	ds_read_b128 v[198:201], v160 offset:34816
	ds_read_b128 v[202:205], v160 offset:35840
	ds_read_b128 v[206:209], v160 offset:36864
	ds_read_b128 v[210:213], v160 offset:37888
	ds_read_b128 v[214:217], v160 offset:38912
	ds_read_b128 v[218:221], v160 offset:39936
	global_load_lds_dwordx4 v[228:229], off
	v_lshl_add_u64 v[228:229], s[38:39], 0, v[132:133]
	s_mov_b32 m0, s46
	s_nop 0
	global_load_lds_dwordx4 v[228:229], off
	s_waitcnt vmcnt(8)
	s_waitcnt lgkmcnt(0)
	s_barrier
	s_setprio 1
	v_mfma_f32_16x16x32_bf16 v[78:81], v[150:153], v[190:193], v[78:81]
	v_mfma_f32_16x16x32_bf16 v[70:73], v[166:169], v[190:193], v[70:73]
	v_mfma_f32_16x16x32_bf16 v[62:65], v[150:153], v[198:201], v[62:65]
	v_mfma_f32_16x16x32_bf16 v[58:61], v[166:169], v[198:201], v[58:61]
	v_mfma_f32_16x16x32_bf16 v[54:57], v[150:153], v[206:209], v[54:57]
	v_mfma_f32_16x16x32_bf16 v[50:53], v[166:169], v[206:209], v[50:53]
	v_mfma_f32_16x16x32_bf16 v[46:49], v[150:153], v[214:217], v[46:49]
	v_mfma_f32_16x16x32_bf16 v[42:45], v[166:169], v[214:217], v[42:45]
	v_mfma_f32_16x16x32_bf16 v[78:81], v[162:165], v[194:197], v[78:81]
	v_mfma_f32_16x16x32_bf16 v[70:73], v[170:173], v[194:197], v[70:73]
	v_mfma_f32_16x16x32_bf16 v[62:65], v[162:165], v[202:205], v[62:65]
	v_mfma_f32_16x16x32_bf16 v[58:61], v[170:173], v[202:205], v[58:61]
	v_mfma_f32_16x16x32_bf16 v[54:57], v[162:165], v[210:213], v[54:57]
	v_mfma_f32_16x16x32_bf16 v[50:53], v[170:173], v[210:213], v[50:53]
	v_mfma_f32_16x16x32_bf16 v[46:49], v[162:165], v[218:221], v[46:49]
	v_mfma_f32_16x16x32_bf16 v[42:45], v[170:173], v[218:221], v[42:45]
	v_mfma_f32_16x16x32_bf16 v[126:129], v[174:177], v[190:193], v[126:129]
	v_mfma_f32_16x16x32_bf16 v[122:125], v[182:185], v[190:193], v[122:125]
	v_mfma_f32_16x16x32_bf16 v[118:121], v[174:177], v[198:201], v[118:121]
	v_mfma_f32_16x16x32_bf16 v[114:117], v[182:185], v[198:201], v[114:117]
	v_mfma_f32_16x16x32_bf16 v[110:113], v[174:177], v[206:209], v[110:113]
	v_mfma_f32_16x16x32_bf16 v[106:109], v[182:185], v[206:209], v[106:109]
	v_mfma_f32_16x16x32_bf16 v[102:105], v[174:177], v[214:217], v[102:105]
	v_mfma_f32_16x16x32_bf16 v[98:101], v[182:185], v[214:217], v[98:101]
	v_mfma_f32_16x16x32_bf16 v[126:129], v[178:181], v[194:197], v[126:129]
	v_mfma_f32_16x16x32_bf16 v[122:125], v[186:189], v[194:197], v[122:125]
	v_mfma_f32_16x16x32_bf16 v[118:121], v[178:181], v[202:205], v[118:121]
	v_mfma_f32_16x16x32_bf16 v[114:117], v[186:189], v[202:205], v[114:117]
	v_mfma_f32_16x16x32_bf16 v[110:113], v[178:181], v[210:213], v[110:113]
	v_mfma_f32_16x16x32_bf16 v[106:109], v[186:189], v[210:213], v[106:109]
	v_mfma_f32_16x16x32_bf16 v[102:105], v[178:181], v[218:221], v[102:105]
	v_mfma_f32_16x16x32_bf16 v[98:101], v[186:189], v[218:221], v[98:101]
	s_setprio 0
	s_barrier
	s_add_i32 s38, s58, s40
	v_lshl_add_u64 v[146:147], v[146:147], 0, s[18:19]
	s_mov_b32 m0, s38
	ds_read_b128 v[190:193], v160 offset:49152
	ds_read_b128 v[194:197], v160 offset:50176
	ds_read_b128 v[198:201], v160 offset:51200
	ds_read_b128 v[202:205], v160 offset:52224
	ds_read_b128 v[206:209], v160 offset:53248
	ds_read_b128 v[210:213], v160 offset:54272
	ds_read_b128 v[214:217], v160 offset:55296
	ds_read_b128 v[218:221], v160 offset:56320
	global_load_lds_dwordx4 v[146:147], off
	s_add_i32 m0, s38, 0x2000
	s_add_u32 s36, s36, 0x100080
	v_lshl_add_u64 v[146:147], v[222:223], 0, s[18:19]
	s_addc_u32 s37, s37, 0
	s_add_i32 s38, s59, s40
	global_load_lds_dwordx4 v[146:147], off
	v_lshl_add_u64 v[146:147], s[36:37], 0, v[134:135]
	s_mov_b32 m0, s38
	s_nop 0
	global_load_lds_dwordx4 v[146:147], off
	v_lshl_add_u64 v[146:147], s[36:37], 0, v[130:131]
	s_add_i32 m0, s38, 0x2000
	s_nop 0
	global_load_lds_dwordx4 v[146:147], off
	v_lshl_add_u64 v[146:147], v[224:225], 0, s[18:19]
	s_mov_b32 m0, s48
	s_nop 0
	global_load_lds_dwordx4 v[146:147], off
	v_lshl_add_u64 v[146:147], v[226:227], 0, s[18:19]
	s_mov_b32 m0, s49
	s_nop 0
	global_load_lds_dwordx4 v[146:147], off
	s_waitcnt vmcnt(8)
	s_waitcnt lgkmcnt(0)
	s_barrier
	s_setprio 1
	v_mfma_f32_16x16x32_bf16 v[30:33], v[150:153], v[190:193], v[30:33]
	v_mfma_f32_16x16x32_bf16 v[26:29], v[166:169], v[190:193], v[26:29]
	v_mfma_f32_16x16x32_bf16 v[22:25], v[150:153], v[198:201], v[22:25]
	v_mfma_f32_16x16x32_bf16 v[18:21], v[166:169], v[198:201], v[18:21]
	v_mfma_f32_16x16x32_bf16 v[14:17], v[150:153], v[206:209], v[14:17]
	v_mfma_f32_16x16x32_bf16 v[10:13], v[166:169], v[206:209], v[10:13]
	v_mfma_f32_16x16x32_bf16 v[6:9], v[150:153], v[214:217], v[6:9]
	v_mfma_f32_16x16x32_bf16 v[2:5], v[166:169], v[214:217], v[2:5]
	v_mfma_f32_16x16x32_bf16 v[30:33], v[162:165], v[194:197], v[30:33]
	v_mfma_f32_16x16x32_bf16 v[26:29], v[170:173], v[194:197], v[26:29]
	v_mfma_f32_16x16x32_bf16 v[22:25], v[162:165], v[202:205], v[22:25]
	v_mfma_f32_16x16x32_bf16 v[18:21], v[170:173], v[202:205], v[18:21]
	v_mfma_f32_16x16x32_bf16 v[14:17], v[162:165], v[210:213], v[14:17]
	v_mfma_f32_16x16x32_bf16 v[10:13], v[170:173], v[210:213], v[10:13]
	v_mfma_f32_16x16x32_bf16 v[6:9], v[162:165], v[218:221], v[6:9]
	v_mfma_f32_16x16x32_bf16 v[2:5], v[170:173], v[218:221], v[2:5]
	v_mfma_f32_16x16x32_bf16 v[94:97], v[174:177], v[190:193], v[94:97]
	v_mfma_f32_16x16x32_bf16 v[90:93], v[182:185], v[190:193], v[90:93]
	v_mfma_f32_16x16x32_bf16 v[86:89], v[174:177], v[198:201], v[86:89]
	v_mfma_f32_16x16x32_bf16 v[82:85], v[182:185], v[198:201], v[82:85]
	v_mfma_f32_16x16x32_bf16 v[74:77], v[174:177], v[206:209], v[74:77]
	v_mfma_f32_16x16x32_bf16 v[66:69], v[182:185], v[206:209], v[66:69]
	v_mfma_f32_16x16x32_bf16 v[38:41], v[174:177], v[214:217], v[38:41]
	v_mfma_f32_16x16x32_bf16 v[34:37], v[182:185], v[214:217], v[34:37]
	v_mfma_f32_16x16x32_bf16 v[94:97], v[178:181], v[194:197], v[94:97]
	v_mfma_f32_16x16x32_bf16 v[90:93], v[186:189], v[194:197], v[90:93]
	v_mfma_f32_16x16x32_bf16 v[86:89], v[178:181], v[202:205], v[86:89]
	v_mfma_f32_16x16x32_bf16 v[82:85], v[186:189], v[202:205], v[82:85]
	v_mfma_f32_16x16x32_bf16 v[74:77], v[178:181], v[210:213], v[74:77]
	v_mfma_f32_16x16x32_bf16 v[66:69], v[186:189], v[210:213], v[66:69]
	v_mfma_f32_16x16x32_bf16 v[38:41], v[178:181], v[218:221], v[38:41]
	v_mfma_f32_16x16x32_bf16 v[34:37], v[186:189], v[218:221], v[34:37]
	s_setprio 0
	s_barrier
	s_add_i32 s57, s57, 2
	s_add_u32 s34, s34, 0x100
	s_addc_u32 s35, s35, 0
	s_add_u32 s55, s55, 0x100
	s_addc_u32 s56, s56, 0
	s_cmp_gt_u32 s57, 61
	s_cbranch_scc0 .LBB0_91
	s_and_b64 vcc, exec, s[20:21]
	s_cbranch_vccz .LBB0_94
	s_barrier

.LBB0_317:
	ds_read_b128 v[148:151], v166
	ds_read_b128 v[170:173], v166 offset:1024
	ds_read_b128 v[174:177], v166 offset:2048
	ds_read_b128 v[178:181], v166 offset:3072
	ds_read_b128 v[182:185], v167
	ds_read_b128 v[186:189], v167 offset:1024
	ds_read_b128 v[190:193], v167 offset:2048
	ds_read_b128 v[194:197], v167 offset:3072
	s_add_u32 s28, s26, 0xfffc0080
	s_addc_u32 s29, s27, -1
	s_cmp_eq_u32 s53, 12
	s_cselect_b32 s31, s19, s29
	s_cselect_b32 s30, s49, s28
	s_cselect_b32 s29, s17, s52
	s_cselect_b32 s28, s50, s51
	v_lshl_add_u64 v[230:231], s[26:27], 0, v[138:139]
	s_add_i32 m0, s25, 0xc000
	ds_read_b128 v[198:201], v168
	ds_read_b128 v[202:205], v168 offset:1024
	ds_read_b128 v[206:209], v168 offset:2048
	ds_read_b128 v[210:213], v168 offset:3072
	ds_read_b128 v[214:217], v168 offset:4096
	ds_read_b128 v[218:221], v168 offset:5120
	ds_read_b128 v[222:225], v168 offset:6144
	ds_read_b128 v[226:229], v168 offset:7168
	global_load_lds_dwordx4 v[230:231], off
	v_lshl_add_u64 v[230:231], s[26:27], 0, v[140:141]
	s_add_i32 m0, s25, 0xe000
	s_nop 0
	global_load_lds_dwordx4 v[230:231], off
	s_waitcnt vmcnt(8)
	s_waitcnt lgkmcnt(0)
	s_barrier
	s_setprio 1
	v_mfma_f32_16x16x32_bf16 v[126:129], v[148:151], v[198:201], v[126:129]
	v_mfma_f32_16x16x32_bf16 v[122:125], v[174:177], v[198:201], v[122:125]
	v_mfma_f32_16x16x32_bf16 v[114:117], v[148:151], v[206:209], v[114:117]
	v_mfma_f32_16x16x32_bf16 v[106:109], v[174:177], v[206:209], v[106:109]
	v_mfma_f32_16x16x32_bf16 v[98:101], v[148:151], v[214:217], v[98:101]
	v_mfma_f32_16x16x32_bf16 v[90:93], v[174:177], v[214:217], v[90:93]
	v_mfma_f32_16x16x32_bf16 v[82:85], v[148:151], v[222:225], v[82:85]
	v_mfma_f32_16x16x32_bf16 v[74:77], v[174:177], v[222:225], v[74:77]
	v_mfma_f32_16x16x32_bf16 v[126:129], v[170:173], v[202:205], v[126:129]
	v_mfma_f32_16x16x32_bf16 v[122:125], v[178:181], v[202:205], v[122:125]
	v_mfma_f32_16x16x32_bf16 v[114:117], v[170:173], v[210:213], v[114:117]
	v_mfma_f32_16x16x32_bf16 v[106:109], v[178:181], v[210:213], v[106:109]
	v_mfma_f32_16x16x32_bf16 v[98:101], v[170:173], v[218:221], v[98:101]
	v_mfma_f32_16x16x32_bf16 v[90:93], v[178:181], v[218:221], v[90:93]
	v_mfma_f32_16x16x32_bf16 v[82:85], v[170:173], v[226:229], v[82:85]
	v_mfma_f32_16x16x32_bf16 v[74:77], v[178:181], v[226:229], v[74:77]
	v_mfma_f32_16x16x32_bf16 v[118:121], v[182:185], v[198:201], v[118:121]
	v_mfma_f32_16x16x32_bf16 v[110:113], v[190:193], v[198:201], v[110:113]
	v_mfma_f32_16x16x32_bf16 v[102:105], v[182:185], v[206:209], v[102:105]
	v_mfma_f32_16x16x32_bf16 v[94:97], v[190:193], v[206:209], v[94:97]
	v_mfma_f32_16x16x32_bf16 v[86:89], v[182:185], v[214:217], v[86:89]
	v_mfma_f32_16x16x32_bf16 v[78:81], v[190:193], v[214:217], v[78:81]
	v_mfma_f32_16x16x32_bf16 v[70:73], v[182:185], v[222:225], v[70:73]
	v_mfma_f32_16x16x32_bf16 v[66:69], v[190:193], v[222:225], v[66:69]
	v_mfma_f32_16x16x32_bf16 v[118:121], v[186:189], v[202:205], v[118:121]
	v_mfma_f32_16x16x32_bf16 v[110:113], v[194:197], v[202:205], v[110:113]
	v_mfma_f32_16x16x32_bf16 v[102:105], v[186:189], v[210:213], v[102:105]
	v_mfma_f32_16x16x32_bf16 v[94:97], v[194:197], v[210:213], v[94:97]
	v_mfma_f32_16x16x32_bf16 v[86:89], v[186:189], v[218:221], v[86:89]
	v_mfma_f32_16x16x32_bf16 v[78:81], v[194:197], v[218:221], v[78:81]
	v_mfma_f32_16x16x32_bf16 v[70:73], v[186:189], v[226:229], v[70:73]
	v_mfma_f32_16x16x32_bf16 v[66:69], v[194:197], v[226:229], v[66:69]
	s_setprio 0
	s_barrier
	s_add_i32 s54, s46, s36
	v_lshl_add_u64 v[230:231], s[28:29], 0, v[134:135]
	s_mov_b32 m0, s54
	ds_read_b128 v[198:201], v168 offset:16384
	ds_read_b128 v[202:205], v168 offset:17408
	ds_read_b128 v[206:209], v168 offset:18432
	ds_read_b128 v[210:213], v168 offset:19456
	ds_read_b128 v[214:217], v168 offset:20480
	ds_read_b128 v[218:221], v168 offset:21504
	ds_read_b128 v[222:225], v168 offset:22528
	ds_read_b128 v[226:229], v168 offset:23552
	global_load_lds_dwordx4 v[230:231], off
	s_add_i32 m0, s54, 0x2000
	s_add_u32 s54, s28, 0x40000
	v_lshl_add_u64 v[232:233], s[28:29], 0, v[130:131]
	s_addc_u32 s55, s29, 0
	s_add_i32 s56, s47, s36
	global_load_lds_dwordx4 v[232:233], off
	v_lshl_add_u64 v[234:235], s[54:55], 0, v[134:135]
	s_mov_b32 m0, s56
	v_lshl_add_u64 v[236:237], s[30:31], 0, v[132:133]
	global_load_lds_dwordx4 v[234:235], off
	v_lshl_add_u64 v[234:235], s[54:55], 0, v[130:131]
	s_add_i32 m0, s56, 0x2000
	s_nop 0
	global_load_lds_dwordx4 v[234:235], off
	v_lshl_add_u64 v[234:235], s[30:31], 0, v[136:137]
	s_mov_b32 m0, s25
	s_nop 0
	global_load_lds_dwordx4 v[234:235], off
	s_mov_b32 m0, s38
	s_nop 0
	global_load_lds_dwordx4 v[236:237], off
	s_waitcnt vmcnt(8)
	s_waitcnt lgkmcnt(0)
	s_barrier
	s_setprio 1
	v_mfma_f32_16x16x32_bf16 v[62:65], v[148:151], v[198:201], v[62:65]
	v_mfma_f32_16x16x32_bf16 v[58:61], v[174:177], v[198:201], v[58:61]
	v_mfma_f32_16x16x32_bf16 v[50:53], v[148:151], v[206:209], v[50:53]
	v_mfma_f32_16x16x32_bf16 v[42:45], v[174:177], v[206:209], v[42:45]
	v_mfma_f32_16x16x32_bf16 v[34:37], v[148:151], v[214:217], v[34:37]
	v_mfma_f32_16x16x32_bf16 v[26:29], v[174:177], v[214:217], v[26:29]
	v_mfma_f32_16x16x32_bf16 v[18:21], v[148:151], v[222:225], v[18:21]
	v_mfma_f32_16x16x32_bf16 v[10:13], v[174:177], v[222:225], v[10:13]
	v_mfma_f32_16x16x32_bf16 v[62:65], v[170:173], v[202:205], v[62:65]
	v_mfma_f32_16x16x32_bf16 v[58:61], v[178:181], v[202:205], v[58:61]
	v_mfma_f32_16x16x32_bf16 v[50:53], v[170:173], v[210:213], v[50:53]
	v_mfma_f32_16x16x32_bf16 v[42:45], v[178:181], v[210:213], v[42:45]
	v_mfma_f32_16x16x32_bf16 v[34:37], v[170:173], v[218:221], v[34:37]
	v_mfma_f32_16x16x32_bf16 v[26:29], v[178:181], v[218:221], v[26:29]
	v_mfma_f32_16x16x32_bf16 v[18:21], v[170:173], v[226:229], v[18:21]
	v_mfma_f32_16x16x32_bf16 v[10:13], v[178:181], v[226:229], v[10:13]
	v_mfma_f32_16x16x32_bf16 v[54:57], v[182:185], v[198:201], v[54:57]
	v_mfma_f32_16x16x32_bf16 v[46:49], v[190:193], v[198:201], v[46:49]
	v_mfma_f32_16x16x32_bf16 v[38:41], v[182:185], v[206:209], v[38:41]
	v_mfma_f32_16x16x32_bf16 v[30:33], v[190:193], v[206:209], v[30:33]
	v_mfma_f32_16x16x32_bf16 v[22:25], v[182:185], v[214:217], v[22:25]
	v_mfma_f32_16x16x32_bf16 v[14:17], v[190:193], v[214:217], v[14:17]
	v_mfma_f32_16x16x32_bf16 v[6:9], v[182:185], v[222:225], v[6:9]
	v_mfma_f32_16x16x32_bf16 v[2:5], v[190:193], v[222:225], v[2:5]
	v_mfma_f32_16x16x32_bf16 v[54:57], v[186:189], v[202:205], v[54:57]
	v_mfma_f32_16x16x32_bf16 v[46:49], v[194:197], v[202:205], v[46:49]
	v_mfma_f32_16x16x32_bf16 v[38:41], v[186:189], v[210:213], v[38:41]
	v_mfma_f32_16x16x32_bf16 v[30:33], v[194:197], v[210:213], v[30:33]
	v_mfma_f32_16x16x32_bf16 v[22:25], v[186:189], v[218:221], v[22:25]
	v_mfma_f32_16x16x32_bf16 v[14:17], v[194:197], v[218:221], v[14:17]
	v_mfma_f32_16x16x32_bf16 v[6:9], v[186:189], v[226:229], v[6:9]
	v_mfma_f32_16x16x32_bf16 v[2:5], v[194:197], v[226:229], v[2:5]
	s_setprio 0
	s_barrier
	s_add_i32 s54, 0, 0x18000
	v_add_u32_e32 v146, s54, v164
	s_add_i32 s55, 0, 0x1c000
	ds_read_b128 v[148:151], v146
	ds_read_b128 v[170:173], v146 offset:1024
	ds_read_b128 v[174:177], v146 offset:2048
	ds_read_b128 v[178:181], v146 offset:3072
	v_add_u32_e32 v146, s55, v164
	ds_read_b128 v[182:185], v146
	ds_read_b128 v[186:189], v146 offset:1024
	ds_read_b128 v[190:193], v146 offset:2048
	ds_read_b128 v[194:197], v146 offset:3072
	s_add_u32 s30, s30, 0x40000
	s_addc_u32 s31, s31, 0
	s_mov_b32 m0, s39
	v_lshl_add_u64 v[238:239], s[30:31], 0, v[136:137]
	ds_read_b128 v[198:201], v168 offset:32768
	ds_read_b128 v[202:205], v168 offset:33792
	ds_read_b128 v[206:209], v168 offset:34816
	ds_read_b128 v[210:213], v168 offset:35840
	ds_read_b128 v[214:217], v168 offset:36864
	ds_read_b128 v[218:221], v168 offset:37888
	ds_read_b128 v[222:225], v168 offset:38912
	ds_read_b128 v[226:229], v168 offset:39936
	global_load_lds_dwordx4 v[238:239], off
	v_lshl_add_u64 v[238:239], s[30:31], 0, v[132:133]
	s_mov_b32 m0, s40
	s_nop 0
	global_load_lds_dwordx4 v[238:239], off
	s_waitcnt vmcnt(8)
	s_waitcnt lgkmcnt(0)
	s_barrier
	s_setprio 1
	v_mfma_f32_16x16x32_bf16 v[126:129], v[148:151], v[198:201], v[126:129]
	v_mfma_f32_16x16x32_bf16 v[122:125], v[174:177], v[198:201], v[122:125]
	v_mfma_f32_16x16x32_bf16 v[114:117], v[148:151], v[206:209], v[114:117]
	v_mfma_f32_16x16x32_bf16 v[106:109], v[174:177], v[206:209], v[106:109]
	v_mfma_f32_16x16x32_bf16 v[98:101], v[148:151], v[214:217], v[98:101]
	v_mfma_f32_16x16x32_bf16 v[90:93], v[174:177], v[214:217], v[90:93]
	v_mfma_f32_16x16x32_bf16 v[82:85], v[148:151], v[222:225], v[82:85]
	v_mfma_f32_16x16x32_bf16 v[74:77], v[174:177], v[222:225], v[74:77]
	v_mfma_f32_16x16x32_bf16 v[126:129], v[170:173], v[202:205], v[126:129]
	v_mfma_f32_16x16x32_bf16 v[122:125], v[178:181], v[202:205], v[122:125]
	v_mfma_f32_16x16x32_bf16 v[114:117], v[170:173], v[210:213], v[114:117]
	v_mfma_f32_16x16x32_bf16 v[106:109], v[178:181], v[210:213], v[106:109]
	v_mfma_f32_16x16x32_bf16 v[98:101], v[170:173], v[218:221], v[98:101]
	v_mfma_f32_16x16x32_bf16 v[90:93], v[178:181], v[218:221], v[90:93]
	v_mfma_f32_16x16x32_bf16 v[82:85], v[170:173], v[226:229], v[82:85]
	v_mfma_f32_16x16x32_bf16 v[74:77], v[178:181], v[226:229], v[74:77]
	v_mfma_f32_16x16x32_bf16 v[118:121], v[182:185], v[198:201], v[118:121]
	v_mfma_f32_16x16x32_bf16 v[110:113], v[190:193], v[198:201], v[110:113]
	v_mfma_f32_16x16x32_bf16 v[102:105], v[182:185], v[206:209], v[102:105]
	v_mfma_f32_16x16x32_bf16 v[94:97], v[190:193], v[206:209], v[94:97]
	v_mfma_f32_16x16x32_bf16 v[86:89], v[182:185], v[214:217], v[86:89]
	v_mfma_f32_16x16x32_bf16 v[78:81], v[190:193], v[214:217], v[78:81]
	v_mfma_f32_16x16x32_bf16 v[70:73], v[182:185], v[222:225], v[70:73]
	v_mfma_f32_16x16x32_bf16 v[66:69], v[190:193], v[222:225], v[66:69]
	v_mfma_f32_16x16x32_bf16 v[118:121], v[186:189], v[202:205], v[118:121]
	v_mfma_f32_16x16x32_bf16 v[110:113], v[194:197], v[202:205], v[110:113]
	v_mfma_f32_16x16x32_bf16 v[102:105], v[186:189], v[210:213], v[102:105]
	v_mfma_f32_16x16x32_bf16 v[94:97], v[194:197], v[210:213], v[94:97]
	v_mfma_f32_16x16x32_bf16 v[86:89], v[186:189], v[218:221], v[86:89]
	v_mfma_f32_16x16x32_bf16 v[78:81], v[194:197], v[218:221], v[78:81]
	v_mfma_f32_16x16x32_bf16 v[70:73], v[186:189], v[226:229], v[70:73]
	v_mfma_f32_16x16x32_bf16 v[66:69], v[194:197], v[226:229], v[66:69]
	s_setprio 0
	s_barrier
	s_add_i32 s30, s54, s36
	v_lshl_add_u64 v[230:231], v[230:231], 0, s[12:13]
	s_mov_b32 m0, s30
	ds_read_b128 v[198:201], v168 offset:49152
	ds_read_b128 v[202:205], v168 offset:50176
	ds_read_b128 v[206:209], v168 offset:51200
	ds_read_b128 v[210:213], v168 offset:52224
	ds_read_b128 v[214:217], v168 offset:53248
	ds_read_b128 v[218:221], v168 offset:54272
	ds_read_b128 v[222:225], v168 offset:55296
	ds_read_b128 v[226:229], v168 offset:56320
	global_load_lds_dwordx4 v[230:231], off
	s_add_i32 m0, s30, 0x2000
	s_add_u32 s28, s28, 0x40080
	v_lshl_add_u64 v[230:231], v[232:233], 0, s[12:13]
	s_addc_u32 s29, s29, 0
	s_add_i32 s30, s55, s36
	global_load_lds_dwordx4 v[230:231], off
	v_lshl_add_u64 v[230:231], s[28:29], 0, v[134:135]
	s_mov_b32 m0, s30
	s_nop 0
	global_load_lds_dwordx4 v[230:231], off
	v_lshl_add_u64 v[230:231], s[28:29], 0, v[130:131]
	s_add_i32 m0, s30, 0x2000
	s_nop 0
	global_load_lds_dwordx4 v[230:231], off
	v_lshl_add_u64 v[230:231], v[234:235], 0, s[12:13]
	s_mov_b32 m0, s42
	s_nop 0
	global_load_lds_dwordx4 v[230:231], off
	v_lshl_add_u64 v[230:231], v[236:237], 0, s[12:13]
	s_mov_b32 m0, s43
	s_nop 0
	global_load_lds_dwordx4 v[230:231], off
	s_waitcnt vmcnt(8)
	s_waitcnt lgkmcnt(0)
	s_barrier
	s_setprio 1
	v_mfma_f32_16x16x32_bf16 v[62:65], v[148:151], v[198:201], v[62:65]
	v_mfma_f32_16x16x32_bf16 v[58:61], v[174:177], v[198:201], v[58:61]
	v_mfma_f32_16x16x32_bf16 v[50:53], v[148:151], v[206:209], v[50:53]
	v_mfma_f32_16x16x32_bf16 v[42:45], v[174:177], v[206:209], v[42:45]
	v_mfma_f32_16x16x32_bf16 v[34:37], v[148:151], v[214:217], v[34:37]
	v_mfma_f32_16x16x32_bf16 v[26:29], v[174:177], v[214:217], v[26:29]
	v_mfma_f32_16x16x32_bf16 v[18:21], v[148:151], v[222:225], v[18:21]
	v_mfma_f32_16x16x32_bf16 v[10:13], v[174:177], v[222:225], v[10:13]
	v_mfma_f32_16x16x32_bf16 v[62:65], v[170:173], v[202:205], v[62:65]
	v_mfma_f32_16x16x32_bf16 v[58:61], v[178:181], v[202:205], v[58:61]
	v_mfma_f32_16x16x32_bf16 v[50:53], v[170:173], v[210:213], v[50:53]
	v_mfma_f32_16x16x32_bf16 v[42:45], v[178:181], v[210:213], v[42:45]
	v_mfma_f32_16x16x32_bf16 v[34:37], v[170:173], v[218:221], v[34:37]
	v_mfma_f32_16x16x32_bf16 v[26:29], v[178:181], v[218:221], v[26:29]
	v_mfma_f32_16x16x32_bf16 v[18:21], v[170:173], v[226:229], v[18:21]
	v_mfma_f32_16x16x32_bf16 v[10:13], v[178:181], v[226:229], v[10:13]
	v_mfma_f32_16x16x32_bf16 v[54:57], v[182:185], v[198:201], v[54:57]
	v_mfma_f32_16x16x32_bf16 v[46:49], v[190:193], v[198:201], v[46:49]
	v_mfma_f32_16x16x32_bf16 v[38:41], v[182:185], v[206:209], v[38:41]
	v_mfma_f32_16x16x32_bf16 v[30:33], v[190:193], v[206:209], v[30:33]
	v_mfma_f32_16x16x32_bf16 v[22:25], v[182:185], v[214:217], v[22:25]
	v_mfma_f32_16x16x32_bf16 v[14:17], v[190:193], v[214:217], v[14:17]
	v_mfma_f32_16x16x32_bf16 v[6:9], v[182:185], v[222:225], v[6:9]
	v_mfma_f32_16x16x32_bf16 v[2:5], v[190:193], v[222:225], v[2:5]
	v_mfma_f32_16x16x32_bf16 v[54:57], v[186:189], v[202:205], v[54:57]
	v_mfma_f32_16x16x32_bf16 v[46:49], v[194:197], v[202:205], v[46:49]
	v_mfma_f32_16x16x32_bf16 v[38:41], v[186:189], v[210:213], v[38:41]
	v_mfma_f32_16x16x32_bf16 v[30:33], v[194:197], v[210:213], v[30:33]
	v_mfma_f32_16x16x32_bf16 v[22:25], v[186:189], v[218:221], v[22:25]
	v_mfma_f32_16x16x32_bf16 v[14:17], v[194:197], v[218:221], v[14:17]
	v_mfma_f32_16x16x32_bf16 v[6:9], v[186:189], v[226:229], v[6:9]
	v_mfma_f32_16x16x32_bf16 v[2:5], v[194:197], v[226:229], v[2:5]
	s_setprio 0
	s_barrier
	s_add_i32 s53, s53, 2
	s_add_u32 s26, s26, 0x100
	s_addc_u32 s27, s27, 0
	s_add_u32 s51, s51, 0x100
	s_addc_u32 s52, s52, 0
	s_cmp_gt_u32 s53, 13
	s_cbranch_scc0 .LBB0_317
	s_and_b64 vcc, exec, s[14:15]
	s_cbranch_vccz .LBB0_320
	s_barrier

.LBB0_341:
	ds_read_b128 v[156:159], v1
	ds_read_b128 v[160:163], v1 offset:1024
	ds_read_b128 v[164:167], v1 offset:2048
	ds_read_b128 v[168:171], v1 offset:3072
	ds_read_b128 v[172:175], v147
	ds_read_b128 v[176:179], v147 offset:1024
	ds_read_b128 v[180:183], v147 offset:2048
	ds_read_b128 v[184:187], v147 offset:3072
	s_add_u32 s38, s36, 0xfffe0080
	s_addc_u32 s39, s37, -1
	s_cmp_eq_u32 s63, 4
	s_cselect_b32 s41, s27, s39
	s_cselect_b32 s40, s59, s38
	s_cselect_b32 s39, s25, s62
	s_cselect_b32 s38, s60, s61
	v_lshl_add_u64 v[148:149], s[36:37], 0, v[138:139]
	s_add_i32 m0, s35, 0xc000
	ds_read_b128 v[188:191], v152
	ds_read_b128 v[192:195], v152 offset:1024
	ds_read_b128 v[196:199], v152 offset:2048
	ds_read_b128 v[200:203], v152 offset:3072
	ds_read_b128 v[204:207], v152 offset:4096
	ds_read_b128 v[208:211], v152 offset:5120
	ds_read_b128 v[212:215], v152 offset:6144
	ds_read_b128 v[216:219], v152 offset:7168
	global_load_lds_dwordx4 v[148:149], off
	v_lshl_add_u64 v[148:149], s[36:37], 0, v[140:141]
	s_add_i32 m0, s35, 0xe000
	s_nop 0
	global_load_lds_dwordx4 v[148:149], off
	s_waitcnt vmcnt(8)
	s_waitcnt lgkmcnt(0)
	s_barrier
	s_setprio 1
	v_mfma_f32_16x16x32_bf16 v[126:129], v[156:159], v[188:191], v[126:129]
	v_mfma_f32_16x16x32_bf16 v[122:125], v[164:167], v[188:191], v[122:125]
	v_mfma_f32_16x16x32_bf16 v[114:117], v[156:159], v[196:199], v[114:117]
	v_mfma_f32_16x16x32_bf16 v[106:109], v[164:167], v[196:199], v[106:109]
	v_mfma_f32_16x16x32_bf16 v[98:101], v[156:159], v[204:207], v[98:101]
	v_mfma_f32_16x16x32_bf16 v[90:93], v[164:167], v[204:207], v[90:93]
	v_mfma_f32_16x16x32_bf16 v[82:85], v[156:159], v[212:215], v[82:85]
	v_mfma_f32_16x16x32_bf16 v[74:77], v[164:167], v[212:215], v[74:77]
	v_mfma_f32_16x16x32_bf16 v[126:129], v[160:163], v[192:195], v[126:129]
	v_mfma_f32_16x16x32_bf16 v[122:125], v[168:171], v[192:195], v[122:125]
	v_mfma_f32_16x16x32_bf16 v[114:117], v[160:163], v[200:203], v[114:117]
	v_mfma_f32_16x16x32_bf16 v[106:109], v[168:171], v[200:203], v[106:109]
	v_mfma_f32_16x16x32_bf16 v[98:101], v[160:163], v[208:211], v[98:101]
	v_mfma_f32_16x16x32_bf16 v[90:93], v[168:171], v[208:211], v[90:93]
	v_mfma_f32_16x16x32_bf16 v[82:85], v[160:163], v[216:219], v[82:85]
	v_mfma_f32_16x16x32_bf16 v[74:77], v[168:171], v[216:219], v[74:77]
	v_mfma_f32_16x16x32_bf16 v[118:121], v[172:175], v[188:191], v[118:121]
	v_mfma_f32_16x16x32_bf16 v[110:113], v[180:183], v[188:191], v[110:113]
	v_mfma_f32_16x16x32_bf16 v[102:105], v[172:175], v[196:199], v[102:105]
	v_mfma_f32_16x16x32_bf16 v[94:97], v[180:183], v[196:199], v[94:97]
	v_mfma_f32_16x16x32_bf16 v[86:89], v[172:175], v[204:207], v[86:89]
	v_mfma_f32_16x16x32_bf16 v[78:81], v[180:183], v[204:207], v[78:81]
	v_mfma_f32_16x16x32_bf16 v[70:73], v[172:175], v[212:215], v[70:73]
	v_mfma_f32_16x16x32_bf16 v[66:69], v[180:183], v[212:215], v[66:69]
	v_mfma_f32_16x16x32_bf16 v[118:121], v[176:179], v[192:195], v[118:121]
	v_mfma_f32_16x16x32_bf16 v[110:113], v[184:187], v[192:195], v[110:113]
	v_mfma_f32_16x16x32_bf16 v[102:105], v[176:179], v[200:203], v[102:105]
	v_mfma_f32_16x16x32_bf16 v[94:97], v[184:187], v[200:203], v[94:97]
	v_mfma_f32_16x16x32_bf16 v[86:89], v[176:179], v[208:211], v[86:89]
	v_mfma_f32_16x16x32_bf16 v[78:81], v[184:187], v[208:211], v[78:81]
	v_mfma_f32_16x16x32_bf16 v[70:73], v[176:179], v[216:219], v[70:73]
	v_mfma_f32_16x16x32_bf16 v[66:69], v[184:187], v[216:219], v[66:69]
	s_setprio 0
	s_barrier
	s_add_i32 s64, s53, s45
	v_lshl_add_u64 v[148:149], s[38:39], 0, v[132:133]
	s_mov_b32 m0, s64
	ds_read_b128 v[188:191], v152 offset:16384
	ds_read_b128 v[192:195], v152 offset:17408
	ds_read_b128 v[196:199], v152 offset:18432
	ds_read_b128 v[200:203], v152 offset:19456
	ds_read_b128 v[204:207], v152 offset:20480
	ds_read_b128 v[208:211], v152 offset:21504
	ds_read_b128 v[212:215], v152 offset:22528
	ds_read_b128 v[216:219], v152 offset:23552
	global_load_lds_dwordx4 v[148:149], off
	s_add_i32 m0, s64, 0x2000
	s_add_u32 s64, s38, 0x20000
	v_lshl_add_u64 v[220:221], s[38:39], 0, v[136:137]
	s_addc_u32 s65, s39, 0
	s_add_i32 s66, s54, s45
	global_load_lds_dwordx4 v[220:221], off
	v_lshl_add_u64 v[222:223], s[64:65], 0, v[132:133]
	s_mov_b32 m0, s66
	v_lshl_add_u64 v[224:225], s[40:41], 0, v[134:135]
	global_load_lds_dwordx4 v[222:223], off
	v_lshl_add_u64 v[222:223], s[64:65], 0, v[136:137]
	s_add_i32 m0, s66, 0x2000
	s_nop 0
	global_load_lds_dwordx4 v[222:223], off
	v_lshl_add_u64 v[222:223], s[40:41], 0, v[130:131]
	s_mov_b32 m0, s35
	s_nop 0
	global_load_lds_dwordx4 v[222:223], off
	s_mov_b32 m0, s46
	s_nop 0
	global_load_lds_dwordx4 v[224:225], off
	s_waitcnt vmcnt(8)
	s_waitcnt lgkmcnt(0)
	s_barrier
	s_setprio 1
	v_mfma_f32_16x16x32_bf16 v[62:65], v[156:159], v[188:191], v[62:65]
	v_mfma_f32_16x16x32_bf16 v[58:61], v[164:167], v[188:191], v[58:61]
	v_mfma_f32_16x16x32_bf16 v[50:53], v[156:159], v[196:199], v[50:53]
	v_mfma_f32_16x16x32_bf16 v[42:45], v[164:167], v[196:199], v[42:45]
	v_mfma_f32_16x16x32_bf16 v[34:37], v[156:159], v[204:207], v[34:37]
	v_mfma_f32_16x16x32_bf16 v[26:29], v[164:167], v[204:207], v[26:29]
	v_mfma_f32_16x16x32_bf16 v[18:21], v[156:159], v[212:215], v[18:21]
	v_mfma_f32_16x16x32_bf16 v[10:13], v[164:167], v[212:215], v[10:13]
	v_mfma_f32_16x16x32_bf16 v[62:65], v[160:163], v[192:195], v[62:65]
	v_mfma_f32_16x16x32_bf16 v[58:61], v[168:171], v[192:195], v[58:61]
	v_mfma_f32_16x16x32_bf16 v[50:53], v[160:163], v[200:203], v[50:53]
	v_mfma_f32_16x16x32_bf16 v[42:45], v[168:171], v[200:203], v[42:45]
	v_mfma_f32_16x16x32_bf16 v[34:37], v[160:163], v[208:211], v[34:37]
	v_mfma_f32_16x16x32_bf16 v[26:29], v[168:171], v[208:211], v[26:29]
	v_mfma_f32_16x16x32_bf16 v[18:21], v[160:163], v[216:219], v[18:21]
	v_mfma_f32_16x16x32_bf16 v[10:13], v[168:171], v[216:219], v[10:13]
	v_mfma_f32_16x16x32_bf16 v[54:57], v[172:175], v[188:191], v[54:57]
	v_mfma_f32_16x16x32_bf16 v[46:49], v[180:183], v[188:191], v[46:49]
	v_mfma_f32_16x16x32_bf16 v[38:41], v[172:175], v[196:199], v[38:41]
	v_mfma_f32_16x16x32_bf16 v[30:33], v[180:183], v[196:199], v[30:33]
	v_mfma_f32_16x16x32_bf16 v[22:25], v[172:175], v[204:207], v[22:25]
	v_mfma_f32_16x16x32_bf16 v[14:17], v[180:183], v[204:207], v[14:17]
	v_mfma_f32_16x16x32_bf16 v[6:9], v[172:175], v[212:215], v[6:9]
	v_mfma_f32_16x16x32_bf16 v[2:5], v[180:183], v[212:215], v[2:5]
	v_mfma_f32_16x16x32_bf16 v[54:57], v[176:179], v[192:195], v[54:57]
	v_mfma_f32_16x16x32_bf16 v[46:49], v[184:187], v[192:195], v[46:49]
	v_mfma_f32_16x16x32_bf16 v[38:41], v[176:179], v[200:203], v[38:41]
	v_mfma_f32_16x16x32_bf16 v[30:33], v[184:187], v[200:203], v[30:33]
	v_mfma_f32_16x16x32_bf16 v[22:25], v[176:179], v[208:211], v[22:25]
	v_mfma_f32_16x16x32_bf16 v[14:17], v[184:187], v[208:211], v[14:17]
	v_mfma_f32_16x16x32_bf16 v[6:9], v[176:179], v[216:219], v[6:9]
	v_mfma_f32_16x16x32_bf16 v[2:5], v[184:187], v[216:219], v[2:5]
	s_setprio 0
	s_barrier
	s_add_i32 s64, 0, 0x18000
	v_add_u32_e32 v146, s64, v151
	s_add_i32 s65, 0, 0x1c000
	ds_read_b128 v[156:159], v146
	ds_read_b128 v[160:163], v146 offset:1024
	ds_read_b128 v[164:167], v146 offset:2048
	ds_read_b128 v[168:171], v146 offset:3072
	v_add_u32_e32 v146, s65, v151
	ds_read_b128 v[172:175], v146
	ds_read_b128 v[176:179], v146 offset:1024
	ds_read_b128 v[180:183], v146 offset:2048
	ds_read_b128 v[184:187], v146 offset:3072
	s_add_u32 s40, s40, 0x20000
	s_addc_u32 s41, s41, 0
	s_mov_b32 m0, s47
	v_lshl_add_u64 v[226:227], s[40:41], 0, v[130:131]
	ds_read_b128 v[188:191], v152 offset:32768
	ds_read_b128 v[192:195], v152 offset:33792
	ds_read_b128 v[196:199], v152 offset:34816
	ds_read_b128 v[200:203], v152 offset:35840
	ds_read_b128 v[204:207], v152 offset:36864
	ds_read_b128 v[208:211], v152 offset:37888
	ds_read_b128 v[212:215], v152 offset:38912
	ds_read_b128 v[216:219], v152 offset:39936
	global_load_lds_dwordx4 v[226:227], off
	v_lshl_add_u64 v[226:227], s[40:41], 0, v[134:135]
	s_mov_b32 m0, s48
	s_nop 0
	global_load_lds_dwordx4 v[226:227], off
	s_waitcnt vmcnt(8)
	s_waitcnt lgkmcnt(0)
	s_barrier
	s_setprio 1
	v_mfma_f32_16x16x32_bf16 v[126:129], v[156:159], v[188:191], v[126:129]
	v_mfma_f32_16x16x32_bf16 v[122:125], v[164:167], v[188:191], v[122:125]
	v_mfma_f32_16x16x32_bf16 v[114:117], v[156:159], v[196:199], v[114:117]
	v_mfma_f32_16x16x32_bf16 v[106:109], v[164:167], v[196:199], v[106:109]
	v_mfma_f32_16x16x32_bf16 v[98:101], v[156:159], v[204:207], v[98:101]
	v_mfma_f32_16x16x32_bf16 v[90:93], v[164:167], v[204:207], v[90:93]
	v_mfma_f32_16x16x32_bf16 v[82:85], v[156:159], v[212:215], v[82:85]
	v_mfma_f32_16x16x32_bf16 v[74:77], v[164:167], v[212:215], v[74:77]
	v_mfma_f32_16x16x32_bf16 v[126:129], v[160:163], v[192:195], v[126:129]
	v_mfma_f32_16x16x32_bf16 v[122:125], v[168:171], v[192:195], v[122:125]
	v_mfma_f32_16x16x32_bf16 v[114:117], v[160:163], v[200:203], v[114:117]
	v_mfma_f32_16x16x32_bf16 v[106:109], v[168:171], v[200:203], v[106:109]
	v_mfma_f32_16x16x32_bf16 v[98:101], v[160:163], v[208:211], v[98:101]
	v_mfma_f32_16x16x32_bf16 v[90:93], v[168:171], v[208:211], v[90:93]
	v_mfma_f32_16x16x32_bf16 v[82:85], v[160:163], v[216:219], v[82:85]
	v_mfma_f32_16x16x32_bf16 v[74:77], v[168:171], v[216:219], v[74:77]
	v_mfma_f32_16x16x32_bf16 v[118:121], v[172:175], v[188:191], v[118:121]
	v_mfma_f32_16x16x32_bf16 v[110:113], v[180:183], v[188:191], v[110:113]
	v_mfma_f32_16x16x32_bf16 v[102:105], v[172:175], v[196:199], v[102:105]
	v_mfma_f32_16x16x32_bf16 v[94:97], v[180:183], v[196:199], v[94:97]
	v_mfma_f32_16x16x32_bf16 v[86:89], v[172:175], v[204:207], v[86:89]
	v_mfma_f32_16x16x32_bf16 v[78:81], v[180:183], v[204:207], v[78:81]
	v_mfma_f32_16x16x32_bf16 v[70:73], v[172:175], v[212:215], v[70:73]
	v_mfma_f32_16x16x32_bf16 v[66:69], v[180:183], v[212:215], v[66:69]
	v_mfma_f32_16x16x32_bf16 v[118:121], v[176:179], v[192:195], v[118:121]
	v_mfma_f32_16x16x32_bf16 v[110:113], v[184:187], v[192:195], v[110:113]
	v_mfma_f32_16x16x32_bf16 v[102:105], v[176:179], v[200:203], v[102:105]
	v_mfma_f32_16x16x32_bf16 v[94:97], v[184:187], v[200:203], v[94:97]
	v_mfma_f32_16x16x32_bf16 v[86:89], v[176:179], v[208:211], v[86:89]
	v_mfma_f32_16x16x32_bf16 v[78:81], v[184:187], v[208:211], v[78:81]
	v_mfma_f32_16x16x32_bf16 v[70:73], v[176:179], v[216:219], v[70:73]
	v_mfma_f32_16x16x32_bf16 v[66:69], v[184:187], v[216:219], v[66:69]
	s_setprio 0
	s_barrier
	s_add_i32 s40, s64, s45
	v_lshl_add_u64 v[148:149], v[148:149], 0, s[12:13]
	s_mov_b32 m0, s40
	ds_read_b128 v[188:191], v152 offset:49152
	ds_read_b128 v[192:195], v152 offset:50176
	ds_read_b128 v[196:199], v152 offset:51200
	ds_read_b128 v[200:203], v152 offset:52224
	ds_read_b128 v[204:207], v152 offset:53248
	ds_read_b128 v[208:211], v152 offset:54272
	ds_read_b128 v[212:215], v152 offset:55296
	ds_read_b128 v[216:219], v152 offset:56320
	global_load_lds_dwordx4 v[148:149], off
	s_add_i32 m0, s40, 0x2000
	s_add_u32 s38, s38, 0x20080
	v_lshl_add_u64 v[148:149], v[220:221], 0, s[12:13]
	s_addc_u32 s39, s39, 0
	s_add_i32 s40, s65, s45
	global_load_lds_dwordx4 v[148:149], off
	v_lshl_add_u64 v[148:149], s[38:39], 0, v[132:133]
	s_mov_b32 m0, s40
	s_nop 0
	global_load_lds_dwordx4 v[148:149], off
	v_lshl_add_u64 v[148:149], s[38:39], 0, v[136:137]
	s_add_i32 m0, s40, 0x2000
	s_nop 0
	global_load_lds_dwordx4 v[148:149], off
	v_lshl_add_u64 v[148:149], v[222:223], 0, s[12:13]
	s_mov_b32 m0, s50
	s_nop 0
	global_load_lds_dwordx4 v[148:149], off
	v_lshl_add_u64 v[148:149], v[224:225], 0, s[12:13]
	s_mov_b32 m0, s51
	s_nop 0
	global_load_lds_dwordx4 v[148:149], off
	s_waitcnt vmcnt(8)
	s_waitcnt lgkmcnt(0)
	s_barrier
	s_setprio 1
	v_mfma_f32_16x16x32_bf16 v[62:65], v[156:159], v[188:191], v[62:65]
	v_mfma_f32_16x16x32_bf16 v[58:61], v[164:167], v[188:191], v[58:61]
	v_mfma_f32_16x16x32_bf16 v[50:53], v[156:159], v[196:199], v[50:53]
	v_mfma_f32_16x16x32_bf16 v[42:45], v[164:167], v[196:199], v[42:45]
	v_mfma_f32_16x16x32_bf16 v[34:37], v[156:159], v[204:207], v[34:37]
	v_mfma_f32_16x16x32_bf16 v[26:29], v[164:167], v[204:207], v[26:29]
	v_mfma_f32_16x16x32_bf16 v[18:21], v[156:159], v[212:215], v[18:21]
	v_mfma_f32_16x16x32_bf16 v[10:13], v[164:167], v[212:215], v[10:13]
	v_mfma_f32_16x16x32_bf16 v[62:65], v[160:163], v[192:195], v[62:65]
	v_mfma_f32_16x16x32_bf16 v[58:61], v[168:171], v[192:195], v[58:61]
	v_mfma_f32_16x16x32_bf16 v[50:53], v[160:163], v[200:203], v[50:53]
	v_mfma_f32_16x16x32_bf16 v[42:45], v[168:171], v[200:203], v[42:45]
	v_mfma_f32_16x16x32_bf16 v[34:37], v[160:163], v[208:211], v[34:37]
	v_mfma_f32_16x16x32_bf16 v[26:29], v[168:171], v[208:211], v[26:29]
	v_mfma_f32_16x16x32_bf16 v[18:21], v[160:163], v[216:219], v[18:21]
	v_mfma_f32_16x16x32_bf16 v[10:13], v[168:171], v[216:219], v[10:13]
	v_mfma_f32_16x16x32_bf16 v[54:57], v[172:175], v[188:191], v[54:57]
	v_mfma_f32_16x16x32_bf16 v[46:49], v[180:183], v[188:191], v[46:49]
	v_mfma_f32_16x16x32_bf16 v[38:41], v[172:175], v[196:199], v[38:41]
	v_mfma_f32_16x16x32_bf16 v[30:33], v[180:183], v[196:199], v[30:33]
	v_mfma_f32_16x16x32_bf16 v[22:25], v[172:175], v[204:207], v[22:25]
	v_mfma_f32_16x16x32_bf16 v[14:17], v[180:183], v[204:207], v[14:17]
	v_mfma_f32_16x16x32_bf16 v[6:9], v[172:175], v[212:215], v[6:9]
	v_mfma_f32_16x16x32_bf16 v[2:5], v[180:183], v[212:215], v[2:5]
	v_mfma_f32_16x16x32_bf16 v[54:57], v[176:179], v[192:195], v[54:57]
	v_mfma_f32_16x16x32_bf16 v[46:49], v[184:187], v[192:195], v[46:49]
	v_mfma_f32_16x16x32_bf16 v[38:41], v[176:179], v[200:203], v[38:41]
	v_mfma_f32_16x16x32_bf16 v[30:33], v[184:187], v[200:203], v[30:33]
	v_mfma_f32_16x16x32_bf16 v[22:25], v[176:179], v[208:211], v[22:25]
	v_mfma_f32_16x16x32_bf16 v[14:17], v[184:187], v[208:211], v[14:17]
	v_mfma_f32_16x16x32_bf16 v[6:9], v[176:179], v[216:219], v[6:9]
	v_mfma_f32_16x16x32_bf16 v[2:5], v[184:187], v[216:219], v[2:5]
	s_setprio 0
	s_barrier
	s_add_i32 s63, s63, 2
	s_add_u32 s36, s36, 0x100
	s_addc_u32 s37, s37, 0
	s_add_u32 s61, s61, 0x100
	s_addc_u32 s62, s62, 0
	s_cmp_gt_u32 s63, 5
	s_cbranch_scc0 .LBB0_341
	s_and_b64 vcc, exec, s[14:15]
	s_cbranch_vccz .LBB0_344
	s_barrier

.LBB0_728:
	ds_read_b128 v[130:133], v156
	ds_read_b128 v[134:137], v156 offset:1024
	ds_read_b128 v[160:163], v156 offset:2048
	ds_read_b128 v[164:167], v156 offset:3072
	ds_read_b128 v[168:171], v157
	ds_read_b128 v[172:175], v157 offset:1024
	ds_read_b128 v[176:179], v157 offset:2048
	ds_read_b128 v[180:183], v157 offset:3072
	s_add_u32 s28, s26, 0xfff00080
	s_addc_u32 s29, s27, -1
	s_cmp_eq_u32 s48, 60
	s_cselect_b32 s31, s19, s29
	s_cselect_b32 s30, s44, s28
	s_cselect_b32 s29, s17, s47
	s_cselect_b32 s28, s45, s46
	v_lshl_add_u64 v[216:217], s[26:27], 0, v[146:147]
	s_add_i32 m0, s25, 0xc000
	ds_read_b128 v[184:187], v158
	ds_read_b128 v[188:191], v158 offset:1024
	ds_read_b128 v[192:195], v158 offset:2048
	ds_read_b128 v[196:199], v158 offset:3072
	ds_read_b128 v[200:203], v158 offset:4096
	ds_read_b128 v[204:207], v158 offset:5120
	ds_read_b128 v[208:211], v158 offset:6144
	ds_read_b128 v[212:215], v158 offset:7168
	global_load_lds_dwordx4 v[216:217], off
	v_lshl_add_u64 v[216:217], s[26:27], 0, v[148:149]
	s_add_i32 m0, s25, 0xe000
	s_nop 0
	global_load_lds_dwordx4 v[216:217], off
	s_waitcnt vmcnt(8)
	s_waitcnt lgkmcnt(0)
	s_barrier
	s_setprio 1
	v_mfma_f32_16x16x32_bf16 v[126:129], v[130:133], v[184:187], v[126:129]
	v_mfma_f32_16x16x32_bf16 v[122:125], v[160:163], v[184:187], v[122:125]
	v_mfma_f32_16x16x32_bf16 v[118:121], v[130:133], v[192:195], v[118:121]
	v_mfma_f32_16x16x32_bf16 v[114:117], v[160:163], v[192:195], v[114:117]
	v_mfma_f32_16x16x32_bf16 v[94:97], v[130:133], v[200:203], v[94:97]
	v_mfma_f32_16x16x32_bf16 v[90:93], v[160:163], v[200:203], v[90:93]
	v_mfma_f32_16x16x32_bf16 v[82:85], v[130:133], v[208:211], v[82:85]
	v_mfma_f32_16x16x32_bf16 v[74:77], v[160:163], v[208:211], v[74:77]
	v_mfma_f32_16x16x32_bf16 v[126:129], v[134:137], v[188:191], v[126:129]
	v_mfma_f32_16x16x32_bf16 v[122:125], v[164:167], v[188:191], v[122:125]
	v_mfma_f32_16x16x32_bf16 v[118:121], v[134:137], v[196:199], v[118:121]
	v_mfma_f32_16x16x32_bf16 v[114:117], v[164:167], v[196:199], v[114:117]
	v_mfma_f32_16x16x32_bf16 v[94:97], v[134:137], v[204:207], v[94:97]
	v_mfma_f32_16x16x32_bf16 v[90:93], v[164:167], v[204:207], v[90:93]
	v_mfma_f32_16x16x32_bf16 v[82:85], v[134:137], v[212:215], v[82:85]
	v_mfma_f32_16x16x32_bf16 v[74:77], v[164:167], v[212:215], v[74:77]
	v_mfma_f32_16x16x32_bf16 v[110:113], v[168:171], v[184:187], v[110:113]
	v_mfma_f32_16x16x32_bf16 v[106:109], v[176:179], v[184:187], v[106:109]
	v_mfma_f32_16x16x32_bf16 v[102:105], v[168:171], v[192:195], v[102:105]
	v_mfma_f32_16x16x32_bf16 v[98:101], v[176:179], v[192:195], v[98:101]
	v_mfma_f32_16x16x32_bf16 v[86:89], v[168:171], v[200:203], v[86:89]
	v_mfma_f32_16x16x32_bf16 v[78:81], v[176:179], v[200:203], v[78:81]
	v_mfma_f32_16x16x32_bf16 v[70:73], v[168:171], v[208:211], v[70:73]
	v_mfma_f32_16x16x32_bf16 v[66:69], v[176:179], v[208:211], v[66:69]
	v_mfma_f32_16x16x32_bf16 v[110:113], v[172:175], v[188:191], v[110:113]
	v_mfma_f32_16x16x32_bf16 v[106:109], v[180:183], v[188:191], v[106:109]
	v_mfma_f32_16x16x32_bf16 v[102:105], v[172:175], v[196:199], v[102:105]
	v_mfma_f32_16x16x32_bf16 v[98:101], v[180:183], v[196:199], v[98:101]
	v_mfma_f32_16x16x32_bf16 v[86:89], v[172:175], v[204:207], v[86:89]
	v_mfma_f32_16x16x32_bf16 v[78:81], v[180:183], v[204:207], v[78:81]
	v_mfma_f32_16x16x32_bf16 v[70:73], v[172:175], v[212:215], v[70:73]
	v_mfma_f32_16x16x32_bf16 v[66:69], v[180:183], v[212:215], v[66:69]
	s_setprio 0
	s_barrier
	s_add_i32 s49, s42, s34
	v_lshl_add_u64 v[216:217], s[28:29], 0, v[140:141]
	s_mov_b32 m0, s49
	ds_read_b128 v[184:187], v158 offset:16384
	ds_read_b128 v[188:191], v158 offset:17408
	ds_read_b128 v[192:195], v158 offset:18432
	ds_read_b128 v[196:199], v158 offset:19456
	ds_read_b128 v[200:203], v158 offset:20480
	ds_read_b128 v[204:207], v158 offset:21504
	ds_read_b128 v[208:211], v158 offset:22528
	ds_read_b128 v[212:215], v158 offset:23552
	global_load_lds_dwordx4 v[216:217], off
	s_add_i32 m0, s49, 0x2000
	s_add_u32 s50, s28, 0x100000
	v_lshl_add_u64 v[218:219], s[28:29], 0, v[144:145]
	s_addc_u32 s51, s29, 0
	s_add_i32 s49, s43, s34
	global_load_lds_dwordx4 v[218:219], off
	v_lshl_add_u64 v[220:221], s[50:51], 0, v[140:141]
	s_mov_b32 m0, s49
	v_lshl_add_u64 v[222:223], s[30:31], 0, v[142:143]
	global_load_lds_dwordx4 v[220:221], off
	v_lshl_add_u64 v[220:221], s[50:51], 0, v[144:145]
	s_add_i32 m0, s49, 0x2000
	s_nop 0
	global_load_lds_dwordx4 v[220:221], off
	v_lshl_add_u64 v[220:221], s[30:31], 0, v[138:139]
	s_mov_b32 m0, s25
	s_nop 0
	global_load_lds_dwordx4 v[220:221], off
	s_mov_b32 m0, s35
	s_nop 0
	global_load_lds_dwordx4 v[222:223], off
	s_waitcnt vmcnt(8)
	s_waitcnt lgkmcnt(0)
	s_barrier
	s_setprio 1
	v_mfma_f32_16x16x32_bf16 v[62:65], v[130:133], v[184:187], v[62:65]
	v_mfma_f32_16x16x32_bf16 v[58:61], v[160:163], v[184:187], v[58:61]
	v_mfma_f32_16x16x32_bf16 v[50:53], v[130:133], v[192:195], v[50:53]
	v_mfma_f32_16x16x32_bf16 v[42:45], v[160:163], v[192:195], v[42:45]
	v_mfma_f32_16x16x32_bf16 v[34:37], v[130:133], v[200:203], v[34:37]
	v_mfma_f32_16x16x32_bf16 v[26:29], v[160:163], v[200:203], v[26:29]
	v_mfma_f32_16x16x32_bf16 v[18:21], v[130:133], v[208:211], v[18:21]
	v_mfma_f32_16x16x32_bf16 v[10:13], v[160:163], v[208:211], v[10:13]
	v_mfma_f32_16x16x32_bf16 v[62:65], v[134:137], v[188:191], v[62:65]
	v_mfma_f32_16x16x32_bf16 v[58:61], v[164:167], v[188:191], v[58:61]
	v_mfma_f32_16x16x32_bf16 v[50:53], v[134:137], v[196:199], v[50:53]
	v_mfma_f32_16x16x32_bf16 v[42:45], v[164:167], v[196:199], v[42:45]
	v_mfma_f32_16x16x32_bf16 v[34:37], v[134:137], v[204:207], v[34:37]
	v_mfma_f32_16x16x32_bf16 v[26:29], v[164:167], v[204:207], v[26:29]
	v_mfma_f32_16x16x32_bf16 v[18:21], v[134:137], v[212:215], v[18:21]
	v_mfma_f32_16x16x32_bf16 v[10:13], v[164:167], v[212:215], v[10:13]
	v_mfma_f32_16x16x32_bf16 v[54:57], v[168:171], v[184:187], v[54:57]
	v_mfma_f32_16x16x32_bf16 v[46:49], v[176:179], v[184:187], v[46:49]
	v_mfma_f32_16x16x32_bf16 v[38:41], v[168:171], v[192:195], v[38:41]
	v_mfma_f32_16x16x32_bf16 v[30:33], v[176:179], v[192:195], v[30:33]
	v_mfma_f32_16x16x32_bf16 v[22:25], v[168:171], v[200:203], v[22:25]
	v_mfma_f32_16x16x32_bf16 v[14:17], v[176:179], v[200:203], v[14:17]
	v_mfma_f32_16x16x32_bf16 v[6:9], v[168:171], v[208:211], v[6:9]
	v_mfma_f32_16x16x32_bf16 v[2:5], v[176:179], v[208:211], v[2:5]
	v_mfma_f32_16x16x32_bf16 v[54:57], v[172:175], v[188:191], v[54:57]
	v_mfma_f32_16x16x32_bf16 v[46:49], v[180:183], v[188:191], v[46:49]
	v_mfma_f32_16x16x32_bf16 v[38:41], v[172:175], v[196:199], v[38:41]
	v_mfma_f32_16x16x32_bf16 v[30:33], v[180:183], v[196:199], v[30:33]
	v_mfma_f32_16x16x32_bf16 v[22:25], v[172:175], v[204:207], v[22:25]
	v_mfma_f32_16x16x32_bf16 v[14:17], v[180:183], v[204:207], v[14:17]
	v_mfma_f32_16x16x32_bf16 v[6:9], v[172:175], v[212:215], v[6:9]
	v_mfma_f32_16x16x32_bf16 v[2:5], v[180:183], v[212:215], v[2:5]
	s_setprio 0
	s_barrier
	s_add_i32 s49, 0, 0x18000
	v_add_u32_e32 v159, s49, v154
	s_add_i32 s50, 0, 0x1c000
	ds_read_b128 v[130:133], v159
	ds_read_b128 v[134:137], v159 offset:1024
	ds_read_b128 v[160:163], v159 offset:2048
	ds_read_b128 v[164:167], v159 offset:3072
	v_add_u32_e32 v159, s50, v154
	ds_read_b128 v[168:171], v159
	ds_read_b128 v[172:175], v159 offset:1024
	ds_read_b128 v[176:179], v159 offset:2048
	ds_read_b128 v[180:183], v159 offset:3072
	s_add_u32 s30, s30, 0x100000
	s_addc_u32 s31, s31, 0
	s_mov_b32 m0, s36
	v_lshl_add_u64 v[224:225], s[30:31], 0, v[138:139]
	ds_read_b128 v[184:187], v158 offset:32768
	ds_read_b128 v[188:191], v158 offset:33792
	ds_read_b128 v[192:195], v158 offset:34816
	ds_read_b128 v[196:199], v158 offset:35840
	ds_read_b128 v[200:203], v158 offset:36864
	ds_read_b128 v[204:207], v158 offset:37888
	ds_read_b128 v[208:211], v158 offset:38912
	ds_read_b128 v[212:215], v158 offset:39936
	global_load_lds_dwordx4 v[224:225], off
	v_lshl_add_u64 v[224:225], s[30:31], 0, v[142:143]
	s_mov_b32 m0, s37
	s_nop 0
	global_load_lds_dwordx4 v[224:225], off
	s_waitcnt vmcnt(8)
	s_waitcnt lgkmcnt(0)
	s_barrier
	s_setprio 1
	v_mfma_f32_16x16x32_bf16 v[126:129], v[130:133], v[184:187], v[126:129]
	v_mfma_f32_16x16x32_bf16 v[122:125], v[160:163], v[184:187], v[122:125]
	v_mfma_f32_16x16x32_bf16 v[118:121], v[130:133], v[192:195], v[118:121]
	v_mfma_f32_16x16x32_bf16 v[114:117], v[160:163], v[192:195], v[114:117]
	v_mfma_f32_16x16x32_bf16 v[94:97], v[130:133], v[200:203], v[94:97]
	v_mfma_f32_16x16x32_bf16 v[90:93], v[160:163], v[200:203], v[90:93]
	v_mfma_f32_16x16x32_bf16 v[82:85], v[130:133], v[208:211], v[82:85]
	v_mfma_f32_16x16x32_bf16 v[74:77], v[160:163], v[208:211], v[74:77]
	v_mfma_f32_16x16x32_bf16 v[126:129], v[134:137], v[188:191], v[126:129]
	v_mfma_f32_16x16x32_bf16 v[122:125], v[164:167], v[188:191], v[122:125]
	v_mfma_f32_16x16x32_bf16 v[118:121], v[134:137], v[196:199], v[118:121]
	v_mfma_f32_16x16x32_bf16 v[114:117], v[164:167], v[196:199], v[114:117]
	v_mfma_f32_16x16x32_bf16 v[94:97], v[134:137], v[204:207], v[94:97]
	v_mfma_f32_16x16x32_bf16 v[90:93], v[164:167], v[204:207], v[90:93]
	v_mfma_f32_16x16x32_bf16 v[82:85], v[134:137], v[212:215], v[82:85]
	v_mfma_f32_16x16x32_bf16 v[74:77], v[164:167], v[212:215], v[74:77]
	v_mfma_f32_16x16x32_bf16 v[110:113], v[168:171], v[184:187], v[110:113]
	v_mfma_f32_16x16x32_bf16 v[106:109], v[176:179], v[184:187], v[106:109]
	v_mfma_f32_16x16x32_bf16 v[102:105], v[168:171], v[192:195], v[102:105]
	v_mfma_f32_16x16x32_bf16 v[98:101], v[176:179], v[192:195], v[98:101]
	v_mfma_f32_16x16x32_bf16 v[86:89], v[168:171], v[200:203], v[86:89]
	v_mfma_f32_16x16x32_bf16 v[78:81], v[176:179], v[200:203], v[78:81]
	v_mfma_f32_16x16x32_bf16 v[70:73], v[168:171], v[208:211], v[70:73]
	v_mfma_f32_16x16x32_bf16 v[66:69], v[176:179], v[208:211], v[66:69]
	v_mfma_f32_16x16x32_bf16 v[110:113], v[172:175], v[188:191], v[110:113]
	v_mfma_f32_16x16x32_bf16 v[106:109], v[180:183], v[188:191], v[106:109]
	v_mfma_f32_16x16x32_bf16 v[102:105], v[172:175], v[196:199], v[102:105]
	v_mfma_f32_16x16x32_bf16 v[98:101], v[180:183], v[196:199], v[98:101]
	v_mfma_f32_16x16x32_bf16 v[86:89], v[172:175], v[204:207], v[86:89]
	v_mfma_f32_16x16x32_bf16 v[78:81], v[180:183], v[204:207], v[78:81]
	v_mfma_f32_16x16x32_bf16 v[70:73], v[172:175], v[212:215], v[70:73]
	v_mfma_f32_16x16x32_bf16 v[66:69], v[180:183], v[212:215], v[66:69]
	s_setprio 0
	s_barrier
	s_add_i32 s30, s49, s34
	v_lshl_add_u64 v[216:217], v[216:217], 0, s[10:11]
	s_mov_b32 m0, s30
	ds_read_b128 v[184:187], v158 offset:49152
	ds_read_b128 v[188:191], v158 offset:50176
	ds_read_b128 v[192:195], v158 offset:51200
	ds_read_b128 v[196:199], v158 offset:52224
	ds_read_b128 v[200:203], v158 offset:53248
	ds_read_b128 v[204:207], v158 offset:54272
	ds_read_b128 v[208:211], v158 offset:55296
	ds_read_b128 v[212:215], v158 offset:56320
	global_load_lds_dwordx4 v[216:217], off
	s_add_i32 m0, s30, 0x2000
	s_add_u32 s28, s28, 0x100080
	v_lshl_add_u64 v[216:217], v[218:219], 0, s[10:11]
	s_addc_u32 s29, s29, 0
	s_add_i32 s30, s50, s34
	global_load_lds_dwordx4 v[216:217], off
	v_lshl_add_u64 v[216:217], s[28:29], 0, v[140:141]
	s_mov_b32 m0, s30
	s_nop 0
	global_load_lds_dwordx4 v[216:217], off
	v_lshl_add_u64 v[216:217], s[28:29], 0, v[144:145]
	s_add_i32 m0, s30, 0x2000
	s_nop 0
	global_load_lds_dwordx4 v[216:217], off
	v_lshl_add_u64 v[216:217], v[220:221], 0, s[10:11]
	s_mov_b32 m0, s39
	s_nop 0
	global_load_lds_dwordx4 v[216:217], off
	v_lshl_add_u64 v[216:217], v[222:223], 0, s[10:11]
	s_mov_b32 m0, s40
	s_nop 0
	global_load_lds_dwordx4 v[216:217], off
	s_waitcnt vmcnt(8)
	s_waitcnt lgkmcnt(0)
	s_barrier
	s_setprio 1
	v_mfma_f32_16x16x32_bf16 v[62:65], v[130:133], v[184:187], v[62:65]
	v_mfma_f32_16x16x32_bf16 v[58:61], v[160:163], v[184:187], v[58:61]
	v_mfma_f32_16x16x32_bf16 v[50:53], v[130:133], v[192:195], v[50:53]
	v_mfma_f32_16x16x32_bf16 v[42:45], v[160:163], v[192:195], v[42:45]
	v_mfma_f32_16x16x32_bf16 v[34:37], v[130:133], v[200:203], v[34:37]
	v_mfma_f32_16x16x32_bf16 v[26:29], v[160:163], v[200:203], v[26:29]
	v_mfma_f32_16x16x32_bf16 v[18:21], v[130:133], v[208:211], v[18:21]
	v_mfma_f32_16x16x32_bf16 v[10:13], v[160:163], v[208:211], v[10:13]
	v_mfma_f32_16x16x32_bf16 v[62:65], v[134:137], v[188:191], v[62:65]
	v_mfma_f32_16x16x32_bf16 v[58:61], v[164:167], v[188:191], v[58:61]
	v_mfma_f32_16x16x32_bf16 v[50:53], v[134:137], v[196:199], v[50:53]
	v_mfma_f32_16x16x32_bf16 v[42:45], v[164:167], v[196:199], v[42:45]
	v_mfma_f32_16x16x32_bf16 v[34:37], v[134:137], v[204:207], v[34:37]
	v_mfma_f32_16x16x32_bf16 v[26:29], v[164:167], v[204:207], v[26:29]
	v_mfma_f32_16x16x32_bf16 v[18:21], v[134:137], v[212:215], v[18:21]
	v_mfma_f32_16x16x32_bf16 v[10:13], v[164:167], v[212:215], v[10:13]
	v_mfma_f32_16x16x32_bf16 v[54:57], v[168:171], v[184:187], v[54:57]
	v_mfma_f32_16x16x32_bf16 v[46:49], v[176:179], v[184:187], v[46:49]
	v_mfma_f32_16x16x32_bf16 v[38:41], v[168:171], v[192:195], v[38:41]
	v_mfma_f32_16x16x32_bf16 v[30:33], v[176:179], v[192:195], v[30:33]
	v_mfma_f32_16x16x32_bf16 v[22:25], v[168:171], v[200:203], v[22:25]
	v_mfma_f32_16x16x32_bf16 v[14:17], v[176:179], v[200:203], v[14:17]
	v_mfma_f32_16x16x32_bf16 v[6:9], v[168:171], v[208:211], v[6:9]
	v_mfma_f32_16x16x32_bf16 v[2:5], v[176:179], v[208:211], v[2:5]
	v_mfma_f32_16x16x32_bf16 v[54:57], v[172:175], v[188:191], v[54:57]
	v_mfma_f32_16x16x32_bf16 v[46:49], v[180:183], v[188:191], v[46:49]
	v_mfma_f32_16x16x32_bf16 v[38:41], v[172:175], v[196:199], v[38:41]
	v_mfma_f32_16x16x32_bf16 v[30:33], v[180:183], v[196:199], v[30:33]
	v_mfma_f32_16x16x32_bf16 v[22:25], v[172:175], v[204:207], v[22:25]
	v_mfma_f32_16x16x32_bf16 v[14:17], v[180:183], v[204:207], v[14:17]
	v_mfma_f32_16x16x32_bf16 v[6:9], v[172:175], v[212:215], v[6:9]
	v_mfma_f32_16x16x32_bf16 v[2:5], v[180:183], v[212:215], v[2:5]
	s_setprio 0
	s_barrier
	s_add_i32 s48, s48, 2
	s_add_u32 s26, s26, 0x100
	s_addc_u32 s27, s27, 0
	s_add_u32 s46, s46, 0x100
	s_addc_u32 s47, s47, 0
	s_cmp_gt_u32 s48, 61
	s_cbranch_scc0 .LBB0_728
	s_and_b64 vcc, exec, s[12:13]
	s_cbranch_vccz .LBB0_731
	s_barrier

.LBB0_860:
	ds_read_b128 v[156:159], v153
	ds_read_b128 v[160:163], v153 offset:1024
	ds_read_b128 v[164:167], v153 offset:2048
	ds_read_b128 v[168:171], v153 offset:3072
	ds_read_b128 v[172:175], v154
	ds_read_b128 v[176:179], v154 offset:1024
	ds_read_b128 v[180:183], v154 offset:2048
	ds_read_b128 v[184:187], v154 offset:3072
	s_add_u32 s28, s26, 0xfff00080
	s_addc_u32 s29, s27, -1
	s_cmp_eq_u32 s51, 60
	s_cselect_b32 s31, s19, s29
	s_cselect_b32 s30, s47, s28
	s_cselect_b32 s29, s17, s50
	s_cselect_b32 s28, s48, s49
	v_lshl_add_u64 v[146:147], s[26:27], 0, v[138:139]
	s_add_i32 m0, s25, 0xc000
	ds_read_b128 v[188:191], v155
	ds_read_b128 v[192:195], v155 offset:1024
	ds_read_b128 v[196:199], v155 offset:2048
	ds_read_b128 v[200:203], v155 offset:3072
	ds_read_b128 v[204:207], v155 offset:4096
	ds_read_b128 v[208:211], v155 offset:5120
	ds_read_b128 v[212:215], v155 offset:6144
	ds_read_b128 v[216:219], v155 offset:7168
	global_load_lds_dwordx4 v[146:147], off
	v_lshl_add_u64 v[146:147], s[26:27], 0, v[140:141]
	s_add_i32 m0, s25, 0xe000
	s_nop 0
	global_load_lds_dwordx4 v[146:147], off
	s_waitcnt vmcnt(8)
	s_waitcnt lgkmcnt(0)
	s_barrier
	s_setprio 1
	v_mfma_f32_16x16x32_bf16 v[126:129], v[156:159], v[188:191], v[126:129]
	v_mfma_f32_16x16x32_bf16 v[122:125], v[164:167], v[188:191], v[122:125]
	v_mfma_f32_16x16x32_bf16 v[110:113], v[156:159], v[196:199], v[110:113]
	v_mfma_f32_16x16x32_bf16 v[106:109], v[164:167], v[196:199], v[106:109]
	v_mfma_f32_16x16x32_bf16 v[94:97], v[156:159], v[204:207], v[94:97]
	v_mfma_f32_16x16x32_bf16 v[90:93], v[164:167], v[204:207], v[90:93]
	v_mfma_f32_16x16x32_bf16 v[78:81], v[156:159], v[212:215], v[78:81]
	v_mfma_f32_16x16x32_bf16 v[74:77], v[164:167], v[212:215], v[74:77]
	v_mfma_f32_16x16x32_bf16 v[126:129], v[160:163], v[192:195], v[126:129]
	v_mfma_f32_16x16x32_bf16 v[122:125], v[168:171], v[192:195], v[122:125]
	v_mfma_f32_16x16x32_bf16 v[110:113], v[160:163], v[200:203], v[110:113]
	v_mfma_f32_16x16x32_bf16 v[106:109], v[168:171], v[200:203], v[106:109]
	v_mfma_f32_16x16x32_bf16 v[94:97], v[160:163], v[208:211], v[94:97]
	v_mfma_f32_16x16x32_bf16 v[90:93], v[168:171], v[208:211], v[90:93]
	v_mfma_f32_16x16x32_bf16 v[78:81], v[160:163], v[216:219], v[78:81]
	v_mfma_f32_16x16x32_bf16 v[74:77], v[168:171], v[216:219], v[74:77]
	v_mfma_f32_16x16x32_bf16 v[118:121], v[172:175], v[188:191], v[118:121]
	v_mfma_f32_16x16x32_bf16 v[114:117], v[180:183], v[188:191], v[114:117]
	v_mfma_f32_16x16x32_bf16 v[102:105], v[172:175], v[196:199], v[102:105]
	v_mfma_f32_16x16x32_bf16 v[98:101], v[180:183], v[196:199], v[98:101]
	v_mfma_f32_16x16x32_bf16 v[86:89], v[172:175], v[204:207], v[86:89]
	v_mfma_f32_16x16x32_bf16 v[82:85], v[180:183], v[204:207], v[82:85]
	v_mfma_f32_16x16x32_bf16 v[70:73], v[172:175], v[212:215], v[70:73]
	v_mfma_f32_16x16x32_bf16 v[66:69], v[180:183], v[212:215], v[66:69]
	v_mfma_f32_16x16x32_bf16 v[118:121], v[176:179], v[192:195], v[118:121]
	v_mfma_f32_16x16x32_bf16 v[114:117], v[184:187], v[192:195], v[114:117]
	v_mfma_f32_16x16x32_bf16 v[102:105], v[176:179], v[200:203], v[102:105]
	v_mfma_f32_16x16x32_bf16 v[98:101], v[184:187], v[200:203], v[98:101]
	v_mfma_f32_16x16x32_bf16 v[86:89], v[176:179], v[208:211], v[86:89]
	v_mfma_f32_16x16x32_bf16 v[82:85], v[184:187], v[208:211], v[82:85]
	v_mfma_f32_16x16x32_bf16 v[70:73], v[176:179], v[216:219], v[70:73]
	v_mfma_f32_16x16x32_bf16 v[66:69], v[184:187], v[216:219], v[66:69]
	s_setprio 0
	s_barrier
	s_add_i32 s52, s44, s34
	v_lshl_add_u64 v[146:147], s[28:29], 0, v[134:135]
	s_mov_b32 m0, s52
	ds_read_b128 v[188:191], v155 offset:16384
	ds_read_b128 v[192:195], v155 offset:17408
	ds_read_b128 v[196:199], v155 offset:18432
	ds_read_b128 v[200:203], v155 offset:19456
	ds_read_b128 v[204:207], v155 offset:20480
	ds_read_b128 v[208:211], v155 offset:21504
	ds_read_b128 v[212:215], v155 offset:22528
	ds_read_b128 v[216:219], v155 offset:23552
	global_load_lds_dwordx4 v[146:147], off
	s_add_i32 m0, s52, 0x2000
	s_add_u32 s52, s28, 0x100000
	v_lshl_add_u64 v[220:221], s[28:29], 0, v[130:131]
	s_addc_u32 s53, s29, 0
	s_add_i32 s54, s45, s34
	global_load_lds_dwordx4 v[220:221], off
	v_lshl_add_u64 v[222:223], s[52:53], 0, v[134:135]
	s_mov_b32 m0, s54
	v_lshl_add_u64 v[224:225], s[30:31], 0, v[132:133]
	global_load_lds_dwordx4 v[222:223], off
	v_lshl_add_u64 v[222:223], s[52:53], 0, v[130:131]
	s_add_i32 m0, s54, 0x2000
	s_nop 0
	global_load_lds_dwordx4 v[222:223], off
	v_lshl_add_u64 v[222:223], s[30:31], 0, v[136:137]
	s_mov_b32 m0, s25
	s_nop 0
	global_load_lds_dwordx4 v[222:223], off
	s_mov_b32 m0, s37
	s_nop 0
	global_load_lds_dwordx4 v[224:225], off
	s_waitcnt vmcnt(8)
	s_waitcnt lgkmcnt(0)
	s_barrier
	s_setprio 1
	v_mfma_f32_16x16x32_bf16 v[62:65], v[156:159], v[188:191], v[62:65]
	v_mfma_f32_16x16x32_bf16 v[58:61], v[164:167], v[188:191], v[58:61]
	v_mfma_f32_16x16x32_bf16 v[46:49], v[156:159], v[196:199], v[46:49]
	v_mfma_f32_16x16x32_bf16 v[42:45], v[164:167], v[196:199], v[42:45]
	v_mfma_f32_16x16x32_bf16 v[30:33], v[156:159], v[204:207], v[30:33]
	v_mfma_f32_16x16x32_bf16 v[26:29], v[164:167], v[204:207], v[26:29]
	v_mfma_f32_16x16x32_bf16 v[14:17], v[156:159], v[212:215], v[14:17]
	v_mfma_f32_16x16x32_bf16 v[10:13], v[164:167], v[212:215], v[10:13]
	v_mfma_f32_16x16x32_bf16 v[62:65], v[160:163], v[192:195], v[62:65]
	v_mfma_f32_16x16x32_bf16 v[58:61], v[168:171], v[192:195], v[58:61]
	v_mfma_f32_16x16x32_bf16 v[46:49], v[160:163], v[200:203], v[46:49]
	v_mfma_f32_16x16x32_bf16 v[42:45], v[168:171], v[200:203], v[42:45]
	v_mfma_f32_16x16x32_bf16 v[30:33], v[160:163], v[208:211], v[30:33]
	v_mfma_f32_16x16x32_bf16 v[26:29], v[168:171], v[208:211], v[26:29]
	v_mfma_f32_16x16x32_bf16 v[14:17], v[160:163], v[216:219], v[14:17]
	v_mfma_f32_16x16x32_bf16 v[10:13], v[168:171], v[216:219], v[10:13]
	v_mfma_f32_16x16x32_bf16 v[54:57], v[172:175], v[188:191], v[54:57]
	v_mfma_f32_16x16x32_bf16 v[50:53], v[180:183], v[188:191], v[50:53]
	v_mfma_f32_16x16x32_bf16 v[38:41], v[172:175], v[196:199], v[38:41]
	v_mfma_f32_16x16x32_bf16 v[34:37], v[180:183], v[196:199], v[34:37]
	v_mfma_f32_16x16x32_bf16 v[22:25], v[172:175], v[204:207], v[22:25]
	v_mfma_f32_16x16x32_bf16 v[18:21], v[180:183], v[204:207], v[18:21]
	v_mfma_f32_16x16x32_bf16 v[6:9], v[172:175], v[212:215], v[6:9]
	v_mfma_f32_16x16x32_bf16 v[2:5], v[180:183], v[212:215], v[2:5]
	v_mfma_f32_16x16x32_bf16 v[54:57], v[176:179], v[192:195], v[54:57]
	v_mfma_f32_16x16x32_bf16 v[50:53], v[184:187], v[192:195], v[50:53]
	v_mfma_f32_16x16x32_bf16 v[38:41], v[176:179], v[200:203], v[38:41]
	v_mfma_f32_16x16x32_bf16 v[34:37], v[184:187], v[200:203], v[34:37]
	v_mfma_f32_16x16x32_bf16 v[22:25], v[176:179], v[208:211], v[22:25]
	v_mfma_f32_16x16x32_bf16 v[18:21], v[184:187], v[208:211], v[18:21]
	v_mfma_f32_16x16x32_bf16 v[6:9], v[176:179], v[216:219], v[6:9]
	v_mfma_f32_16x16x32_bf16 v[2:5], v[184:187], v[216:219], v[2:5]
	s_setprio 0
	s_barrier
	s_add_i32 s52, 0, 0x18000
	s_add_i32 s53, 0, 0x1c000
	v_add_u32_e32 v168, s52, v151
	v_add_u32_e32 v184, s53, v151
	ds_read_b128 v[156:159], v168
	ds_read_b128 v[160:163], v168 offset:1024
	ds_read_b128 v[164:167], v168 offset:2048
	ds_read_b128 v[168:171], v168 offset:3072
	ds_read_b128 v[172:175], v184
	ds_read_b128 v[176:179], v184 offset:1024
	ds_read_b128 v[180:183], v184 offset:2048
	ds_read_b128 v[184:187], v184 offset:3072
	s_add_u32 s30, s30, 0x100000
	s_addc_u32 s31, s31, 0
	s_mov_b32 m0, s38
	v_lshl_add_u64 v[226:227], s[30:31], 0, v[136:137]
	ds_read_b128 v[188:191], v155 offset:32768
	ds_read_b128 v[192:195], v155 offset:33792
	ds_read_b128 v[196:199], v155 offset:34816
	ds_read_b128 v[200:203], v155 offset:35840
	ds_read_b128 v[204:207], v155 offset:36864
	ds_read_b128 v[208:211], v155 offset:37888
	ds_read_b128 v[212:215], v155 offset:38912
	ds_read_b128 v[216:219], v155 offset:39936
	global_load_lds_dwordx4 v[226:227], off
	v_lshl_add_u64 v[226:227], s[30:31], 0, v[132:133]
	s_mov_b32 m0, s39
	s_nop 0
	global_load_lds_dwordx4 v[226:227], off
	s_waitcnt vmcnt(8)
	s_waitcnt lgkmcnt(0)
	s_barrier
	s_setprio 1
	v_mfma_f32_16x16x32_bf16 v[126:129], v[156:159], v[188:191], v[126:129]
	v_mfma_f32_16x16x32_bf16 v[122:125], v[164:167], v[188:191], v[122:125]
	v_mfma_f32_16x16x32_bf16 v[110:113], v[156:159], v[196:199], v[110:113]
	v_mfma_f32_16x16x32_bf16 v[106:109], v[164:167], v[196:199], v[106:109]
	v_mfma_f32_16x16x32_bf16 v[94:97], v[156:159], v[204:207], v[94:97]
	v_mfma_f32_16x16x32_bf16 v[90:93], v[164:167], v[204:207], v[90:93]
	v_mfma_f32_16x16x32_bf16 v[78:81], v[156:159], v[212:215], v[78:81]
	v_mfma_f32_16x16x32_bf16 v[74:77], v[164:167], v[212:215], v[74:77]
	v_mfma_f32_16x16x32_bf16 v[126:129], v[160:163], v[192:195], v[126:129]
	v_mfma_f32_16x16x32_bf16 v[122:125], v[168:171], v[192:195], v[122:125]
	v_mfma_f32_16x16x32_bf16 v[110:113], v[160:163], v[200:203], v[110:113]
	v_mfma_f32_16x16x32_bf16 v[106:109], v[168:171], v[200:203], v[106:109]
	v_mfma_f32_16x16x32_bf16 v[94:97], v[160:163], v[208:211], v[94:97]
	v_mfma_f32_16x16x32_bf16 v[90:93], v[168:171], v[208:211], v[90:93]
	v_mfma_f32_16x16x32_bf16 v[78:81], v[160:163], v[216:219], v[78:81]
	v_mfma_f32_16x16x32_bf16 v[74:77], v[168:171], v[216:219], v[74:77]
	v_mfma_f32_16x16x32_bf16 v[118:121], v[172:175], v[188:191], v[118:121]
	v_mfma_f32_16x16x32_bf16 v[114:117], v[180:183], v[188:191], v[114:117]
	v_mfma_f32_16x16x32_bf16 v[102:105], v[172:175], v[196:199], v[102:105]
	v_mfma_f32_16x16x32_bf16 v[98:101], v[180:183], v[196:199], v[98:101]
	v_mfma_f32_16x16x32_bf16 v[86:89], v[172:175], v[204:207], v[86:89]
	v_mfma_f32_16x16x32_bf16 v[82:85], v[180:183], v[204:207], v[82:85]
	v_mfma_f32_16x16x32_bf16 v[70:73], v[172:175], v[212:215], v[70:73]
	v_mfma_f32_16x16x32_bf16 v[66:69], v[180:183], v[212:215], v[66:69]
	v_mfma_f32_16x16x32_bf16 v[118:121], v[176:179], v[192:195], v[118:121]
	v_mfma_f32_16x16x32_bf16 v[114:117], v[184:187], v[192:195], v[114:117]
	v_mfma_f32_16x16x32_bf16 v[102:105], v[176:179], v[200:203], v[102:105]
	v_mfma_f32_16x16x32_bf16 v[98:101], v[184:187], v[200:203], v[98:101]
	v_mfma_f32_16x16x32_bf16 v[86:89], v[176:179], v[208:211], v[86:89]
	v_mfma_f32_16x16x32_bf16 v[82:85], v[184:187], v[208:211], v[82:85]
	v_mfma_f32_16x16x32_bf16 v[70:73], v[176:179], v[216:219], v[70:73]
	v_mfma_f32_16x16x32_bf16 v[66:69], v[184:187], v[216:219], v[66:69]
	s_setprio 0
	s_barrier
	s_add_i32 s30, s52, s34
	v_lshl_add_u64 v[146:147], v[146:147], 0, s[12:13]
	s_mov_b32 m0, s30
	ds_read_b128 v[188:191], v155 offset:49152
	ds_read_b128 v[192:195], v155 offset:50176
	ds_read_b128 v[196:199], v155 offset:51200
	ds_read_b128 v[200:203], v155 offset:52224
	ds_read_b128 v[204:207], v155 offset:53248
	ds_read_b128 v[208:211], v155 offset:54272
	ds_read_b128 v[212:215], v155 offset:55296
	ds_read_b128 v[216:219], v155 offset:56320
	global_load_lds_dwordx4 v[146:147], off
	s_add_i32 m0, s30, 0x2000
	s_add_u32 s28, s28, 0x100080
	v_lshl_add_u64 v[146:147], v[220:221], 0, s[12:13]
	s_addc_u32 s29, s29, 0
	s_add_i32 s30, s53, s34
	global_load_lds_dwordx4 v[146:147], off
	v_lshl_add_u64 v[146:147], s[28:29], 0, v[134:135]
	s_mov_b32 m0, s30
	s_nop 0
	global_load_lds_dwordx4 v[146:147], off
	v_lshl_add_u64 v[146:147], s[28:29], 0, v[130:131]
	s_add_i32 m0, s30, 0x2000
	s_nop 0
	global_load_lds_dwordx4 v[146:147], off
	v_lshl_add_u64 v[146:147], v[222:223], 0, s[12:13]
	s_mov_b32 m0, s41
	s_nop 0
	global_load_lds_dwordx4 v[146:147], off
	v_lshl_add_u64 v[146:147], v[224:225], 0, s[12:13]
	s_mov_b32 m0, s42
	s_nop 0
	global_load_lds_dwordx4 v[146:147], off
	s_waitcnt vmcnt(8)
	s_waitcnt lgkmcnt(0)
	s_barrier
	s_setprio 1
	v_mfma_f32_16x16x32_bf16 v[62:65], v[156:159], v[188:191], v[62:65]
	v_mfma_f32_16x16x32_bf16 v[58:61], v[164:167], v[188:191], v[58:61]
	v_mfma_f32_16x16x32_bf16 v[46:49], v[156:159], v[196:199], v[46:49]
	v_mfma_f32_16x16x32_bf16 v[42:45], v[164:167], v[196:199], v[42:45]
	v_mfma_f32_16x16x32_bf16 v[30:33], v[156:159], v[204:207], v[30:33]
	v_mfma_f32_16x16x32_bf16 v[26:29], v[164:167], v[204:207], v[26:29]
	v_mfma_f32_16x16x32_bf16 v[14:17], v[156:159], v[212:215], v[14:17]
	v_mfma_f32_16x16x32_bf16 v[10:13], v[164:167], v[212:215], v[10:13]
	v_mfma_f32_16x16x32_bf16 v[62:65], v[160:163], v[192:195], v[62:65]
	v_mfma_f32_16x16x32_bf16 v[58:61], v[168:171], v[192:195], v[58:61]
	v_mfma_f32_16x16x32_bf16 v[46:49], v[160:163], v[200:203], v[46:49]
	v_mfma_f32_16x16x32_bf16 v[42:45], v[168:171], v[200:203], v[42:45]
	v_mfma_f32_16x16x32_bf16 v[30:33], v[160:163], v[208:211], v[30:33]
	v_mfma_f32_16x16x32_bf16 v[26:29], v[168:171], v[208:211], v[26:29]
	v_mfma_f32_16x16x32_bf16 v[14:17], v[160:163], v[216:219], v[14:17]
	v_mfma_f32_16x16x32_bf16 v[10:13], v[168:171], v[216:219], v[10:13]
	v_mfma_f32_16x16x32_bf16 v[54:57], v[172:175], v[188:191], v[54:57]
	v_mfma_f32_16x16x32_bf16 v[50:53], v[180:183], v[188:191], v[50:53]
	v_mfma_f32_16x16x32_bf16 v[38:41], v[172:175], v[196:199], v[38:41]
	v_mfma_f32_16x16x32_bf16 v[34:37], v[180:183], v[196:199], v[34:37]
	v_mfma_f32_16x16x32_bf16 v[22:25], v[172:175], v[204:207], v[22:25]
	v_mfma_f32_16x16x32_bf16 v[18:21], v[180:183], v[204:207], v[18:21]
	v_mfma_f32_16x16x32_bf16 v[6:9], v[172:175], v[212:215], v[6:9]
	v_mfma_f32_16x16x32_bf16 v[2:5], v[180:183], v[212:215], v[2:5]
	v_mfma_f32_16x16x32_bf16 v[54:57], v[176:179], v[192:195], v[54:57]
	v_mfma_f32_16x16x32_bf16 v[50:53], v[184:187], v[192:195], v[50:53]
	v_mfma_f32_16x16x32_bf16 v[38:41], v[176:179], v[200:203], v[38:41]
	v_mfma_f32_16x16x32_bf16 v[34:37], v[184:187], v[200:203], v[34:37]
	v_mfma_f32_16x16x32_bf16 v[22:25], v[176:179], v[208:211], v[22:25]
	v_mfma_f32_16x16x32_bf16 v[18:21], v[184:187], v[208:211], v[18:21]
	v_mfma_f32_16x16x32_bf16 v[6:9], v[176:179], v[216:219], v[6:9]
	v_mfma_f32_16x16x32_bf16 v[2:5], v[184:187], v[216:219], v[2:5]
	s_setprio 0
	s_barrier
	s_add_i32 s51, s51, 2
	s_add_u32 s26, s26, 0x100
	s_addc_u32 s27, s27, 0
	s_add_u32 s49, s49, 0x100
	s_addc_u32 s50, s50, 0
	s_cmp_gt_u32 s51, 61
	s_cbranch_scc0 .LBB0_860
	s_and_b64 vcc, exec, s[14:15]
	s_cbranch_vccz .LBB0_863
	s_barrier

.LBB0_955:
	ds_read_b128 v[130:133], v199
	ds_read_b128 v[134:137], v199 offset:1024
	ds_read_b128 v[138:141], v199 offset:2048
	ds_read_b128 v[142:145], v199 offset:3072
	ds_read_b128 v[146:149], v200
	ds_read_b128 v[166:169], v200 offset:1024
	ds_read_b128 v[170:173], v200 offset:2048
	ds_read_b128 v[174:177], v200 offset:3072
	s_add_u32 s26, s24, 0xffd50080
	s_addc_u32 s27, s25, -1
	s_cmpk_eq_i32 s50, 0xa8
	s_cselect_b32 s29, s9, s27
	s_cselect_b32 s28, s8, s26
	s_cselect_b32 s27, s23, s49
	s_cselect_b32 s26, s22, s48
	v_lshl_add_u64 v[194:195], s[24:25], 0, v[158:159]
	s_add_i32 m0, s35, 0xc000
	ds_read_b128 v[178:181], v201
	ds_read_b128 v[182:185], v201 offset:1024
	ds_read_b128 v[186:189], v201 offset:2048
	ds_read_b128 v[190:193], v201 offset:3072
	ds_read_b128 v[202:205], v201 offset:4096
	ds_read_b128 v[206:209], v201 offset:5120
	ds_read_b128 v[210:213], v201 offset:6144
	ds_read_b128 v[214:217], v201 offset:7168
	global_load_lds_dwordx4 v[194:195], off
	v_lshl_add_u64 v[194:195], s[24:25], 0, v[160:161]
	s_add_i32 m0, s35, 0xe000
	s_nop 0
	global_load_lds_dwordx4 v[194:195], off
	s_waitcnt vmcnt(8)
	s_waitcnt lgkmcnt(0)
	s_barrier
	s_setprio 1
	v_mfma_f32_16x16x32_bf16 v[126:129], v[130:133], v[178:181], v[126:129]
	v_mfma_f32_16x16x32_bf16 v[122:125], v[138:141], v[178:181], v[122:125]
	v_mfma_f32_16x16x32_bf16 v[118:121], v[130:133], v[186:189], v[118:121]
	v_mfma_f32_16x16x32_bf16 v[114:117], v[138:141], v[186:189], v[114:117]
	v_mfma_f32_16x16x32_bf16 v[110:113], v[130:133], v[202:205], v[110:113]
	v_mfma_f32_16x16x32_bf16 v[106:109], v[138:141], v[202:205], v[106:109]
	v_mfma_f32_16x16x32_bf16 v[102:105], v[130:133], v[210:213], v[102:105]
	v_mfma_f32_16x16x32_bf16 v[98:101], v[138:141], v[210:213], v[98:101]
	v_mfma_f32_16x16x32_bf16 v[126:129], v[134:137], v[182:185], v[126:129]
	v_mfma_f32_16x16x32_bf16 v[122:125], v[142:145], v[182:185], v[122:125]
	v_mfma_f32_16x16x32_bf16 v[118:121], v[134:137], v[190:193], v[118:121]
	v_mfma_f32_16x16x32_bf16 v[114:117], v[142:145], v[190:193], v[114:117]
	v_mfma_f32_16x16x32_bf16 v[110:113], v[134:137], v[206:209], v[110:113]
	v_mfma_f32_16x16x32_bf16 v[106:109], v[142:145], v[206:209], v[106:109]
	v_mfma_f32_16x16x32_bf16 v[102:105], v[134:137], v[214:217], v[102:105]
	v_mfma_f32_16x16x32_bf16 v[98:101], v[142:145], v[214:217], v[98:101]
	v_mfma_f32_16x16x32_bf16 v[62:65], v[146:149], v[178:181], v[62:65]
	v_mfma_f32_16x16x32_bf16 v[58:61], v[170:173], v[178:181], v[58:61]
	v_mfma_f32_16x16x32_bf16 v[54:57], v[146:149], v[186:189], v[54:57]
	v_mfma_f32_16x16x32_bf16 v[50:53], v[170:173], v[186:189], v[50:53]
	v_mfma_f32_16x16x32_bf16 v[46:49], v[146:149], v[202:205], v[46:49]
	v_mfma_f32_16x16x32_bf16 v[42:45], v[170:173], v[202:205], v[42:45]
	v_mfma_f32_16x16x32_bf16 v[38:41], v[146:149], v[210:213], v[38:41]
	v_mfma_f32_16x16x32_bf16 v[34:37], v[170:173], v[210:213], v[34:37]
	v_mfma_f32_16x16x32_bf16 v[62:65], v[166:169], v[182:185], v[62:65]
	v_mfma_f32_16x16x32_bf16 v[58:61], v[174:177], v[182:185], v[58:61]
	v_mfma_f32_16x16x32_bf16 v[54:57], v[166:169], v[190:193], v[54:57]
	v_mfma_f32_16x16x32_bf16 v[50:53], v[174:177], v[190:193], v[50:53]
	v_mfma_f32_16x16x32_bf16 v[46:49], v[166:169], v[206:209], v[46:49]
	v_mfma_f32_16x16x32_bf16 v[42:45], v[174:177], v[206:209], v[42:45]
	v_mfma_f32_16x16x32_bf16 v[38:41], v[166:169], v[214:217], v[38:41]
	v_mfma_f32_16x16x32_bf16 v[34:37], v[174:177], v[214:217], v[34:37]
	s_setprio 0
	s_barrier
	s_add_i32 s51, s43, s34
	v_lshl_add_u64 v[194:195], s[26:27], 0, v[152:153]
	s_mov_b32 m0, s51
	ds_read_b128 v[178:181], v201 offset:16384
	ds_read_b128 v[182:185], v201 offset:17408
	ds_read_b128 v[186:189], v201 offset:18432
	ds_read_b128 v[190:193], v201 offset:19456
	ds_read_b128 v[202:205], v201 offset:20480
	ds_read_b128 v[206:209], v201 offset:21504
	ds_read_b128 v[210:213], v201 offset:22528
	ds_read_b128 v[214:217], v201 offset:23552
	global_load_lds_dwordx4 v[194:195], off
	s_add_i32 m0, s51, 0x2000
	s_add_u32 s52, s26, 0x2b0000
	v_lshl_add_u64 v[218:219], s[26:27], 0, v[156:157]
	s_addc_u32 s53, s27, 0
	s_add_i32 s51, s44, s34
	global_load_lds_dwordx4 v[218:219], off
	v_lshl_add_u64 v[220:221], s[52:53], 0, v[152:153]
	s_mov_b32 m0, s51
	v_lshl_add_u64 v[222:223], s[28:29], 0, v[154:155]
	global_load_lds_dwordx4 v[220:221], off
	v_lshl_add_u64 v[220:221], s[52:53], 0, v[156:157]
	s_add_i32 m0, s51, 0x2000
	s_nop 0
	global_load_lds_dwordx4 v[220:221], off
	v_lshl_add_u64 v[220:221], s[28:29], 0, v[150:151]
	s_mov_b32 m0, s35
	s_nop 0
	global_load_lds_dwordx4 v[220:221], off
	s_mov_b32 m0, s36
	s_nop 0
	global_load_lds_dwordx4 v[222:223], off
	s_waitcnt vmcnt(8)
	s_waitcnt lgkmcnt(0)
	s_barrier
	s_setprio 1
	v_mfma_f32_16x16x32_bf16 v[94:97], v[130:133], v[178:181], v[94:97]
	v_mfma_f32_16x16x32_bf16 v[90:93], v[138:141], v[178:181], v[90:93]
	v_mfma_f32_16x16x32_bf16 v[86:89], v[130:133], v[186:189], v[86:89]
	v_mfma_f32_16x16x32_bf16 v[82:85], v[138:141], v[186:189], v[82:85]
	v_mfma_f32_16x16x32_bf16 v[78:81], v[130:133], v[202:205], v[78:81]
	v_mfma_f32_16x16x32_bf16 v[74:77], v[138:141], v[202:205], v[74:77]
	v_mfma_f32_16x16x32_bf16 v[70:73], v[130:133], v[210:213], v[70:73]
	v_mfma_f32_16x16x32_bf16 v[66:69], v[138:141], v[210:213], v[66:69]
	v_mfma_f32_16x16x32_bf16 v[94:97], v[134:137], v[182:185], v[94:97]
	v_mfma_f32_16x16x32_bf16 v[90:93], v[142:145], v[182:185], v[90:93]
	v_mfma_f32_16x16x32_bf16 v[86:89], v[134:137], v[190:193], v[86:89]
	v_mfma_f32_16x16x32_bf16 v[82:85], v[142:145], v[190:193], v[82:85]
	v_mfma_f32_16x16x32_bf16 v[78:81], v[134:137], v[206:209], v[78:81]
	v_mfma_f32_16x16x32_bf16 v[74:77], v[142:145], v[206:209], v[74:77]
	v_mfma_f32_16x16x32_bf16 v[70:73], v[134:137], v[214:217], v[70:73]
	v_mfma_f32_16x16x32_bf16 v[66:69], v[142:145], v[214:217], v[66:69]
	v_mfma_f32_16x16x32_bf16 v[30:33], v[146:149], v[178:181], v[30:33]
	v_mfma_f32_16x16x32_bf16 v[26:29], v[170:173], v[178:181], v[26:29]
	v_mfma_f32_16x16x32_bf16 v[22:25], v[146:149], v[186:189], v[22:25]
	v_mfma_f32_16x16x32_bf16 v[18:21], v[170:173], v[186:189], v[18:21]
	v_mfma_f32_16x16x32_bf16 v[14:17], v[146:149], v[202:205], v[14:17]
	v_mfma_f32_16x16x32_bf16 v[10:13], v[170:173], v[202:205], v[10:13]
	v_mfma_f32_16x16x32_bf16 v[6:9], v[146:149], v[210:213], v[6:9]
	v_mfma_f32_16x16x32_bf16 v[2:5], v[170:173], v[210:213], v[2:5]
	v_mfma_f32_16x16x32_bf16 v[30:33], v[166:169], v[182:185], v[30:33]
	v_mfma_f32_16x16x32_bf16 v[26:29], v[174:177], v[182:185], v[26:29]
	v_mfma_f32_16x16x32_bf16 v[22:25], v[166:169], v[190:193], v[22:25]
	v_mfma_f32_16x16x32_bf16 v[18:21], v[174:177], v[190:193], v[18:21]
	v_mfma_f32_16x16x32_bf16 v[14:17], v[166:169], v[206:209], v[14:17]
	v_mfma_f32_16x16x32_bf16 v[10:13], v[174:177], v[206:209], v[10:13]
	v_mfma_f32_16x16x32_bf16 v[6:9], v[166:169], v[214:217], v[6:9]
	v_mfma_f32_16x16x32_bf16 v[2:5], v[174:177], v[214:217], v[2:5]
	s_setprio 0
	s_barrier
	s_add_i32 s51, 0, 0x18000
	s_add_i32 s52, 0, 0x1c000
	v_add_u32_e32 v142, s51, v197
	v_add_u32_e32 v174, s52, v197
	ds_read_b128 v[130:133], v142
	ds_read_b128 v[134:137], v142 offset:1024
	ds_read_b128 v[138:141], v142 offset:2048
	ds_read_b128 v[142:145], v142 offset:3072
	ds_read_b128 v[146:149], v174
	ds_read_b128 v[166:169], v174 offset:1024
	ds_read_b128 v[170:173], v174 offset:2048
	ds_read_b128 v[174:177], v174 offset:3072
	s_add_u32 s28, s28, 0x2b0000
	s_addc_u32 s29, s29, 0
	s_mov_b32 m0, s37
	v_lshl_add_u64 v[224:225], s[28:29], 0, v[150:151]
	ds_read_b128 v[178:181], v201 offset:32768
	ds_read_b128 v[182:185], v201 offset:33792
	ds_read_b128 v[186:189], v201 offset:34816
	ds_read_b128 v[190:193], v201 offset:35840
	ds_read_b128 v[202:205], v201 offset:36864
	ds_read_b128 v[206:209], v201 offset:37888
	ds_read_b128 v[210:213], v201 offset:38912
	ds_read_b128 v[214:217], v201 offset:39936
	global_load_lds_dwordx4 v[224:225], off
	v_lshl_add_u64 v[224:225], s[28:29], 0, v[154:155]
	s_mov_b32 m0, s38
	s_nop 0
	global_load_lds_dwordx4 v[224:225], off
	s_waitcnt vmcnt(8)
	s_waitcnt lgkmcnt(0)
	s_barrier
	s_setprio 1
	v_mfma_f32_16x16x32_bf16 v[126:129], v[130:133], v[178:181], v[126:129]
	v_mfma_f32_16x16x32_bf16 v[122:125], v[138:141], v[178:181], v[122:125]
	v_mfma_f32_16x16x32_bf16 v[118:121], v[130:133], v[186:189], v[118:121]
	v_mfma_f32_16x16x32_bf16 v[114:117], v[138:141], v[186:189], v[114:117]
	v_mfma_f32_16x16x32_bf16 v[110:113], v[130:133], v[202:205], v[110:113]
	v_mfma_f32_16x16x32_bf16 v[106:109], v[138:141], v[202:205], v[106:109]
	v_mfma_f32_16x16x32_bf16 v[102:105], v[130:133], v[210:213], v[102:105]
	v_mfma_f32_16x16x32_bf16 v[98:101], v[138:141], v[210:213], v[98:101]
	v_mfma_f32_16x16x32_bf16 v[126:129], v[134:137], v[182:185], v[126:129]
	v_mfma_f32_16x16x32_bf16 v[122:125], v[142:145], v[182:185], v[122:125]
	v_mfma_f32_16x16x32_bf16 v[118:121], v[134:137], v[190:193], v[118:121]
	v_mfma_f32_16x16x32_bf16 v[114:117], v[142:145], v[190:193], v[114:117]
	v_mfma_f32_16x16x32_bf16 v[110:113], v[134:137], v[206:209], v[110:113]
	v_mfma_f32_16x16x32_bf16 v[106:109], v[142:145], v[206:209], v[106:109]
	v_mfma_f32_16x16x32_bf16 v[102:105], v[134:137], v[214:217], v[102:105]
	v_mfma_f32_16x16x32_bf16 v[98:101], v[142:145], v[214:217], v[98:101]
	v_mfma_f32_16x16x32_bf16 v[62:65], v[146:149], v[178:181], v[62:65]
	v_mfma_f32_16x16x32_bf16 v[58:61], v[170:173], v[178:181], v[58:61]
	v_mfma_f32_16x16x32_bf16 v[54:57], v[146:149], v[186:189], v[54:57]
	v_mfma_f32_16x16x32_bf16 v[50:53], v[170:173], v[186:189], v[50:53]
	v_mfma_f32_16x16x32_bf16 v[46:49], v[146:149], v[202:205], v[46:49]
	v_mfma_f32_16x16x32_bf16 v[42:45], v[170:173], v[202:205], v[42:45]
	v_mfma_f32_16x16x32_bf16 v[38:41], v[146:149], v[210:213], v[38:41]
	v_mfma_f32_16x16x32_bf16 v[34:37], v[170:173], v[210:213], v[34:37]
	v_mfma_f32_16x16x32_bf16 v[62:65], v[166:169], v[182:185], v[62:65]
	v_mfma_f32_16x16x32_bf16 v[58:61], v[174:177], v[182:185], v[58:61]
	v_mfma_f32_16x16x32_bf16 v[54:57], v[166:169], v[190:193], v[54:57]
	v_mfma_f32_16x16x32_bf16 v[50:53], v[174:177], v[190:193], v[50:53]
	v_mfma_f32_16x16x32_bf16 v[46:49], v[166:169], v[206:209], v[46:49]
	v_mfma_f32_16x16x32_bf16 v[42:45], v[174:177], v[206:209], v[42:45]
	v_mfma_f32_16x16x32_bf16 v[38:41], v[166:169], v[214:217], v[38:41]
	v_mfma_f32_16x16x32_bf16 v[34:37], v[174:177], v[214:217], v[34:37]
	s_setprio 0
	s_barrier
	s_add_i32 s28, s51, s34
	v_lshl_add_u64 v[194:195], v[194:195], 0, s[16:17]
	s_mov_b32 m0, s28
	ds_read_b128 v[178:181], v201 offset:49152
	ds_read_b128 v[182:185], v201 offset:50176
	ds_read_b128 v[186:189], v201 offset:51200
	ds_read_b128 v[190:193], v201 offset:52224
	ds_read_b128 v[202:205], v201 offset:53248
	ds_read_b128 v[206:209], v201 offset:54272
	ds_read_b128 v[210:213], v201 offset:55296
	ds_read_b128 v[214:217], v201 offset:56320
	global_load_lds_dwordx4 v[194:195], off
	s_add_i32 m0, s28, 0x2000
	s_add_u32 s26, s26, 0x2b0080
	v_lshl_add_u64 v[194:195], v[218:219], 0, s[16:17]
	s_addc_u32 s27, s27, 0
	s_add_i32 s28, s52, s34
	global_load_lds_dwordx4 v[194:195], off
	v_lshl_add_u64 v[194:195], s[26:27], 0, v[152:153]
	s_mov_b32 m0, s28
	s_nop 0
	global_load_lds_dwordx4 v[194:195], off
	v_lshl_add_u64 v[194:195], s[26:27], 0, v[156:157]
	s_add_i32 m0, s28, 0x2000
	s_nop 0
	global_load_lds_dwordx4 v[194:195], off
	v_lshl_add_u64 v[194:195], v[220:221], 0, s[16:17]
	s_mov_b32 m0, s40
	s_nop 0
	global_load_lds_dwordx4 v[194:195], off
	v_lshl_add_u64 v[194:195], v[222:223], 0, s[16:17]
	s_mov_b32 m0, s41
	s_nop 0
	global_load_lds_dwordx4 v[194:195], off
	s_waitcnt vmcnt(8)
	s_waitcnt lgkmcnt(0)
	s_barrier
	s_setprio 1
	v_mfma_f32_16x16x32_bf16 v[94:97], v[130:133], v[178:181], v[94:97]
	v_mfma_f32_16x16x32_bf16 v[90:93], v[138:141], v[178:181], v[90:93]
	v_mfma_f32_16x16x32_bf16 v[86:89], v[130:133], v[186:189], v[86:89]
	v_mfma_f32_16x16x32_bf16 v[82:85], v[138:141], v[186:189], v[82:85]
	v_mfma_f32_16x16x32_bf16 v[78:81], v[130:133], v[202:205], v[78:81]
	v_mfma_f32_16x16x32_bf16 v[74:77], v[138:141], v[202:205], v[74:77]
	v_mfma_f32_16x16x32_bf16 v[70:73], v[130:133], v[210:213], v[70:73]
	v_mfma_f32_16x16x32_bf16 v[66:69], v[138:141], v[210:213], v[66:69]
	v_mfma_f32_16x16x32_bf16 v[94:97], v[134:137], v[182:185], v[94:97]
	v_mfma_f32_16x16x32_bf16 v[90:93], v[142:145], v[182:185], v[90:93]
	v_mfma_f32_16x16x32_bf16 v[86:89], v[134:137], v[190:193], v[86:89]
	v_mfma_f32_16x16x32_bf16 v[82:85], v[142:145], v[190:193], v[82:85]
	v_mfma_f32_16x16x32_bf16 v[78:81], v[134:137], v[206:209], v[78:81]
	v_mfma_f32_16x16x32_bf16 v[74:77], v[142:145], v[206:209], v[74:77]
	v_mfma_f32_16x16x32_bf16 v[70:73], v[134:137], v[214:217], v[70:73]
	v_mfma_f32_16x16x32_bf16 v[66:69], v[142:145], v[214:217], v[66:69]
	v_mfma_f32_16x16x32_bf16 v[30:33], v[146:149], v[178:181], v[30:33]
	v_mfma_f32_16x16x32_bf16 v[26:29], v[170:173], v[178:181], v[26:29]
	v_mfma_f32_16x16x32_bf16 v[22:25], v[146:149], v[186:189], v[22:25]
	v_mfma_f32_16x16x32_bf16 v[18:21], v[170:173], v[186:189], v[18:21]
	v_mfma_f32_16x16x32_bf16 v[14:17], v[146:149], v[202:205], v[14:17]
	v_mfma_f32_16x16x32_bf16 v[10:13], v[170:173], v[202:205], v[10:13]
	v_mfma_f32_16x16x32_bf16 v[6:9], v[146:149], v[210:213], v[6:9]
	v_mfma_f32_16x16x32_bf16 v[2:5], v[170:173], v[210:213], v[2:5]
	v_mfma_f32_16x16x32_bf16 v[30:33], v[166:169], v[182:185], v[30:33]
	v_mfma_f32_16x16x32_bf16 v[26:29], v[174:177], v[182:185], v[26:29]
	v_mfma_f32_16x16x32_bf16 v[22:25], v[166:169], v[190:193], v[22:25]
	v_mfma_f32_16x16x32_bf16 v[18:21], v[174:177], v[190:193], v[18:21]
	v_mfma_f32_16x16x32_bf16 v[14:17], v[166:169], v[206:209], v[14:17]
	v_mfma_f32_16x16x32_bf16 v[10:13], v[174:177], v[206:209], v[10:13]
	v_mfma_f32_16x16x32_bf16 v[6:9], v[166:169], v[214:217], v[6:9]
	v_mfma_f32_16x16x32_bf16 v[2:5], v[174:177], v[214:217], v[2:5]
	s_setprio 0
	s_barrier
	s_add_i32 s50, s50, 2
	s_add_u32 s24, s24, 0x100
	s_addc_u32 s25, s25, 0
	s_add_u32 s48, s48, 0x100
	s_addc_u32 s49, s49, 0
	s_cmpk_gt_u32 s50, 0xa9
	s_cbranch_scc0 .LBB0_955
	s_and_b64 vcc, exec, s[18:19]
	s_cbranch_vccz .LBB0_958
	s_barrier

.LBB0_1087:
	ds_read_b128 v[148:151], v156
	ds_read_b128 v[160:163], v156 offset:1024
	ds_read_b128 v[164:167], v156 offset:2048
	ds_read_b128 v[168:171], v156 offset:3072
	ds_read_b128 v[172:175], v157
	ds_read_b128 v[176:179], v157 offset:1024
	ds_read_b128 v[180:183], v157 offset:2048
	ds_read_b128 v[184:187], v157 offset:3072
	s_add_u32 s28, s26, 0xfff00080
	s_addc_u32 s29, s27, -1
	s_cmp_eq_u32 s51, 60
	s_cselect_b32 s31, s19, s29
	s_cselect_b32 s30, s47, s28
	s_cselect_b32 s29, s17, s50
	s_cselect_b32 s28, s48, s49
	v_lshl_add_u64 v[220:221], s[26:27], 0, v[138:139]
	s_add_i32 m0, s25, 0xc000
	ds_read_b128 v[188:191], v158
	ds_read_b128 v[192:195], v158 offset:1024
	ds_read_b128 v[196:199], v158 offset:2048
	ds_read_b128 v[200:203], v158 offset:3072
	ds_read_b128 v[204:207], v158 offset:4096
	ds_read_b128 v[208:211], v158 offset:5120
	ds_read_b128 v[212:215], v158 offset:6144
	ds_read_b128 v[216:219], v158 offset:7168
	global_load_lds_dwordx4 v[220:221], off
	v_lshl_add_u64 v[220:221], s[26:27], 0, v[140:141]
	s_add_i32 m0, s25, 0xe000
	s_nop 0
	global_load_lds_dwordx4 v[220:221], off
	s_waitcnt vmcnt(8)
	s_waitcnt lgkmcnt(0)
	s_barrier
	s_setprio 1
	v_mfma_f32_16x16x32_bf16 v[126:129], v[148:151], v[188:191], v[126:129]
	v_mfma_f32_16x16x32_bf16 v[122:125], v[164:167], v[188:191], v[122:125]
	v_mfma_f32_16x16x32_bf16 v[114:117], v[148:151], v[196:199], v[114:117]
	v_mfma_f32_16x16x32_bf16 v[106:109], v[164:167], v[196:199], v[106:109]
	v_mfma_f32_16x16x32_bf16 v[98:101], v[148:151], v[204:207], v[98:101]
	v_mfma_f32_16x16x32_bf16 v[90:93], v[164:167], v[204:207], v[90:93]
	v_mfma_f32_16x16x32_bf16 v[82:85], v[148:151], v[212:215], v[82:85]
	v_mfma_f32_16x16x32_bf16 v[74:77], v[164:167], v[212:215], v[74:77]
	v_mfma_f32_16x16x32_bf16 v[126:129], v[160:163], v[192:195], v[126:129]
	v_mfma_f32_16x16x32_bf16 v[122:125], v[168:171], v[192:195], v[122:125]
	v_mfma_f32_16x16x32_bf16 v[114:117], v[160:163], v[200:203], v[114:117]
	v_mfma_f32_16x16x32_bf16 v[106:109], v[168:171], v[200:203], v[106:109]
	v_mfma_f32_16x16x32_bf16 v[98:101], v[160:163], v[208:211], v[98:101]
	v_mfma_f32_16x16x32_bf16 v[90:93], v[168:171], v[208:211], v[90:93]
	v_mfma_f32_16x16x32_bf16 v[82:85], v[160:163], v[216:219], v[82:85]
	v_mfma_f32_16x16x32_bf16 v[74:77], v[168:171], v[216:219], v[74:77]
	v_mfma_f32_16x16x32_bf16 v[118:121], v[172:175], v[188:191], v[118:121]
	v_mfma_f32_16x16x32_bf16 v[110:113], v[180:183], v[188:191], v[110:113]
	v_mfma_f32_16x16x32_bf16 v[102:105], v[172:175], v[196:199], v[102:105]
	v_mfma_f32_16x16x32_bf16 v[94:97], v[180:183], v[196:199], v[94:97]
	v_mfma_f32_16x16x32_bf16 v[86:89], v[172:175], v[204:207], v[86:89]
	v_mfma_f32_16x16x32_bf16 v[78:81], v[180:183], v[204:207], v[78:81]
	v_mfma_f32_16x16x32_bf16 v[70:73], v[172:175], v[212:215], v[70:73]
	v_mfma_f32_16x16x32_bf16 v[66:69], v[180:183], v[212:215], v[66:69]
	v_mfma_f32_16x16x32_bf16 v[118:121], v[176:179], v[192:195], v[118:121]
	v_mfma_f32_16x16x32_bf16 v[110:113], v[184:187], v[192:195], v[110:113]
	v_mfma_f32_16x16x32_bf16 v[102:105], v[176:179], v[200:203], v[102:105]
	v_mfma_f32_16x16x32_bf16 v[94:97], v[184:187], v[200:203], v[94:97]
	v_mfma_f32_16x16x32_bf16 v[86:89], v[176:179], v[208:211], v[86:89]
	v_mfma_f32_16x16x32_bf16 v[78:81], v[184:187], v[208:211], v[78:81]
	v_mfma_f32_16x16x32_bf16 v[70:73], v[176:179], v[216:219], v[70:73]
	v_mfma_f32_16x16x32_bf16 v[66:69], v[184:187], v[216:219], v[66:69]
	s_setprio 0
	s_barrier
	s_add_i32 s52, s44, s34
	v_lshl_add_u64 v[220:221], s[28:29], 0, v[134:135]
	s_mov_b32 m0, s52
	ds_read_b128 v[188:191], v158 offset:16384
	ds_read_b128 v[192:195], v158 offset:17408
	ds_read_b128 v[196:199], v158 offset:18432
	ds_read_b128 v[200:203], v158 offset:19456
	ds_read_b128 v[204:207], v158 offset:20480
	ds_read_b128 v[208:211], v158 offset:21504
	ds_read_b128 v[212:215], v158 offset:22528
	ds_read_b128 v[216:219], v158 offset:23552
	global_load_lds_dwordx4 v[220:221], off
	s_add_i32 m0, s52, 0x2000
	s_add_u32 s52, s28, 0x100000
	v_lshl_add_u64 v[222:223], s[28:29], 0, v[130:131]
	s_addc_u32 s53, s29, 0
	s_add_i32 s54, s45, s34
	global_load_lds_dwordx4 v[222:223], off
	v_lshl_add_u64 v[224:225], s[52:53], 0, v[134:135]
	s_mov_b32 m0, s54
	v_lshl_add_u64 v[226:227], s[30:31], 0, v[132:133]
	global_load_lds_dwordx4 v[224:225], off
	v_lshl_add_u64 v[224:225], s[52:53], 0, v[130:131]
	s_add_i32 m0, s54, 0x2000
	s_nop 0
	global_load_lds_dwordx4 v[224:225], off
	v_lshl_add_u64 v[224:225], s[30:31], 0, v[136:137]
	s_mov_b32 m0, s25
	s_nop 0
	global_load_lds_dwordx4 v[224:225], off
	s_mov_b32 m0, s37
	s_nop 0
	global_load_lds_dwordx4 v[226:227], off
	s_waitcnt vmcnt(8)
	s_waitcnt lgkmcnt(0)
	s_barrier
	s_setprio 1
	v_mfma_f32_16x16x32_bf16 v[62:65], v[148:151], v[188:191], v[62:65]
	v_mfma_f32_16x16x32_bf16 v[58:61], v[164:167], v[188:191], v[58:61]
	v_mfma_f32_16x16x32_bf16 v[50:53], v[148:151], v[196:199], v[50:53]
	v_mfma_f32_16x16x32_bf16 v[42:45], v[164:167], v[196:199], v[42:45]
	v_mfma_f32_16x16x32_bf16 v[34:37], v[148:151], v[204:207], v[34:37]
	v_mfma_f32_16x16x32_bf16 v[26:29], v[164:167], v[204:207], v[26:29]
	v_mfma_f32_16x16x32_bf16 v[18:21], v[148:151], v[212:215], v[18:21]
	v_mfma_f32_16x16x32_bf16 v[10:13], v[164:167], v[212:215], v[10:13]
	v_mfma_f32_16x16x32_bf16 v[62:65], v[160:163], v[192:195], v[62:65]
	v_mfma_f32_16x16x32_bf16 v[58:61], v[168:171], v[192:195], v[58:61]
	v_mfma_f32_16x16x32_bf16 v[50:53], v[160:163], v[200:203], v[50:53]
	v_mfma_f32_16x16x32_bf16 v[42:45], v[168:171], v[200:203], v[42:45]
	v_mfma_f32_16x16x32_bf16 v[34:37], v[160:163], v[208:211], v[34:37]
	v_mfma_f32_16x16x32_bf16 v[26:29], v[168:171], v[208:211], v[26:29]
	v_mfma_f32_16x16x32_bf16 v[18:21], v[160:163], v[216:219], v[18:21]
	v_mfma_f32_16x16x32_bf16 v[10:13], v[168:171], v[216:219], v[10:13]
	v_mfma_f32_16x16x32_bf16 v[54:57], v[172:175], v[188:191], v[54:57]
	v_mfma_f32_16x16x32_bf16 v[46:49], v[180:183], v[188:191], v[46:49]
	v_mfma_f32_16x16x32_bf16 v[38:41], v[172:175], v[196:199], v[38:41]
	v_mfma_f32_16x16x32_bf16 v[30:33], v[180:183], v[196:199], v[30:33]
	v_mfma_f32_16x16x32_bf16 v[22:25], v[172:175], v[204:207], v[22:25]
	v_mfma_f32_16x16x32_bf16 v[14:17], v[180:183], v[204:207], v[14:17]
	v_mfma_f32_16x16x32_bf16 v[6:9], v[172:175], v[212:215], v[6:9]
	v_mfma_f32_16x16x32_bf16 v[2:5], v[180:183], v[212:215], v[2:5]
	v_mfma_f32_16x16x32_bf16 v[54:57], v[176:179], v[192:195], v[54:57]
	v_mfma_f32_16x16x32_bf16 v[46:49], v[184:187], v[192:195], v[46:49]
	v_mfma_f32_16x16x32_bf16 v[38:41], v[176:179], v[200:203], v[38:41]
	v_mfma_f32_16x16x32_bf16 v[30:33], v[184:187], v[200:203], v[30:33]
	v_mfma_f32_16x16x32_bf16 v[22:25], v[176:179], v[208:211], v[22:25]
	v_mfma_f32_16x16x32_bf16 v[14:17], v[184:187], v[208:211], v[14:17]
	v_mfma_f32_16x16x32_bf16 v[6:9], v[176:179], v[216:219], v[6:9]
	v_mfma_f32_16x16x32_bf16 v[2:5], v[184:187], v[216:219], v[2:5]
	s_setprio 0
	s_barrier
	s_add_i32 s52, 0, 0x18000
	v_add_u32_e32 v146, s52, v154
	s_add_i32 s53, 0, 0x1c000
	ds_read_b128 v[148:151], v146
	ds_read_b128 v[160:163], v146 offset:1024
	ds_read_b128 v[164:167], v146 offset:2048
	ds_read_b128 v[168:171], v146 offset:3072
	v_add_u32_e32 v146, s53, v154
	ds_read_b128 v[172:175], v146
	ds_read_b128 v[176:179], v146 offset:1024
	ds_read_b128 v[180:183], v146 offset:2048
	ds_read_b128 v[184:187], v146 offset:3072
	s_add_u32 s30, s30, 0x100000
	s_addc_u32 s31, s31, 0
	s_mov_b32 m0, s38
	v_lshl_add_u64 v[228:229], s[30:31], 0, v[136:137]
	ds_read_b128 v[188:191], v158 offset:32768
	ds_read_b128 v[192:195], v158 offset:33792
	ds_read_b128 v[196:199], v158 offset:34816
	ds_read_b128 v[200:203], v158 offset:35840
	ds_read_b128 v[204:207], v158 offset:36864
	ds_read_b128 v[208:211], v158 offset:37888
	ds_read_b128 v[212:215], v158 offset:38912
	ds_read_b128 v[216:219], v158 offset:39936
	global_load_lds_dwordx4 v[228:229], off
	v_lshl_add_u64 v[228:229], s[30:31], 0, v[132:133]
	s_mov_b32 m0, s39
	s_nop 0
	global_load_lds_dwordx4 v[228:229], off
	s_waitcnt vmcnt(8)
	s_waitcnt lgkmcnt(0)
	s_barrier
	s_setprio 1
	v_mfma_f32_16x16x32_bf16 v[126:129], v[148:151], v[188:191], v[126:129]
	v_mfma_f32_16x16x32_bf16 v[122:125], v[164:167], v[188:191], v[122:125]
	v_mfma_f32_16x16x32_bf16 v[114:117], v[148:151], v[196:199], v[114:117]
	v_mfma_f32_16x16x32_bf16 v[106:109], v[164:167], v[196:199], v[106:109]
	v_mfma_f32_16x16x32_bf16 v[98:101], v[148:151], v[204:207], v[98:101]
	v_mfma_f32_16x16x32_bf16 v[90:93], v[164:167], v[204:207], v[90:93]
	v_mfma_f32_16x16x32_bf16 v[82:85], v[148:151], v[212:215], v[82:85]
	v_mfma_f32_16x16x32_bf16 v[74:77], v[164:167], v[212:215], v[74:77]
	v_mfma_f32_16x16x32_bf16 v[126:129], v[160:163], v[192:195], v[126:129]
	v_mfma_f32_16x16x32_bf16 v[122:125], v[168:171], v[192:195], v[122:125]
	v_mfma_f32_16x16x32_bf16 v[114:117], v[160:163], v[200:203], v[114:117]
	v_mfma_f32_16x16x32_bf16 v[106:109], v[168:171], v[200:203], v[106:109]
	v_mfma_f32_16x16x32_bf16 v[98:101], v[160:163], v[208:211], v[98:101]
	v_mfma_f32_16x16x32_bf16 v[90:93], v[168:171], v[208:211], v[90:93]
	v_mfma_f32_16x16x32_bf16 v[82:85], v[160:163], v[216:219], v[82:85]
	v_mfma_f32_16x16x32_bf16 v[74:77], v[168:171], v[216:219], v[74:77]
	v_mfma_f32_16x16x32_bf16 v[118:121], v[172:175], v[188:191], v[118:121]
	v_mfma_f32_16x16x32_bf16 v[110:113], v[180:183], v[188:191], v[110:113]
	v_mfma_f32_16x16x32_bf16 v[102:105], v[172:175], v[196:199], v[102:105]
	v_mfma_f32_16x16x32_bf16 v[94:97], v[180:183], v[196:199], v[94:97]
	v_mfma_f32_16x16x32_bf16 v[86:89], v[172:175], v[204:207], v[86:89]
	v_mfma_f32_16x16x32_bf16 v[78:81], v[180:183], v[204:207], v[78:81]
	v_mfma_f32_16x16x32_bf16 v[70:73], v[172:175], v[212:215], v[70:73]
	v_mfma_f32_16x16x32_bf16 v[66:69], v[180:183], v[212:215], v[66:69]
	v_mfma_f32_16x16x32_bf16 v[118:121], v[176:179], v[192:195], v[118:121]
	v_mfma_f32_16x16x32_bf16 v[110:113], v[184:187], v[192:195], v[110:113]
	v_mfma_f32_16x16x32_bf16 v[102:105], v[176:179], v[200:203], v[102:105]
	v_mfma_f32_16x16x32_bf16 v[94:97], v[184:187], v[200:203], v[94:97]
	v_mfma_f32_16x16x32_bf16 v[86:89], v[176:179], v[208:211], v[86:89]
	v_mfma_f32_16x16x32_bf16 v[78:81], v[184:187], v[208:211], v[78:81]
	v_mfma_f32_16x16x32_bf16 v[70:73], v[176:179], v[216:219], v[70:73]
	v_mfma_f32_16x16x32_bf16 v[66:69], v[184:187], v[216:219], v[66:69]
	s_setprio 0
	s_barrier
	s_add_i32 s30, s52, s34
	v_lshl_add_u64 v[220:221], v[220:221], 0, s[12:13]
	s_mov_b32 m0, s30
	ds_read_b128 v[188:191], v158 offset:49152
	ds_read_b128 v[192:195], v158 offset:50176
	ds_read_b128 v[196:199], v158 offset:51200
	ds_read_b128 v[200:203], v158 offset:52224
	ds_read_b128 v[204:207], v158 offset:53248
	ds_read_b128 v[208:211], v158 offset:54272
	ds_read_b128 v[212:215], v158 offset:55296
	ds_read_b128 v[216:219], v158 offset:56320
	global_load_lds_dwordx4 v[220:221], off
	s_add_i32 m0, s30, 0x2000
	s_add_u32 s28, s28, 0x100080
	v_lshl_add_u64 v[220:221], v[222:223], 0, s[12:13]
	s_addc_u32 s29, s29, 0
	s_add_i32 s30, s53, s34
	global_load_lds_dwordx4 v[220:221], off
	v_lshl_add_u64 v[220:221], s[28:29], 0, v[134:135]
	s_mov_b32 m0, s30
	s_nop 0
	global_load_lds_dwordx4 v[220:221], off
	v_lshl_add_u64 v[220:221], s[28:29], 0, v[130:131]
	s_add_i32 m0, s30, 0x2000
	s_nop 0
	global_load_lds_dwordx4 v[220:221], off
	v_lshl_add_u64 v[220:221], v[224:225], 0, s[12:13]
	s_mov_b32 m0, s41
	s_nop 0
	global_load_lds_dwordx4 v[220:221], off
	v_lshl_add_u64 v[220:221], v[226:227], 0, s[12:13]
	s_mov_b32 m0, s42
	s_nop 0
	global_load_lds_dwordx4 v[220:221], off
	s_waitcnt vmcnt(8)
	s_waitcnt lgkmcnt(0)
	s_barrier
	s_setprio 1
	v_mfma_f32_16x16x32_bf16 v[62:65], v[148:151], v[188:191], v[62:65]
	v_mfma_f32_16x16x32_bf16 v[58:61], v[164:167], v[188:191], v[58:61]
	v_mfma_f32_16x16x32_bf16 v[50:53], v[148:151], v[196:199], v[50:53]
	v_mfma_f32_16x16x32_bf16 v[42:45], v[164:167], v[196:199], v[42:45]
	v_mfma_f32_16x16x32_bf16 v[34:37], v[148:151], v[204:207], v[34:37]
	v_mfma_f32_16x16x32_bf16 v[26:29], v[164:167], v[204:207], v[26:29]
	v_mfma_f32_16x16x32_bf16 v[18:21], v[148:151], v[212:215], v[18:21]
	v_mfma_f32_16x16x32_bf16 v[10:13], v[164:167], v[212:215], v[10:13]
	v_mfma_f32_16x16x32_bf16 v[62:65], v[160:163], v[192:195], v[62:65]
	v_mfma_f32_16x16x32_bf16 v[58:61], v[168:171], v[192:195], v[58:61]
	v_mfma_f32_16x16x32_bf16 v[50:53], v[160:163], v[200:203], v[50:53]
	v_mfma_f32_16x16x32_bf16 v[42:45], v[168:171], v[200:203], v[42:45]
	v_mfma_f32_16x16x32_bf16 v[34:37], v[160:163], v[208:211], v[34:37]
	v_mfma_f32_16x16x32_bf16 v[26:29], v[168:171], v[208:211], v[26:29]
	v_mfma_f32_16x16x32_bf16 v[18:21], v[160:163], v[216:219], v[18:21]
	v_mfma_f32_16x16x32_bf16 v[10:13], v[168:171], v[216:219], v[10:13]
	v_mfma_f32_16x16x32_bf16 v[54:57], v[172:175], v[188:191], v[54:57]
	v_mfma_f32_16x16x32_bf16 v[46:49], v[180:183], v[188:191], v[46:49]
	v_mfma_f32_16x16x32_bf16 v[38:41], v[172:175], v[196:199], v[38:41]
	v_mfma_f32_16x16x32_bf16 v[30:33], v[180:183], v[196:199], v[30:33]
	v_mfma_f32_16x16x32_bf16 v[22:25], v[172:175], v[204:207], v[22:25]
	v_mfma_f32_16x16x32_bf16 v[14:17], v[180:183], v[204:207], v[14:17]
	v_mfma_f32_16x16x32_bf16 v[6:9], v[172:175], v[212:215], v[6:9]
	v_mfma_f32_16x16x32_bf16 v[2:5], v[180:183], v[212:215], v[2:5]
	v_mfma_f32_16x16x32_bf16 v[54:57], v[176:179], v[192:195], v[54:57]
	v_mfma_f32_16x16x32_bf16 v[46:49], v[184:187], v[192:195], v[46:49]
	v_mfma_f32_16x16x32_bf16 v[38:41], v[176:179], v[200:203], v[38:41]
	v_mfma_f32_16x16x32_bf16 v[30:33], v[184:187], v[200:203], v[30:33]
	v_mfma_f32_16x16x32_bf16 v[22:25], v[176:179], v[208:211], v[22:25]
	v_mfma_f32_16x16x32_bf16 v[14:17], v[184:187], v[208:211], v[14:17]
	v_mfma_f32_16x16x32_bf16 v[6:9], v[176:179], v[216:219], v[6:9]
	v_mfma_f32_16x16x32_bf16 v[2:5], v[184:187], v[216:219], v[2:5]
	s_setprio 0
	s_barrier
	s_add_i32 s51, s51, 2
	s_add_u32 s26, s26, 0x100
	s_addc_u32 s27, s27, 0
	s_add_u32 s49, s49, 0x100
	s_addc_u32 s50, s50, 0
	s_cmp_gt_u32 s51, 61
	s_cbranch_scc0 .LBB0_1087
	s_and_b64 vcc, exec, s[14:15]
	s_cbranch_vccz .LBB0_1090
	s_barrier

.LBB0_1241:
	ds_read_b128 v[144:147], v162
	ds_read_b128 v[166:169], v162 offset:1024
	ds_read_b128 v[170:173], v162 offset:2048
	ds_read_b128 v[174:177], v162 offset:3072
	ds_read_b128 v[178:181], v163
	ds_read_b128 v[182:185], v163 offset:1024
	ds_read_b128 v[186:189], v163 offset:2048
	ds_read_b128 v[190:193], v163 offset:3072
	s_add_u32 s40, s38, 0xfff00080
	s_addc_u32 s41, s39, -1
	s_cmp_eq_u32 s63, 60
	s_cselect_b32 s43, s2, s41
	s_cselect_b32 s42, s29, s40
	s_cselect_b32 s41, s27, s62
	s_cselect_b32 s40, s60, s61
	v_lshl_add_u64 v[148:149], s[38:39], 0, v[138:139]
	s_add_i32 m0, s37, 0xc000
	ds_read_b128 v[194:197], v164
	ds_read_b128 v[198:201], v164 offset:1024
	ds_read_b128 v[202:205], v164 offset:2048
	ds_read_b128 v[206:209], v164 offset:3072
	ds_read_b128 v[210:213], v164 offset:4096
	ds_read_b128 v[214:217], v164 offset:5120
	ds_read_b128 v[218:221], v164 offset:6144
	ds_read_b128 v[222:225], v164 offset:7168
	global_load_lds_dwordx4 v[148:149], off
	v_lshl_add_u64 v[148:149], s[38:39], 0, v[140:141]
	s_add_i32 m0, s37, 0xe000
	s_nop 0
	global_load_lds_dwordx4 v[148:149], off
	s_waitcnt vmcnt(8)
	s_waitcnt lgkmcnt(0)
	s_barrier
	s_setprio 1
	v_mfma_f32_16x16x32_bf16 v[126:129], v[144:147], v[194:197], v[126:129]
	v_mfma_f32_16x16x32_bf16 v[122:125], v[170:173], v[194:197], v[122:125]
	v_mfma_f32_16x16x32_bf16 v[110:113], v[144:147], v[202:205], v[110:113]
	v_mfma_f32_16x16x32_bf16 v[106:109], v[170:173], v[202:205], v[106:109]
	v_mfma_f32_16x16x32_bf16 v[94:97], v[144:147], v[210:213], v[94:97]
	v_mfma_f32_16x16x32_bf16 v[90:93], v[170:173], v[210:213], v[90:93]
	v_mfma_f32_16x16x32_bf16 v[78:81], v[144:147], v[218:221], v[78:81]
	v_mfma_f32_16x16x32_bf16 v[74:77], v[170:173], v[218:221], v[74:77]
	v_mfma_f32_16x16x32_bf16 v[126:129], v[166:169], v[198:201], v[126:129]
	v_mfma_f32_16x16x32_bf16 v[122:125], v[174:177], v[198:201], v[122:125]
	v_mfma_f32_16x16x32_bf16 v[110:113], v[166:169], v[206:209], v[110:113]
	v_mfma_f32_16x16x32_bf16 v[106:109], v[174:177], v[206:209], v[106:109]
	v_mfma_f32_16x16x32_bf16 v[94:97], v[166:169], v[214:217], v[94:97]
	v_mfma_f32_16x16x32_bf16 v[90:93], v[174:177], v[214:217], v[90:93]
	v_mfma_f32_16x16x32_bf16 v[78:81], v[166:169], v[222:225], v[78:81]
	v_mfma_f32_16x16x32_bf16 v[74:77], v[174:177], v[222:225], v[74:77]
	v_mfma_f32_16x16x32_bf16 v[118:121], v[178:181], v[194:197], v[118:121]
	v_mfma_f32_16x16x32_bf16 v[114:117], v[186:189], v[194:197], v[114:117]
	v_mfma_f32_16x16x32_bf16 v[102:105], v[178:181], v[202:205], v[102:105]
	v_mfma_f32_16x16x32_bf16 v[98:101], v[186:189], v[202:205], v[98:101]
	v_mfma_f32_16x16x32_bf16 v[86:89], v[178:181], v[210:213], v[86:89]
	v_mfma_f32_16x16x32_bf16 v[82:85], v[186:189], v[210:213], v[82:85]
	v_mfma_f32_16x16x32_bf16 v[70:73], v[178:181], v[218:221], v[70:73]
	v_mfma_f32_16x16x32_bf16 v[66:69], v[186:189], v[218:221], v[66:69]
	v_mfma_f32_16x16x32_bf16 v[118:121], v[182:185], v[198:201], v[118:121]
	v_mfma_f32_16x16x32_bf16 v[114:117], v[190:193], v[198:201], v[114:117]
	v_mfma_f32_16x16x32_bf16 v[102:105], v[182:185], v[206:209], v[102:105]
	v_mfma_f32_16x16x32_bf16 v[98:101], v[190:193], v[206:209], v[98:101]
	v_mfma_f32_16x16x32_bf16 v[86:89], v[182:185], v[214:217], v[86:89]
	v_mfma_f32_16x16x32_bf16 v[82:85], v[190:193], v[214:217], v[82:85]
	v_mfma_f32_16x16x32_bf16 v[70:73], v[182:185], v[222:225], v[70:73]
	v_mfma_f32_16x16x32_bf16 v[66:69], v[190:193], v[222:225], v[66:69]
	s_setprio 0
	s_barrier
	s_add_i32 s64, s56, s45
	v_lshl_add_u64 v[148:149], s[40:41], 0, v[132:133]
	s_mov_b32 m0, s64
	ds_read_b128 v[194:197], v164 offset:16384
	ds_read_b128 v[198:201], v164 offset:17408
	ds_read_b128 v[202:205], v164 offset:18432
	ds_read_b128 v[206:209], v164 offset:19456
	ds_read_b128 v[210:213], v164 offset:20480
	ds_read_b128 v[214:217], v164 offset:21504
	ds_read_b128 v[218:221], v164 offset:22528
	ds_read_b128 v[222:225], v164 offset:23552
	global_load_lds_dwordx4 v[148:149], off
	s_add_i32 m0, s64, 0x2000
	s_add_u32 s64, s40, 0x100000
	v_lshl_add_u64 v[226:227], s[40:41], 0, v[136:137]
	s_addc_u32 s65, s41, 0
	s_add_i32 s66, s57, s45
	global_load_lds_dwordx4 v[226:227], off
	v_lshl_add_u64 v[228:229], s[64:65], 0, v[132:133]
	s_mov_b32 m0, s66
	v_lshl_add_u64 v[230:231], s[42:43], 0, v[134:135]
	global_load_lds_dwordx4 v[228:229], off
	v_lshl_add_u64 v[228:229], s[64:65], 0, v[136:137]
	s_add_i32 m0, s66, 0x2000
	s_nop 0
	global_load_lds_dwordx4 v[228:229], off
	v_lshl_add_u64 v[228:229], s[42:43], 0, v[130:131]
	s_mov_b32 m0, s37
	s_nop 0
	global_load_lds_dwordx4 v[228:229], off
	s_mov_b32 m0, s46
	s_nop 0
	global_load_lds_dwordx4 v[230:231], off
	s_waitcnt vmcnt(8)
	s_waitcnt lgkmcnt(0)
	s_barrier
	s_setprio 1
	v_mfma_f32_16x16x32_bf16 v[62:65], v[144:147], v[194:197], v[62:65]
	v_mfma_f32_16x16x32_bf16 v[58:61], v[170:173], v[194:197], v[58:61]
	v_mfma_f32_16x16x32_bf16 v[46:49], v[144:147], v[202:205], v[46:49]
	v_mfma_f32_16x16x32_bf16 v[42:45], v[170:173], v[202:205], v[42:45]
	v_mfma_f32_16x16x32_bf16 v[30:33], v[144:147], v[210:213], v[30:33]
	v_mfma_f32_16x16x32_bf16 v[26:29], v[170:173], v[210:213], v[26:29]
	v_mfma_f32_16x16x32_bf16 v[14:17], v[144:147], v[218:221], v[14:17]
	v_mfma_f32_16x16x32_bf16 v[10:13], v[170:173], v[218:221], v[10:13]
	v_mfma_f32_16x16x32_bf16 v[62:65], v[166:169], v[198:201], v[62:65]
	v_mfma_f32_16x16x32_bf16 v[58:61], v[174:177], v[198:201], v[58:61]
	v_mfma_f32_16x16x32_bf16 v[46:49], v[166:169], v[206:209], v[46:49]
	v_mfma_f32_16x16x32_bf16 v[42:45], v[174:177], v[206:209], v[42:45]
	v_mfma_f32_16x16x32_bf16 v[30:33], v[166:169], v[214:217], v[30:33]
	v_mfma_f32_16x16x32_bf16 v[26:29], v[174:177], v[214:217], v[26:29]
	v_mfma_f32_16x16x32_bf16 v[14:17], v[166:169], v[222:225], v[14:17]
	v_mfma_f32_16x16x32_bf16 v[10:13], v[174:177], v[222:225], v[10:13]
	v_mfma_f32_16x16x32_bf16 v[54:57], v[178:181], v[194:197], v[54:57]
	v_mfma_f32_16x16x32_bf16 v[50:53], v[186:189], v[194:197], v[50:53]
	v_mfma_f32_16x16x32_bf16 v[38:41], v[178:181], v[202:205], v[38:41]
	v_mfma_f32_16x16x32_bf16 v[34:37], v[186:189], v[202:205], v[34:37]
	v_mfma_f32_16x16x32_bf16 v[22:25], v[178:181], v[210:213], v[22:25]
	v_mfma_f32_16x16x32_bf16 v[18:21], v[186:189], v[210:213], v[18:21]
	v_mfma_f32_16x16x32_bf16 v[6:9], v[178:181], v[218:221], v[6:9]
	v_mfma_f32_16x16x32_bf16 v[2:5], v[186:189], v[218:221], v[2:5]
	v_mfma_f32_16x16x32_bf16 v[54:57], v[182:185], v[198:201], v[54:57]
	v_mfma_f32_16x16x32_bf16 v[50:53], v[190:193], v[198:201], v[50:53]
	v_mfma_f32_16x16x32_bf16 v[38:41], v[182:185], v[206:209], v[38:41]
	v_mfma_f32_16x16x32_bf16 v[34:37], v[190:193], v[206:209], v[34:37]
	v_mfma_f32_16x16x32_bf16 v[22:25], v[182:185], v[214:217], v[22:25]
	v_mfma_f32_16x16x32_bf16 v[18:21], v[190:193], v[214:217], v[18:21]
	v_mfma_f32_16x16x32_bf16 v[6:9], v[182:185], v[222:225], v[6:9]
	v_mfma_f32_16x16x32_bf16 v[2:5], v[190:193], v[222:225], v[2:5]
	s_setprio 0
	s_barrier
	s_add_i32 s64, 0, 0x18000
	v_add_u32_e32 v142, s64, v160
	s_add_i32 s65, 0, 0x1c000
	ds_read_b128 v[144:147], v142
	ds_read_b128 v[166:169], v142 offset:1024
	ds_read_b128 v[170:173], v142 offset:2048
	ds_read_b128 v[174:177], v142 offset:3072
	v_add_u32_e32 v142, s65, v160
	ds_read_b128 v[178:181], v142
	ds_read_b128 v[182:185], v142 offset:1024
	ds_read_b128 v[186:189], v142 offset:2048
	ds_read_b128 v[190:193], v142 offset:3072
	s_add_u32 s42, s42, 0x100000
	s_addc_u32 s43, s43, 0
	s_mov_b32 m0, s47
	v_lshl_add_u64 v[232:233], s[42:43], 0, v[130:131]
	ds_read_b128 v[194:197], v164 offset:32768
	ds_read_b128 v[198:201], v164 offset:33792
	ds_read_b128 v[202:205], v164 offset:34816
	ds_read_b128 v[206:209], v164 offset:35840
	ds_read_b128 v[210:213], v164 offset:36864
	ds_read_b128 v[214:217], v164 offset:37888
	ds_read_b128 v[218:221], v164 offset:38912
	ds_read_b128 v[222:225], v164 offset:39936
	global_load_lds_dwordx4 v[232:233], off
	v_lshl_add_u64 v[232:233], s[42:43], 0, v[134:135]
	s_mov_b32 m0, s48
	s_nop 0
	global_load_lds_dwordx4 v[232:233], off
	s_waitcnt vmcnt(8)
	s_waitcnt lgkmcnt(0)
	s_barrier
	s_setprio 1
	v_mfma_f32_16x16x32_bf16 v[126:129], v[144:147], v[194:197], v[126:129]
	v_mfma_f32_16x16x32_bf16 v[122:125], v[170:173], v[194:197], v[122:125]
	v_mfma_f32_16x16x32_bf16 v[110:113], v[144:147], v[202:205], v[110:113]
	v_mfma_f32_16x16x32_bf16 v[106:109], v[170:173], v[202:205], v[106:109]
	v_mfma_f32_16x16x32_bf16 v[94:97], v[144:147], v[210:213], v[94:97]
	v_mfma_f32_16x16x32_bf16 v[90:93], v[170:173], v[210:213], v[90:93]
	v_mfma_f32_16x16x32_bf16 v[78:81], v[144:147], v[218:221], v[78:81]
	v_mfma_f32_16x16x32_bf16 v[74:77], v[170:173], v[218:221], v[74:77]
	v_mfma_f32_16x16x32_bf16 v[126:129], v[166:169], v[198:201], v[126:129]
	v_mfma_f32_16x16x32_bf16 v[122:125], v[174:177], v[198:201], v[122:125]
	v_mfma_f32_16x16x32_bf16 v[110:113], v[166:169], v[206:209], v[110:113]
	v_mfma_f32_16x16x32_bf16 v[106:109], v[174:177], v[206:209], v[106:109]
	v_mfma_f32_16x16x32_bf16 v[94:97], v[166:169], v[214:217], v[94:97]
	v_mfma_f32_16x16x32_bf16 v[90:93], v[174:177], v[214:217], v[90:93]
	v_mfma_f32_16x16x32_bf16 v[78:81], v[166:169], v[222:225], v[78:81]
	v_mfma_f32_16x16x32_bf16 v[74:77], v[174:177], v[222:225], v[74:77]
	v_mfma_f32_16x16x32_bf16 v[118:121], v[178:181], v[194:197], v[118:121]
	v_mfma_f32_16x16x32_bf16 v[114:117], v[186:189], v[194:197], v[114:117]
	v_mfma_f32_16x16x32_bf16 v[102:105], v[178:181], v[202:205], v[102:105]
	v_mfma_f32_16x16x32_bf16 v[98:101], v[186:189], v[202:205], v[98:101]
	v_mfma_f32_16x16x32_bf16 v[86:89], v[178:181], v[210:213], v[86:89]
	v_mfma_f32_16x16x32_bf16 v[82:85], v[186:189], v[210:213], v[82:85]
	v_mfma_f32_16x16x32_bf16 v[70:73], v[178:181], v[218:221], v[70:73]
	v_mfma_f32_16x16x32_bf16 v[66:69], v[186:189], v[218:221], v[66:69]
	v_mfma_f32_16x16x32_bf16 v[118:121], v[182:185], v[198:201], v[118:121]
	v_mfma_f32_16x16x32_bf16 v[114:117], v[190:193], v[198:201], v[114:117]
	v_mfma_f32_16x16x32_bf16 v[102:105], v[182:185], v[206:209], v[102:105]
	v_mfma_f32_16x16x32_bf16 v[98:101], v[190:193], v[206:209], v[98:101]
	v_mfma_f32_16x16x32_bf16 v[86:89], v[182:185], v[214:217], v[86:89]
	v_mfma_f32_16x16x32_bf16 v[82:85], v[190:193], v[214:217], v[82:85]
	v_mfma_f32_16x16x32_bf16 v[70:73], v[182:185], v[222:225], v[70:73]
	v_mfma_f32_16x16x32_bf16 v[66:69], v[190:193], v[222:225], v[66:69]
	s_setprio 0
	s_barrier
	s_add_i32 s42, s64, s45
	v_lshl_add_u64 v[148:149], v[148:149], 0, s[12:13]
	s_mov_b32 m0, s42
	ds_read_b128 v[194:197], v164 offset:49152
	ds_read_b128 v[198:201], v164 offset:50176
	ds_read_b128 v[202:205], v164 offset:51200
	ds_read_b128 v[206:209], v164 offset:52224
	ds_read_b128 v[210:213], v164 offset:53248
	ds_read_b128 v[214:217], v164 offset:54272
	ds_read_b128 v[218:221], v164 offset:55296
	ds_read_b128 v[222:225], v164 offset:56320
	global_load_lds_dwordx4 v[148:149], off
	s_add_i32 m0, s42, 0x2000
	s_add_u32 s40, s40, 0x100080
	v_lshl_add_u64 v[148:149], v[226:227], 0, s[12:13]
	s_addc_u32 s41, s41, 0
	s_add_i32 s42, s65, s45
	global_load_lds_dwordx4 v[148:149], off
	v_lshl_add_u64 v[148:149], s[40:41], 0, v[132:133]
	s_mov_b32 m0, s42
	s_nop 0
	global_load_lds_dwordx4 v[148:149], off
	v_lshl_add_u64 v[148:149], s[40:41], 0, v[136:137]
	s_add_i32 m0, s42, 0x2000
	s_nop 0
	global_load_lds_dwordx4 v[148:149], off
	v_lshl_add_u64 v[148:149], v[228:229], 0, s[12:13]
	s_mov_b32 m0, s53
	s_nop 0
	global_load_lds_dwordx4 v[148:149], off
	v_lshl_add_u64 v[148:149], v[230:231], 0, s[12:13]
	s_mov_b32 m0, s54
	s_nop 0
	global_load_lds_dwordx4 v[148:149], off
	s_waitcnt vmcnt(8)
	s_waitcnt lgkmcnt(0)
	s_barrier
	s_setprio 1
	v_mfma_f32_16x16x32_bf16 v[62:65], v[144:147], v[194:197], v[62:65]
	v_mfma_f32_16x16x32_bf16 v[58:61], v[170:173], v[194:197], v[58:61]
	v_mfma_f32_16x16x32_bf16 v[46:49], v[144:147], v[202:205], v[46:49]
	v_mfma_f32_16x16x32_bf16 v[42:45], v[170:173], v[202:205], v[42:45]
	v_mfma_f32_16x16x32_bf16 v[30:33], v[144:147], v[210:213], v[30:33]
	v_mfma_f32_16x16x32_bf16 v[26:29], v[170:173], v[210:213], v[26:29]
	v_mfma_f32_16x16x32_bf16 v[14:17], v[144:147], v[218:221], v[14:17]
	v_mfma_f32_16x16x32_bf16 v[10:13], v[170:173], v[218:221], v[10:13]
	v_mfma_f32_16x16x32_bf16 v[62:65], v[166:169], v[198:201], v[62:65]
	v_mfma_f32_16x16x32_bf16 v[58:61], v[174:177], v[198:201], v[58:61]
	v_mfma_f32_16x16x32_bf16 v[46:49], v[166:169], v[206:209], v[46:49]
	v_mfma_f32_16x16x32_bf16 v[42:45], v[174:177], v[206:209], v[42:45]
	v_mfma_f32_16x16x32_bf16 v[30:33], v[166:169], v[214:217], v[30:33]
	v_mfma_f32_16x16x32_bf16 v[26:29], v[174:177], v[214:217], v[26:29]
	v_mfma_f32_16x16x32_bf16 v[14:17], v[166:169], v[222:225], v[14:17]
	v_mfma_f32_16x16x32_bf16 v[10:13], v[174:177], v[222:225], v[10:13]
	v_mfma_f32_16x16x32_bf16 v[54:57], v[178:181], v[194:197], v[54:57]
	v_mfma_f32_16x16x32_bf16 v[50:53], v[186:189], v[194:197], v[50:53]
	v_mfma_f32_16x16x32_bf16 v[38:41], v[178:181], v[202:205], v[38:41]
	v_mfma_f32_16x16x32_bf16 v[34:37], v[186:189], v[202:205], v[34:37]
	v_mfma_f32_16x16x32_bf16 v[22:25], v[178:181], v[210:213], v[22:25]
	v_mfma_f32_16x16x32_bf16 v[18:21], v[186:189], v[210:213], v[18:21]
	v_mfma_f32_16x16x32_bf16 v[6:9], v[178:181], v[218:221], v[6:9]
	v_mfma_f32_16x16x32_bf16 v[2:5], v[186:189], v[218:221], v[2:5]
	v_mfma_f32_16x16x32_bf16 v[54:57], v[182:185], v[198:201], v[54:57]
	v_mfma_f32_16x16x32_bf16 v[50:53], v[190:193], v[198:201], v[50:53]
	v_mfma_f32_16x16x32_bf16 v[38:41], v[182:185], v[206:209], v[38:41]
	v_mfma_f32_16x16x32_bf16 v[34:37], v[190:193], v[206:209], v[34:37]
	v_mfma_f32_16x16x32_bf16 v[22:25], v[182:185], v[214:217], v[22:25]
	v_mfma_f32_16x16x32_bf16 v[18:21], v[190:193], v[214:217], v[18:21]
	v_mfma_f32_16x16x32_bf16 v[6:9], v[182:185], v[222:225], v[6:9]
	v_mfma_f32_16x16x32_bf16 v[2:5], v[190:193], v[222:225], v[2:5]
	s_setprio 0
	s_barrier
	s_add_i32 s63, s63, 2
	s_add_u32 s38, s38, 0x100
	s_addc_u32 s39, s39, 0
	s_add_u32 s61, s61, 0x100
	s_addc_u32 s62, s62, 0
	s_cmp_gt_u32 s63, 61
	s_cbranch_scc0 .LBB0_1241
	s_and_b64 vcc, exec, s[14:15]
	s_cbranch_vccz .LBB0_1244
	s_barrier

.LBB0_1294:
	ds_read_b128 v[144:147], v151
	ds_read_b128 v[160:163], v151 offset:1024
	ds_read_b128 v[164:167], v151 offset:2048
	ds_read_b128 v[168:171], v151 offset:3072
	ds_read_b128 v[172:175], v152
	ds_read_b128 v[176:179], v152 offset:1024
	ds_read_b128 v[180:183], v152 offset:2048
	ds_read_b128 v[184:187], v152 offset:3072
	s_add_u32 s40, s38, 0xfff00080
	s_addc_u32 s41, s39, -1
	s_cmp_eq_u32 s64, 60
	s_cselect_b32 s43, s2, s41
	s_cselect_b32 s42, s29, s40
	s_cselect_b32 s41, s27, s63
	s_cselect_b32 s40, s61, s62
	v_lshl_add_u64 v[148:149], s[38:39], 0, v[138:139]
	s_add_i32 m0, s37, 0xc000
	ds_read_b128 v[188:191], v153
	ds_read_b128 v[192:195], v153 offset:1024
	ds_read_b128 v[196:199], v153 offset:2048
	ds_read_b128 v[200:203], v153 offset:3072
	ds_read_b128 v[204:207], v153 offset:4096
	ds_read_b128 v[208:211], v153 offset:5120
	ds_read_b128 v[212:215], v153 offset:6144
	ds_read_b128 v[216:219], v153 offset:7168
	global_load_lds_dwordx4 v[148:149], off
	v_lshl_add_u64 v[148:149], s[38:39], 0, v[140:141]
	s_add_i32 m0, s37, 0xe000
	s_nop 0
	global_load_lds_dwordx4 v[148:149], off
	s_waitcnt vmcnt(8)
	s_waitcnt lgkmcnt(0)
	s_barrier
	s_setprio 1
	v_mfma_f32_16x16x32_bf16 v[126:129], v[144:147], v[188:191], v[126:129]
	v_mfma_f32_16x16x32_bf16 v[122:125], v[164:167], v[188:191], v[122:125]
	v_mfma_f32_16x16x32_bf16 v[110:113], v[144:147], v[196:199], v[110:113]
	v_mfma_f32_16x16x32_bf16 v[106:109], v[164:167], v[196:199], v[106:109]
	v_mfma_f32_16x16x32_bf16 v[94:97], v[144:147], v[204:207], v[94:97]
	v_mfma_f32_16x16x32_bf16 v[90:93], v[164:167], v[204:207], v[90:93]
	v_mfma_f32_16x16x32_bf16 v[78:81], v[144:147], v[212:215], v[78:81]
	v_mfma_f32_16x16x32_bf16 v[74:77], v[164:167], v[212:215], v[74:77]
	v_mfma_f32_16x16x32_bf16 v[126:129], v[160:163], v[192:195], v[126:129]
	v_mfma_f32_16x16x32_bf16 v[122:125], v[168:171], v[192:195], v[122:125]
	v_mfma_f32_16x16x32_bf16 v[110:113], v[160:163], v[200:203], v[110:113]
	v_mfma_f32_16x16x32_bf16 v[106:109], v[168:171], v[200:203], v[106:109]
	v_mfma_f32_16x16x32_bf16 v[94:97], v[160:163], v[208:211], v[94:97]
	v_mfma_f32_16x16x32_bf16 v[90:93], v[168:171], v[208:211], v[90:93]
	v_mfma_f32_16x16x32_bf16 v[78:81], v[160:163], v[216:219], v[78:81]
	v_mfma_f32_16x16x32_bf16 v[74:77], v[168:171], v[216:219], v[74:77]
	v_mfma_f32_16x16x32_bf16 v[118:121], v[172:175], v[188:191], v[118:121]
	v_mfma_f32_16x16x32_bf16 v[114:117], v[180:183], v[188:191], v[114:117]
	v_mfma_f32_16x16x32_bf16 v[102:105], v[172:175], v[196:199], v[102:105]
	v_mfma_f32_16x16x32_bf16 v[98:101], v[180:183], v[196:199], v[98:101]
	v_mfma_f32_16x16x32_bf16 v[86:89], v[172:175], v[204:207], v[86:89]
	v_mfma_f32_16x16x32_bf16 v[82:85], v[180:183], v[204:207], v[82:85]
	v_mfma_f32_16x16x32_bf16 v[70:73], v[172:175], v[212:215], v[70:73]
	v_mfma_f32_16x16x32_bf16 v[66:69], v[180:183], v[212:215], v[66:69]
	v_mfma_f32_16x16x32_bf16 v[118:121], v[176:179], v[192:195], v[118:121]
	v_mfma_f32_16x16x32_bf16 v[114:117], v[184:187], v[192:195], v[114:117]
	v_mfma_f32_16x16x32_bf16 v[102:105], v[176:179], v[200:203], v[102:105]
	v_mfma_f32_16x16x32_bf16 v[98:101], v[184:187], v[200:203], v[98:101]
	v_mfma_f32_16x16x32_bf16 v[86:89], v[176:179], v[208:211], v[86:89]
	v_mfma_f32_16x16x32_bf16 v[82:85], v[184:187], v[208:211], v[82:85]
	v_mfma_f32_16x16x32_bf16 v[70:73], v[176:179], v[216:219], v[70:73]
	v_mfma_f32_16x16x32_bf16 v[66:69], v[184:187], v[216:219], v[66:69]
	s_setprio 0
	s_barrier
	s_add_i32 s65, s57, s46
	v_lshl_add_u64 v[148:149], s[40:41], 0, v[132:133]
	s_mov_b32 m0, s65
	ds_read_b128 v[188:191], v153 offset:16384
	ds_read_b128 v[192:195], v153 offset:17408
	ds_read_b128 v[196:199], v153 offset:18432
	ds_read_b128 v[200:203], v153 offset:19456
	ds_read_b128 v[204:207], v153 offset:20480
	ds_read_b128 v[208:211], v153 offset:21504
	ds_read_b128 v[212:215], v153 offset:22528
	ds_read_b128 v[216:219], v153 offset:23552
	global_load_lds_dwordx4 v[148:149], off
	s_add_i32 m0, s65, 0x2000
	s_add_u32 s66, s40, 0x100000
	v_lshl_add_u64 v[220:221], s[40:41], 0, v[136:137]
	s_addc_u32 s67, s41, 0
	s_add_i32 s65, s58, s46
	global_load_lds_dwordx4 v[220:221], off
	v_lshl_add_u64 v[222:223], s[66:67], 0, v[132:133]
	s_mov_b32 m0, s65
	v_lshl_add_u64 v[224:225], s[42:43], 0, v[134:135]
	global_load_lds_dwordx4 v[222:223], off
	v_lshl_add_u64 v[222:223], s[66:67], 0, v[136:137]
	s_add_i32 m0, s65, 0x2000
	s_nop 0
	global_load_lds_dwordx4 v[222:223], off
	v_lshl_add_u64 v[222:223], s[42:43], 0, v[130:131]
	s_mov_b32 m0, s37
	s_nop 0
	global_load_lds_dwordx4 v[222:223], off
	s_mov_b32 m0, s47
	s_nop 0
	global_load_lds_dwordx4 v[224:225], off
	s_waitcnt vmcnt(8)
	s_waitcnt lgkmcnt(0)
	s_barrier
	s_setprio 1
	v_mfma_f32_16x16x32_bf16 v[62:65], v[144:147], v[188:191], v[62:65]
	v_mfma_f32_16x16x32_bf16 v[58:61], v[164:167], v[188:191], v[58:61]
	v_mfma_f32_16x16x32_bf16 v[46:49], v[144:147], v[196:199], v[46:49]
	v_mfma_f32_16x16x32_bf16 v[42:45], v[164:167], v[196:199], v[42:45]
	v_mfma_f32_16x16x32_bf16 v[30:33], v[144:147], v[204:207], v[30:33]
	v_mfma_f32_16x16x32_bf16 v[26:29], v[164:167], v[204:207], v[26:29]
	v_mfma_f32_16x16x32_bf16 v[14:17], v[144:147], v[212:215], v[14:17]
	v_mfma_f32_16x16x32_bf16 v[10:13], v[164:167], v[212:215], v[10:13]
	v_mfma_f32_16x16x32_bf16 v[62:65], v[160:163], v[192:195], v[62:65]
	v_mfma_f32_16x16x32_bf16 v[58:61], v[168:171], v[192:195], v[58:61]
	v_mfma_f32_16x16x32_bf16 v[46:49], v[160:163], v[200:203], v[46:49]
	v_mfma_f32_16x16x32_bf16 v[42:45], v[168:171], v[200:203], v[42:45]
	v_mfma_f32_16x16x32_bf16 v[30:33], v[160:163], v[208:211], v[30:33]
	v_mfma_f32_16x16x32_bf16 v[26:29], v[168:171], v[208:211], v[26:29]
	v_mfma_f32_16x16x32_bf16 v[14:17], v[160:163], v[216:219], v[14:17]
	v_mfma_f32_16x16x32_bf16 v[10:13], v[168:171], v[216:219], v[10:13]
	v_mfma_f32_16x16x32_bf16 v[54:57], v[172:175], v[188:191], v[54:57]
	v_mfma_f32_16x16x32_bf16 v[50:53], v[180:183], v[188:191], v[50:53]
	v_mfma_f32_16x16x32_bf16 v[38:41], v[172:175], v[196:199], v[38:41]
	v_mfma_f32_16x16x32_bf16 v[34:37], v[180:183], v[196:199], v[34:37]
	v_mfma_f32_16x16x32_bf16 v[22:25], v[172:175], v[204:207], v[22:25]
	v_mfma_f32_16x16x32_bf16 v[18:21], v[180:183], v[204:207], v[18:21]
	v_mfma_f32_16x16x32_bf16 v[6:9], v[172:175], v[212:215], v[6:9]
	v_mfma_f32_16x16x32_bf16 v[2:5], v[180:183], v[212:215], v[2:5]
	v_mfma_f32_16x16x32_bf16 v[54:57], v[176:179], v[192:195], v[54:57]
	v_mfma_f32_16x16x32_bf16 v[50:53], v[184:187], v[192:195], v[50:53]
	v_mfma_f32_16x16x32_bf16 v[38:41], v[176:179], v[200:203], v[38:41]
	v_mfma_f32_16x16x32_bf16 v[34:37], v[184:187], v[200:203], v[34:37]
	v_mfma_f32_16x16x32_bf16 v[22:25], v[176:179], v[208:211], v[22:25]
	v_mfma_f32_16x16x32_bf16 v[18:21], v[184:187], v[208:211], v[18:21]
	v_mfma_f32_16x16x32_bf16 v[6:9], v[176:179], v[216:219], v[6:9]
	v_mfma_f32_16x16x32_bf16 v[2:5], v[184:187], v[216:219], v[2:5]
	s_setprio 0
	s_barrier
	s_add_i32 s65, 0, 0x18000
	v_add_u32_e32 v142, s65, v156
	s_add_i32 s66, 0, 0x1c000
	ds_read_b128 v[144:147], v142
	ds_read_b128 v[160:163], v142 offset:1024
	ds_read_b128 v[164:167], v142 offset:2048
	ds_read_b128 v[168:171], v142 offset:3072
	v_add_u32_e32 v142, s66, v156
	ds_read_b128 v[172:175], v142
	ds_read_b128 v[176:179], v142 offset:1024
	ds_read_b128 v[180:183], v142 offset:2048
	ds_read_b128 v[184:187], v142 offset:3072
	s_add_u32 s42, s42, 0x100000
	s_addc_u32 s43, s43, 0
	s_mov_b32 m0, s48
	v_lshl_add_u64 v[226:227], s[42:43], 0, v[130:131]
	ds_read_b128 v[188:191], v153 offset:32768
	ds_read_b128 v[192:195], v153 offset:33792
	ds_read_b128 v[196:199], v153 offset:34816
	ds_read_b128 v[200:203], v153 offset:35840
	ds_read_b128 v[204:207], v153 offset:36864
	ds_read_b128 v[208:211], v153 offset:37888
	ds_read_b128 v[212:215], v153 offset:38912
	ds_read_b128 v[216:219], v153 offset:39936
	global_load_lds_dwordx4 v[226:227], off
	v_lshl_add_u64 v[226:227], s[42:43], 0, v[134:135]
	s_mov_b32 m0, s49
	s_nop 0
	global_load_lds_dwordx4 v[226:227], off
	s_waitcnt vmcnt(8)
	s_waitcnt lgkmcnt(0)
	s_barrier
	s_setprio 1
	v_mfma_f32_16x16x32_bf16 v[126:129], v[144:147], v[188:191], v[126:129]
	v_mfma_f32_16x16x32_bf16 v[122:125], v[164:167], v[188:191], v[122:125]
	v_mfma_f32_16x16x32_bf16 v[110:113], v[144:147], v[196:199], v[110:113]
	v_mfma_f32_16x16x32_bf16 v[106:109], v[164:167], v[196:199], v[106:109]
	v_mfma_f32_16x16x32_bf16 v[94:97], v[144:147], v[204:207], v[94:97]
	v_mfma_f32_16x16x32_bf16 v[90:93], v[164:167], v[204:207], v[90:93]
	v_mfma_f32_16x16x32_bf16 v[78:81], v[144:147], v[212:215], v[78:81]
	v_mfma_f32_16x16x32_bf16 v[74:77], v[164:167], v[212:215], v[74:77]
	v_mfma_f32_16x16x32_bf16 v[126:129], v[160:163], v[192:195], v[126:129]
	v_mfma_f32_16x16x32_bf16 v[122:125], v[168:171], v[192:195], v[122:125]
	v_mfma_f32_16x16x32_bf16 v[110:113], v[160:163], v[200:203], v[110:113]
	v_mfma_f32_16x16x32_bf16 v[106:109], v[168:171], v[200:203], v[106:109]
	v_mfma_f32_16x16x32_bf16 v[94:97], v[160:163], v[208:211], v[94:97]
	v_mfma_f32_16x16x32_bf16 v[90:93], v[168:171], v[208:211], v[90:93]
	v_mfma_f32_16x16x32_bf16 v[78:81], v[160:163], v[216:219], v[78:81]
	v_mfma_f32_16x16x32_bf16 v[74:77], v[168:171], v[216:219], v[74:77]
	v_mfma_f32_16x16x32_bf16 v[118:121], v[172:175], v[188:191], v[118:121]
	v_mfma_f32_16x16x32_bf16 v[114:117], v[180:183], v[188:191], v[114:117]
	v_mfma_f32_16x16x32_bf16 v[102:105], v[172:175], v[196:199], v[102:105]
	v_mfma_f32_16x16x32_bf16 v[98:101], v[180:183], v[196:199], v[98:101]
	v_mfma_f32_16x16x32_bf16 v[86:89], v[172:175], v[204:207], v[86:89]
	v_mfma_f32_16x16x32_bf16 v[82:85], v[180:183], v[204:207], v[82:85]
	v_mfma_f32_16x16x32_bf16 v[70:73], v[172:175], v[212:215], v[70:73]
	v_mfma_f32_16x16x32_bf16 v[66:69], v[180:183], v[212:215], v[66:69]
	v_mfma_f32_16x16x32_bf16 v[118:121], v[176:179], v[192:195], v[118:121]
	v_mfma_f32_16x16x32_bf16 v[114:117], v[184:187], v[192:195], v[114:117]
	v_mfma_f32_16x16x32_bf16 v[102:105], v[176:179], v[200:203], v[102:105]
	v_mfma_f32_16x16x32_bf16 v[98:101], v[184:187], v[200:203], v[98:101]
	v_mfma_f32_16x16x32_bf16 v[86:89], v[176:179], v[208:211], v[86:89]
	v_mfma_f32_16x16x32_bf16 v[82:85], v[184:187], v[208:211], v[82:85]
	v_mfma_f32_16x16x32_bf16 v[70:73], v[176:179], v[216:219], v[70:73]
	v_mfma_f32_16x16x32_bf16 v[66:69], v[184:187], v[216:219], v[66:69]
	s_setprio 0
	s_barrier
	s_add_i32 s42, s65, s46
	v_lshl_add_u64 v[148:149], v[148:149], 0, s[12:13]
	s_mov_b32 m0, s42
	ds_read_b128 v[188:191], v153 offset:49152
	ds_read_b128 v[192:195], v153 offset:50176
	ds_read_b128 v[196:199], v153 offset:51200
	ds_read_b128 v[200:203], v153 offset:52224
	ds_read_b128 v[204:207], v153 offset:53248
	ds_read_b128 v[208:211], v153 offset:54272
	ds_read_b128 v[212:215], v153 offset:55296
	ds_read_b128 v[216:219], v153 offset:56320
	global_load_lds_dwordx4 v[148:149], off
	s_add_i32 m0, s42, 0x2000
	s_add_u32 s40, s40, 0x100080
	v_lshl_add_u64 v[148:149], v[220:221], 0, s[12:13]
	s_addc_u32 s41, s41, 0
	s_add_i32 s42, s66, s46
	global_load_lds_dwordx4 v[148:149], off
	v_lshl_add_u64 v[148:149], s[40:41], 0, v[132:133]
	s_mov_b32 m0, s42
	s_nop 0
	global_load_lds_dwordx4 v[148:149], off
	v_lshl_add_u64 v[148:149], s[40:41], 0, v[136:137]
	s_add_i32 m0, s42, 0x2000
	s_nop 0
	global_load_lds_dwordx4 v[148:149], off
	v_lshl_add_u64 v[148:149], v[222:223], 0, s[12:13]
	s_mov_b32 m0, s54
	s_nop 0
	global_load_lds_dwordx4 v[148:149], off
	v_lshl_add_u64 v[148:149], v[224:225], 0, s[12:13]
	s_mov_b32 m0, s55
	s_nop 0
	global_load_lds_dwordx4 v[148:149], off
	s_waitcnt vmcnt(8)
	s_waitcnt lgkmcnt(0)
	s_barrier
	s_setprio 1
	v_mfma_f32_16x16x32_bf16 v[62:65], v[144:147], v[188:191], v[62:65]
	v_mfma_f32_16x16x32_bf16 v[58:61], v[164:167], v[188:191], v[58:61]
	v_mfma_f32_16x16x32_bf16 v[46:49], v[144:147], v[196:199], v[46:49]
	v_mfma_f32_16x16x32_bf16 v[42:45], v[164:167], v[196:199], v[42:45]
	v_mfma_f32_16x16x32_bf16 v[30:33], v[144:147], v[204:207], v[30:33]
	v_mfma_f32_16x16x32_bf16 v[26:29], v[164:167], v[204:207], v[26:29]
	v_mfma_f32_16x16x32_bf16 v[14:17], v[144:147], v[212:215], v[14:17]
	v_mfma_f32_16x16x32_bf16 v[10:13], v[164:167], v[212:215], v[10:13]
	v_mfma_f32_16x16x32_bf16 v[62:65], v[160:163], v[192:195], v[62:65]
	v_mfma_f32_16x16x32_bf16 v[58:61], v[168:171], v[192:195], v[58:61]
	v_mfma_f32_16x16x32_bf16 v[46:49], v[160:163], v[200:203], v[46:49]
	v_mfma_f32_16x16x32_bf16 v[42:45], v[168:171], v[200:203], v[42:45]
	v_mfma_f32_16x16x32_bf16 v[30:33], v[160:163], v[208:211], v[30:33]
	v_mfma_f32_16x16x32_bf16 v[26:29], v[168:171], v[208:211], v[26:29]
	v_mfma_f32_16x16x32_bf16 v[14:17], v[160:163], v[216:219], v[14:17]
	v_mfma_f32_16x16x32_bf16 v[10:13], v[168:171], v[216:219], v[10:13]
	v_mfma_f32_16x16x32_bf16 v[54:57], v[172:175], v[188:191], v[54:57]
	v_mfma_f32_16x16x32_bf16 v[50:53], v[180:183], v[188:191], v[50:53]
	v_mfma_f32_16x16x32_bf16 v[38:41], v[172:175], v[196:199], v[38:41]
	v_mfma_f32_16x16x32_bf16 v[34:37], v[180:183], v[196:199], v[34:37]
	v_mfma_f32_16x16x32_bf16 v[22:25], v[172:175], v[204:207], v[22:25]
	v_mfma_f32_16x16x32_bf16 v[18:21], v[180:183], v[204:207], v[18:21]
	v_mfma_f32_16x16x32_bf16 v[6:9], v[172:175], v[212:215], v[6:9]
	v_mfma_f32_16x16x32_bf16 v[2:5], v[180:183], v[212:215], v[2:5]
	v_mfma_f32_16x16x32_bf16 v[54:57], v[176:179], v[192:195], v[54:57]
	v_mfma_f32_16x16x32_bf16 v[50:53], v[184:187], v[192:195], v[50:53]
	v_mfma_f32_16x16x32_bf16 v[38:41], v[176:179], v[200:203], v[38:41]
	v_mfma_f32_16x16x32_bf16 v[34:37], v[184:187], v[200:203], v[34:37]
	v_mfma_f32_16x16x32_bf16 v[22:25], v[176:179], v[208:211], v[22:25]
	v_mfma_f32_16x16x32_bf16 v[18:21], v[184:187], v[208:211], v[18:21]
	v_mfma_f32_16x16x32_bf16 v[6:9], v[176:179], v[216:219], v[6:9]
	v_mfma_f32_16x16x32_bf16 v[2:5], v[184:187], v[216:219], v[2:5]
	s_setprio 0
	s_barrier
	s_add_i32 s64, s64, 2
	s_add_u32 s38, s38, 0x100
	s_addc_u32 s39, s39, 0
	s_add_u32 s62, s62, 0x100
	s_addc_u32 s63, s63, 0
	s_cmp_gt_u32 s64, 61
	s_cbranch_scc0 .LBB0_1294
	s_and_b64 vcc, exec, s[14:15]
	s_cbranch_vccz .LBB0_1297
	s_barrier

.LBB0_1386:
	s_add_u32 s47, s38, s46
	s_addc_u32 s52, s39, 0
	s_add_u32 s50, s47, 0x100
	s_addc_u32 s51, s52, 0
	s_and_b64 s[48:49], s[44:45], exec
	s_cselect_b32 s49, s2, s51
	s_cselect_b32 s48, s29, s50
	s_add_u32 s46, s40, s46
	s_addc_u32 s50, s41, 0
	s_add_u32 s46, s46, 0x100
	s_addc_u32 s50, s50, 0
	s_and_b64 s[44:45], s[44:45], exec
	s_cselect_b32 s51, s27, s50
	s_cselect_b32 s50, s70, s46
	s_add_u32 s54, s47, 0x10080
	ds_read_b128 v[152:155], v148
	ds_read_b128 v[156:159], v148 offset:1024
	ds_read_b128 v[160:163], v148 offset:2048
	ds_read_b128 v[164:167], v148 offset:3072
	ds_read_b128 v[168:171], v149
	ds_read_b128 v[172:175], v149 offset:1024
	ds_read_b128 v[176:179], v149 offset:2048
	ds_read_b128 v[180:183], v149 offset:3072
	s_addc_u32 s55, s52, 0
	s_add_i32 s83, s66, s57
	s_add_i32 m0, s37, 0xc000
	s_add_i32 s84, s37, 0xe000
	s_add_i32 s79, s83, 0x2000
	s_add_u32 s52, s50, 0x10000
	s_addc_u32 s53, s51, 0
	s_add_i32 s82, s67, s57
	s_add_i32 s81, s82, 0x2000
	s_add_i32 s78, 0, 0x18000
	s_add_i32 s77, 0, 0x1c000
	s_add_u32 s46, s48, 0x10000
	s_addc_u32 s47, s49, 0
	s_add_i32 s76, s78, s57
	s_add_i32 s72, s76, 0x2000
	s_add_u32 s44, s50, 0x10080
	s_addc_u32 s45, s51, 0
	s_add_i32 s73, s77, s57
	s_add_i32 s71, s73, 0x2000
	v_lshl_add_u64 v[140:141], s[54:55], 0, v[130:131]
	ds_read_b128 v[184:187], v150
	ds_read_b128 v[188:191], v150 offset:1024
	ds_read_b128 v[192:195], v150 offset:2048
	ds_read_b128 v[196:199], v150 offset:3072
	ds_read_b128 v[200:203], v150 offset:4096
	ds_read_b128 v[204:207], v150 offset:5120
	ds_read_b128 v[208:211], v150 offset:6144
	ds_read_b128 v[212:215], v150 offset:7168
	global_load_lds_dwordx4 v[140:141], off
	v_lshl_add_u64 v[140:141], s[54:55], 0, v[134:135]
	s_mov_b32 m0, s84
	s_nop 0
	global_load_lds_dwordx4 v[140:141], off
	s_waitcnt vmcnt(8)
	s_waitcnt lgkmcnt(0)
	s_barrier
	s_setprio 1
	v_mfma_f32_16x16x32_bf16 v[126:129], v[152:155], v[184:187], v[126:129]
	v_mfma_f32_16x16x32_bf16 v[122:125], v[160:163], v[184:187], v[122:125]
	v_mfma_f32_16x16x32_bf16 v[114:117], v[152:155], v[192:195], v[114:117]
	v_mfma_f32_16x16x32_bf16 v[106:109], v[160:163], v[192:195], v[106:109]
	v_mfma_f32_16x16x32_bf16 v[98:101], v[152:155], v[200:203], v[98:101]
	v_mfma_f32_16x16x32_bf16 v[90:93], v[160:163], v[200:203], v[90:93]
	v_mfma_f32_16x16x32_bf16 v[82:85], v[152:155], v[208:211], v[82:85]
	v_mfma_f32_16x16x32_bf16 v[74:77], v[160:163], v[208:211], v[74:77]
	v_mfma_f32_16x16x32_bf16 v[126:129], v[156:159], v[188:191], v[126:129]
	v_mfma_f32_16x16x32_bf16 v[122:125], v[164:167], v[188:191], v[122:125]
	v_mfma_f32_16x16x32_bf16 v[114:117], v[156:159], v[196:199], v[114:117]
	v_mfma_f32_16x16x32_bf16 v[106:109], v[164:167], v[196:199], v[106:109]
	v_mfma_f32_16x16x32_bf16 v[98:101], v[156:159], v[204:207], v[98:101]
	v_mfma_f32_16x16x32_bf16 v[90:93], v[164:167], v[204:207], v[90:93]
	v_mfma_f32_16x16x32_bf16 v[82:85], v[156:159], v[212:215], v[82:85]
	v_mfma_f32_16x16x32_bf16 v[74:77], v[164:167], v[212:215], v[74:77]
	v_mfma_f32_16x16x32_bf16 v[118:121], v[168:171], v[184:187], v[118:121]
	v_mfma_f32_16x16x32_bf16 v[110:113], v[176:179], v[184:187], v[110:113]
	v_mfma_f32_16x16x32_bf16 v[102:105], v[168:171], v[192:195], v[102:105]
	v_mfma_f32_16x16x32_bf16 v[94:97], v[176:179], v[192:195], v[94:97]
	v_mfma_f32_16x16x32_bf16 v[86:89], v[168:171], v[200:203], v[86:89]
	v_mfma_f32_16x16x32_bf16 v[78:81], v[176:179], v[200:203], v[78:81]
	v_mfma_f32_16x16x32_bf16 v[70:73], v[168:171], v[208:211], v[70:73]
	v_mfma_f32_16x16x32_bf16 v[66:69], v[176:179], v[208:211], v[66:69]
	v_mfma_f32_16x16x32_bf16 v[118:121], v[172:175], v[188:191], v[118:121]
	v_mfma_f32_16x16x32_bf16 v[110:113], v[180:183], v[188:191], v[110:113]
	v_mfma_f32_16x16x32_bf16 v[102:105], v[172:175], v[196:199], v[102:105]
	v_mfma_f32_16x16x32_bf16 v[94:97], v[180:183], v[196:199], v[94:97]
	v_mfma_f32_16x16x32_bf16 v[86:89], v[172:175], v[204:207], v[86:89]
	v_mfma_f32_16x16x32_bf16 v[78:81], v[180:183], v[204:207], v[78:81]
	v_mfma_f32_16x16x32_bf16 v[70:73], v[172:175], v[212:215], v[70:73]
	v_mfma_f32_16x16x32_bf16 v[66:69], v[180:183], v[212:215], v[66:69]
	s_setprio 0
	s_barrier
	s_mov_b32 m0, s83
	v_lshl_add_u64 v[140:141], s[50:51], 0, v[132:133]
	ds_read_b128 v[184:187], v150 offset:16384
	ds_read_b128 v[188:191], v150 offset:17408
	ds_read_b128 v[192:195], v150 offset:18432
	ds_read_b128 v[196:199], v150 offset:19456
	ds_read_b128 v[200:203], v150 offset:20480
	ds_read_b128 v[204:207], v150 offset:21504
	ds_read_b128 v[208:211], v150 offset:22528
	ds_read_b128 v[212:215], v150 offset:23552
	global_load_lds_dwordx4 v[140:141], off
	v_lshl_add_u64 v[216:217], s[50:51], 0, v[136:137]
	s_mov_b32 m0, s79
	v_lshl_add_u64 v[218:219], s[52:53], 0, v[132:133]
	global_load_lds_dwordx4 v[216:217], off
	s_mov_b32 m0, s82
	v_lshl_add_u64 v[220:221], s[48:49], 0, v[134:135]
	global_load_lds_dwordx4 v[218:219], off
	v_lshl_add_u64 v[218:219], s[52:53], 0, v[136:137]
	s_mov_b32 m0, s81
	s_nop 0
	global_load_lds_dwordx4 v[218:219], off
	v_lshl_add_u64 v[218:219], s[48:49], 0, v[130:131]
	s_mov_b32 m0, s37
	s_nop 0
	global_load_lds_dwordx4 v[218:219], off
	s_mov_b32 m0, s58
	s_nop 0
	global_load_lds_dwordx4 v[220:221], off
	s_waitcnt vmcnt(8)
	s_waitcnt lgkmcnt(0)
	s_barrier
	s_setprio 1
	v_mfma_f32_16x16x32_bf16 v[62:65], v[152:155], v[184:187], v[62:65]
	v_mfma_f32_16x16x32_bf16 v[58:61], v[160:163], v[184:187], v[58:61]
	v_mfma_f32_16x16x32_bf16 v[50:53], v[152:155], v[192:195], v[50:53]
	v_mfma_f32_16x16x32_bf16 v[42:45], v[160:163], v[192:195], v[42:45]
	v_mfma_f32_16x16x32_bf16 v[34:37], v[152:155], v[200:203], v[34:37]
	v_mfma_f32_16x16x32_bf16 v[26:29], v[160:163], v[200:203], v[26:29]
	v_mfma_f32_16x16x32_bf16 v[18:21], v[152:155], v[208:211], v[18:21]
	v_mfma_f32_16x16x32_bf16 v[10:13], v[160:163], v[208:211], v[10:13]
	v_mfma_f32_16x16x32_bf16 v[62:65], v[156:159], v[188:191], v[62:65]
	v_mfma_f32_16x16x32_bf16 v[58:61], v[164:167], v[188:191], v[58:61]
	v_mfma_f32_16x16x32_bf16 v[50:53], v[156:159], v[196:199], v[50:53]
	v_mfma_f32_16x16x32_bf16 v[42:45], v[164:167], v[196:199], v[42:45]
	v_mfma_f32_16x16x32_bf16 v[34:37], v[156:159], v[204:207], v[34:37]
	v_mfma_f32_16x16x32_bf16 v[26:29], v[164:167], v[204:207], v[26:29]
	v_mfma_f32_16x16x32_bf16 v[18:21], v[156:159], v[212:215], v[18:21]
	v_mfma_f32_16x16x32_bf16 v[10:13], v[164:167], v[212:215], v[10:13]
	v_mfma_f32_16x16x32_bf16 v[54:57], v[168:171], v[184:187], v[54:57]
	v_mfma_f32_16x16x32_bf16 v[46:49], v[176:179], v[184:187], v[46:49]
	v_mfma_f32_16x16x32_bf16 v[38:41], v[168:171], v[192:195], v[38:41]
	v_mfma_f32_16x16x32_bf16 v[30:33], v[176:179], v[192:195], v[30:33]
	v_mfma_f32_16x16x32_bf16 v[22:25], v[168:171], v[200:203], v[22:25]
	v_mfma_f32_16x16x32_bf16 v[14:17], v[176:179], v[200:203], v[14:17]
	v_mfma_f32_16x16x32_bf16 v[6:9], v[168:171], v[208:211], v[6:9]
	v_mfma_f32_16x16x32_bf16 v[2:5], v[176:179], v[208:211], v[2:5]
	v_mfma_f32_16x16x32_bf16 v[54:57], v[172:175], v[188:191], v[54:57]
	v_mfma_f32_16x16x32_bf16 v[46:49], v[180:183], v[188:191], v[46:49]
	v_mfma_f32_16x16x32_bf16 v[38:41], v[172:175], v[196:199], v[38:41]
	v_mfma_f32_16x16x32_bf16 v[30:33], v[180:183], v[196:199], v[30:33]
	v_mfma_f32_16x16x32_bf16 v[22:25], v[172:175], v[204:207], v[22:25]
	v_mfma_f32_16x16x32_bf16 v[14:17], v[180:183], v[204:207], v[14:17]
	v_mfma_f32_16x16x32_bf16 v[6:9], v[172:175], v[212:215], v[6:9]
	v_mfma_f32_16x16x32_bf16 v[2:5], v[180:183], v[212:215], v[2:5]
	s_setprio 0
	s_barrier
	v_add_u32_e32 v138, s78, v146
	ds_read_b128 v[152:155], v138
	ds_read_b128 v[156:159], v138 offset:1024
	ds_read_b128 v[160:163], v138 offset:2048
	ds_read_b128 v[164:167], v138 offset:3072
	v_add_u32_e32 v138, s77, v146
	ds_read_b128 v[168:171], v138
	ds_read_b128 v[172:175], v138 offset:1024
	ds_read_b128 v[176:179], v138 offset:2048
	ds_read_b128 v[180:183], v138 offset:3072
	s_mov_b32 m0, s59
	v_lshl_add_u64 v[222:223], s[46:47], 0, v[130:131]
	ds_read_b128 v[184:187], v150 offset:32768
	ds_read_b128 v[188:191], v150 offset:33792
	ds_read_b128 v[192:195], v150 offset:34816
	ds_read_b128 v[196:199], v150 offset:35840
	ds_read_b128 v[200:203], v150 offset:36864
	ds_read_b128 v[204:207], v150 offset:37888
	ds_read_b128 v[208:211], v150 offset:38912
	ds_read_b128 v[212:215], v150 offset:39936
	global_load_lds_dwordx4 v[222:223], off
	v_lshl_add_u64 v[222:223], s[46:47], 0, v[134:135]
	s_mov_b32 m0, s60
	s_nop 0
	global_load_lds_dwordx4 v[222:223], off
	s_waitcnt vmcnt(8)
	s_waitcnt lgkmcnt(0)
	s_barrier
	s_setprio 1
	v_mfma_f32_16x16x32_bf16 v[126:129], v[152:155], v[184:187], v[126:129]
	v_mfma_f32_16x16x32_bf16 v[122:125], v[160:163], v[184:187], v[122:125]
	v_mfma_f32_16x16x32_bf16 v[114:117], v[152:155], v[192:195], v[114:117]
	v_mfma_f32_16x16x32_bf16 v[106:109], v[160:163], v[192:195], v[106:109]
	v_mfma_f32_16x16x32_bf16 v[98:101], v[152:155], v[200:203], v[98:101]
	v_mfma_f32_16x16x32_bf16 v[90:93], v[160:163], v[200:203], v[90:93]
	v_mfma_f32_16x16x32_bf16 v[82:85], v[152:155], v[208:211], v[82:85]
	v_mfma_f32_16x16x32_bf16 v[74:77], v[160:163], v[208:211], v[74:77]
	v_mfma_f32_16x16x32_bf16 v[126:129], v[156:159], v[188:191], v[126:129]
	v_mfma_f32_16x16x32_bf16 v[122:125], v[164:167], v[188:191], v[122:125]
	v_mfma_f32_16x16x32_bf16 v[114:117], v[156:159], v[196:199], v[114:117]
	v_mfma_f32_16x16x32_bf16 v[106:109], v[164:167], v[196:199], v[106:109]
	v_mfma_f32_16x16x32_bf16 v[98:101], v[156:159], v[204:207], v[98:101]
	v_mfma_f32_16x16x32_bf16 v[90:93], v[164:167], v[204:207], v[90:93]
	v_mfma_f32_16x16x32_bf16 v[82:85], v[156:159], v[212:215], v[82:85]
	v_mfma_f32_16x16x32_bf16 v[74:77], v[164:167], v[212:215], v[74:77]
	v_mfma_f32_16x16x32_bf16 v[118:121], v[168:171], v[184:187], v[118:121]
	v_mfma_f32_16x16x32_bf16 v[110:113], v[176:179], v[184:187], v[110:113]
	v_mfma_f32_16x16x32_bf16 v[102:105], v[168:171], v[192:195], v[102:105]
	v_mfma_f32_16x16x32_bf16 v[94:97], v[176:179], v[192:195], v[94:97]
	v_mfma_f32_16x16x32_bf16 v[86:89], v[168:171], v[200:203], v[86:89]
	v_mfma_f32_16x16x32_bf16 v[78:81], v[176:179], v[200:203], v[78:81]
	v_mfma_f32_16x16x32_bf16 v[70:73], v[168:171], v[208:211], v[70:73]
	v_mfma_f32_16x16x32_bf16 v[66:69], v[176:179], v[208:211], v[66:69]
	v_mfma_f32_16x16x32_bf16 v[118:121], v[172:175], v[188:191], v[118:121]
	v_mfma_f32_16x16x32_bf16 v[110:113], v[180:183], v[188:191], v[110:113]
	v_mfma_f32_16x16x32_bf16 v[102:105], v[172:175], v[196:199], v[102:105]
	v_mfma_f32_16x16x32_bf16 v[94:97], v[180:183], v[196:199], v[94:97]
	v_mfma_f32_16x16x32_bf16 v[86:89], v[172:175], v[204:207], v[86:89]
	v_mfma_f32_16x16x32_bf16 v[78:81], v[180:183], v[204:207], v[78:81]
	v_mfma_f32_16x16x32_bf16 v[70:73], v[172:175], v[212:215], v[70:73]
	v_mfma_f32_16x16x32_bf16 v[66:69], v[180:183], v[212:215], v[66:69]
	s_setprio 0
	s_barrier
	s_mov_b32 m0, s76
	v_lshl_add_u64 v[140:141], v[140:141], 0, s[14:15]
	ds_read_b128 v[184:187], v150 offset:49152
	ds_read_b128 v[188:191], v150 offset:50176
	ds_read_b128 v[192:195], v150 offset:51200
	ds_read_b128 v[196:199], v150 offset:52224
	ds_read_b128 v[200:203], v150 offset:53248
	ds_read_b128 v[204:207], v150 offset:54272
	ds_read_b128 v[208:211], v150 offset:55296
	ds_read_b128 v[212:215], v150 offset:56320
	global_load_lds_dwordx4 v[140:141], off
	v_lshl_add_u64 v[140:141], v[216:217], 0, s[14:15]
	s_mov_b32 m0, s72
	s_nop 0
	global_load_lds_dwordx4 v[140:141], off
	v_lshl_add_u64 v[140:141], s[44:45], 0, v[132:133]
	s_mov_b32 m0, s73
	s_nop 0
	global_load_lds_dwordx4 v[140:141], off
	v_lshl_add_u64 v[140:141], s[44:45], 0, v[136:137]
	s_mov_b32 m0, s71
	s_nop 0
	global_load_lds_dwordx4 v[140:141], off
	v_lshl_add_u64 v[140:141], v[218:219], 0, s[14:15]
	s_mov_b32 m0, s63
	s_nop 0
	global_load_lds_dwordx4 v[140:141], off
	v_lshl_add_u64 v[140:141], v[220:221], 0, s[14:15]
	s_mov_b32 m0, s64
	s_nop 0
	global_load_lds_dwordx4 v[140:141], off
	s_waitcnt vmcnt(8)
	s_waitcnt lgkmcnt(0)
	s_barrier
	s_setprio 1
	v_mfma_f32_16x16x32_bf16 v[62:65], v[152:155], v[184:187], v[62:65]
	v_mfma_f32_16x16x32_bf16 v[58:61], v[160:163], v[184:187], v[58:61]
	v_mfma_f32_16x16x32_bf16 v[50:53], v[152:155], v[192:195], v[50:53]
	v_mfma_f32_16x16x32_bf16 v[42:45], v[160:163], v[192:195], v[42:45]
	v_mfma_f32_16x16x32_bf16 v[34:37], v[152:155], v[200:203], v[34:37]
	v_mfma_f32_16x16x32_bf16 v[26:29], v[160:163], v[200:203], v[26:29]
	v_mfma_f32_16x16x32_bf16 v[18:21], v[152:155], v[208:211], v[18:21]
	v_mfma_f32_16x16x32_bf16 v[10:13], v[160:163], v[208:211], v[10:13]
	v_mfma_f32_16x16x32_bf16 v[62:65], v[156:159], v[188:191], v[62:65]
	v_mfma_f32_16x16x32_bf16 v[58:61], v[164:167], v[188:191], v[58:61]
	v_mfma_f32_16x16x32_bf16 v[50:53], v[156:159], v[196:199], v[50:53]
	v_mfma_f32_16x16x32_bf16 v[42:45], v[164:167], v[196:199], v[42:45]
	v_mfma_f32_16x16x32_bf16 v[34:37], v[156:159], v[204:207], v[34:37]
	v_mfma_f32_16x16x32_bf16 v[26:29], v[164:167], v[204:207], v[26:29]
	v_mfma_f32_16x16x32_bf16 v[18:21], v[156:159], v[212:215], v[18:21]
	v_mfma_f32_16x16x32_bf16 v[10:13], v[164:167], v[212:215], v[10:13]
	v_mfma_f32_16x16x32_bf16 v[54:57], v[168:171], v[184:187], v[54:57]
	v_mfma_f32_16x16x32_bf16 v[46:49], v[176:179], v[184:187], v[46:49]
	v_mfma_f32_16x16x32_bf16 v[38:41], v[168:171], v[192:195], v[38:41]
	v_mfma_f32_16x16x32_bf16 v[30:33], v[176:179], v[192:195], v[30:33]
	v_mfma_f32_16x16x32_bf16 v[22:25], v[168:171], v[200:203], v[22:25]
	v_mfma_f32_16x16x32_bf16 v[14:17], v[176:179], v[200:203], v[14:17]
	v_mfma_f32_16x16x32_bf16 v[6:9], v[168:171], v[208:211], v[6:9]
	v_mfma_f32_16x16x32_bf16 v[2:5], v[176:179], v[208:211], v[2:5]
	v_mfma_f32_16x16x32_bf16 v[54:57], v[172:175], v[188:191], v[54:57]
	v_mfma_f32_16x16x32_bf16 v[46:49], v[180:183], v[188:191], v[46:49]
	v_mfma_f32_16x16x32_bf16 v[38:41], v[172:175], v[196:199], v[38:41]
	v_mfma_f32_16x16x32_bf16 v[30:33], v[180:183], v[196:199], v[30:33]
	v_mfma_f32_16x16x32_bf16 v[22:25], v[172:175], v[204:207], v[22:25]
	v_mfma_f32_16x16x32_bf16 v[14:17], v[180:183], v[204:207], v[14:17]
	v_mfma_f32_16x16x32_bf16 v[6:9], v[172:175], v[212:215], v[6:9]
	v_mfma_f32_16x16x32_bf16 v[2:5], v[180:183], v[212:215], v[2:5]
	s_setprio 0
	s_barrier
	s_movk_i32 s46, 0x100
	s_andn2_b64 vcc, exec, s[42:43]
	s_mov_b64 s[44:45], -1
	s_mov_b64 s[42:43], 0
	s_cbranch_vccz .LBB0_1386
	s_and_b64 vcc, exec, s[16:17]
	s_cbranch_vccz .LBB0_1389
	s_barrier

.LBB0_1410:
	s_add_u32 s47, s38, s46
	s_addc_u32 s52, s39, 0
	s_add_u32 s50, s47, 0x100
	s_addc_u32 s51, s52, 0
	s_and_b64 s[48:49], s[44:45], exec
	s_cselect_b32 s49, s2, s51
	s_cselect_b32 s48, s29, s50
	s_add_u32 s46, s40, s46
	s_addc_u32 s50, s41, 0
	s_add_u32 s46, s46, 0x100
	s_addc_u32 s50, s50, 0
	s_and_b64 s[44:45], s[44:45], exec
	s_cselect_b32 s51, s27, s50
	s_cselect_b32 s50, s70, s46
	s_add_u32 s54, s47, 0x10080
	ds_read_b128 v[148:151], v143
	ds_read_b128 v[152:155], v143 offset:1024
	ds_read_b128 v[156:159], v143 offset:2048
	ds_read_b128 v[160:163], v143 offset:3072
	ds_read_b128 v[164:167], v144
	ds_read_b128 v[168:171], v144 offset:1024
	ds_read_b128 v[172:175], v144 offset:2048
	ds_read_b128 v[176:179], v144 offset:3072
	s_addc_u32 s55, s52, 0
	s_add_i32 s83, s66, s58
	s_add_i32 m0, s37, 0xc000
	s_add_i32 s84, s37, 0xe000
	s_add_i32 s79, s83, 0x2000
	s_add_u32 s52, s50, 0x10000
	s_addc_u32 s53, s51, 0
	s_add_i32 s82, s67, s58
	s_add_i32 s81, s82, 0x2000
	s_add_i32 s78, 0, 0x18000
	s_add_i32 s77, 0, 0x1c000
	s_add_u32 s46, s48, 0x10000
	s_addc_u32 s47, s49, 0
	s_add_i32 s76, s78, s58
	s_add_i32 s72, s76, 0x2000
	s_add_u32 s44, s50, 0x10080
	s_addc_u32 s45, s51, 0
	s_add_i32 s73, s77, s58
	s_add_i32 s71, s73, 0x2000
	v_lshl_add_u64 v[140:141], s[54:55], 0, v[130:131]
	ds_read_b128 v[180:183], v146
	ds_read_b128 v[184:187], v146 offset:1024
	ds_read_b128 v[188:191], v146 offset:2048
	ds_read_b128 v[192:195], v146 offset:3072
	ds_read_b128 v[196:199], v146 offset:4096
	ds_read_b128 v[200:203], v146 offset:5120
	ds_read_b128 v[204:207], v146 offset:6144
	ds_read_b128 v[208:211], v146 offset:7168
	global_load_lds_dwordx4 v[140:141], off
	v_lshl_add_u64 v[140:141], s[54:55], 0, v[134:135]
	s_mov_b32 m0, s84
	s_nop 0
	global_load_lds_dwordx4 v[140:141], off
	s_waitcnt vmcnt(8)
	s_waitcnt lgkmcnt(0)
	s_barrier
	s_setprio 1
	v_mfma_f32_16x16x32_bf16 v[126:129], v[148:151], v[180:183], v[126:129]
	v_mfma_f32_16x16x32_bf16 v[122:125], v[156:159], v[180:183], v[122:125]
	v_mfma_f32_16x16x32_bf16 v[114:117], v[148:151], v[188:191], v[114:117]
	v_mfma_f32_16x16x32_bf16 v[106:109], v[156:159], v[188:191], v[106:109]
	v_mfma_f32_16x16x32_bf16 v[98:101], v[148:151], v[196:199], v[98:101]
	v_mfma_f32_16x16x32_bf16 v[90:93], v[156:159], v[196:199], v[90:93]
	v_mfma_f32_16x16x32_bf16 v[82:85], v[148:151], v[204:207], v[82:85]
	v_mfma_f32_16x16x32_bf16 v[74:77], v[156:159], v[204:207], v[74:77]
	v_mfma_f32_16x16x32_bf16 v[126:129], v[152:155], v[184:187], v[126:129]
	v_mfma_f32_16x16x32_bf16 v[122:125], v[160:163], v[184:187], v[122:125]
	v_mfma_f32_16x16x32_bf16 v[114:117], v[152:155], v[192:195], v[114:117]
	v_mfma_f32_16x16x32_bf16 v[106:109], v[160:163], v[192:195], v[106:109]
	v_mfma_f32_16x16x32_bf16 v[98:101], v[152:155], v[200:203], v[98:101]
	v_mfma_f32_16x16x32_bf16 v[90:93], v[160:163], v[200:203], v[90:93]
	v_mfma_f32_16x16x32_bf16 v[82:85], v[152:155], v[208:211], v[82:85]
	v_mfma_f32_16x16x32_bf16 v[74:77], v[160:163], v[208:211], v[74:77]
	v_mfma_f32_16x16x32_bf16 v[118:121], v[164:167], v[180:183], v[118:121]
	v_mfma_f32_16x16x32_bf16 v[110:113], v[172:175], v[180:183], v[110:113]
	v_mfma_f32_16x16x32_bf16 v[102:105], v[164:167], v[188:191], v[102:105]
	v_mfma_f32_16x16x32_bf16 v[94:97], v[172:175], v[188:191], v[94:97]
	v_mfma_f32_16x16x32_bf16 v[86:89], v[164:167], v[196:199], v[86:89]
	v_mfma_f32_16x16x32_bf16 v[78:81], v[172:175], v[196:199], v[78:81]
	v_mfma_f32_16x16x32_bf16 v[70:73], v[164:167], v[204:207], v[70:73]
	v_mfma_f32_16x16x32_bf16 v[66:69], v[172:175], v[204:207], v[66:69]
	v_mfma_f32_16x16x32_bf16 v[118:121], v[168:171], v[184:187], v[118:121]
	v_mfma_f32_16x16x32_bf16 v[110:113], v[176:179], v[184:187], v[110:113]
	v_mfma_f32_16x16x32_bf16 v[102:105], v[168:171], v[192:195], v[102:105]
	v_mfma_f32_16x16x32_bf16 v[94:97], v[176:179], v[192:195], v[94:97]
	v_mfma_f32_16x16x32_bf16 v[86:89], v[168:171], v[200:203], v[86:89]
	v_mfma_f32_16x16x32_bf16 v[78:81], v[176:179], v[200:203], v[78:81]
	v_mfma_f32_16x16x32_bf16 v[70:73], v[168:171], v[208:211], v[70:73]
	v_mfma_f32_16x16x32_bf16 v[66:69], v[176:179], v[208:211], v[66:69]
	s_setprio 0
	s_barrier
	s_mov_b32 m0, s83
	v_lshl_add_u64 v[140:141], s[50:51], 0, v[132:133]
	ds_read_b128 v[180:183], v146 offset:16384
	ds_read_b128 v[184:187], v146 offset:17408
	ds_read_b128 v[188:191], v146 offset:18432
	ds_read_b128 v[192:195], v146 offset:19456
	ds_read_b128 v[196:199], v146 offset:20480
	ds_read_b128 v[200:203], v146 offset:21504
	ds_read_b128 v[204:207], v146 offset:22528
	ds_read_b128 v[208:211], v146 offset:23552
	global_load_lds_dwordx4 v[140:141], off
	v_lshl_add_u64 v[212:213], s[50:51], 0, v[136:137]
	s_mov_b32 m0, s79
	v_lshl_add_u64 v[214:215], s[52:53], 0, v[132:133]
	global_load_lds_dwordx4 v[212:213], off
	s_mov_b32 m0, s82
	v_lshl_add_u64 v[216:217], s[48:49], 0, v[134:135]
	global_load_lds_dwordx4 v[214:215], off
	v_lshl_add_u64 v[214:215], s[52:53], 0, v[136:137]
	s_mov_b32 m0, s81
	s_nop 0
	global_load_lds_dwordx4 v[214:215], off
	v_lshl_add_u64 v[214:215], s[48:49], 0, v[130:131]
	s_mov_b32 m0, s37
	s_nop 0
	global_load_lds_dwordx4 v[214:215], off
	s_mov_b32 m0, s59
	s_nop 0
	global_load_lds_dwordx4 v[216:217], off
	s_waitcnt vmcnt(8)
	s_waitcnt lgkmcnt(0)
	s_barrier
	s_setprio 1
	v_mfma_f32_16x16x32_bf16 v[62:65], v[148:151], v[180:183], v[62:65]
	v_mfma_f32_16x16x32_bf16 v[58:61], v[156:159], v[180:183], v[58:61]
	v_mfma_f32_16x16x32_bf16 v[50:53], v[148:151], v[188:191], v[50:53]
	v_mfma_f32_16x16x32_bf16 v[42:45], v[156:159], v[188:191], v[42:45]
	v_mfma_f32_16x16x32_bf16 v[34:37], v[148:151], v[196:199], v[34:37]
	v_mfma_f32_16x16x32_bf16 v[26:29], v[156:159], v[196:199], v[26:29]
	v_mfma_f32_16x16x32_bf16 v[18:21], v[148:151], v[204:207], v[18:21]
	v_mfma_f32_16x16x32_bf16 v[10:13], v[156:159], v[204:207], v[10:13]
	v_mfma_f32_16x16x32_bf16 v[62:65], v[152:155], v[184:187], v[62:65]
	v_mfma_f32_16x16x32_bf16 v[58:61], v[160:163], v[184:187], v[58:61]
	v_mfma_f32_16x16x32_bf16 v[50:53], v[152:155], v[192:195], v[50:53]
	v_mfma_f32_16x16x32_bf16 v[42:45], v[160:163], v[192:195], v[42:45]
	v_mfma_f32_16x16x32_bf16 v[34:37], v[152:155], v[200:203], v[34:37]
	v_mfma_f32_16x16x32_bf16 v[26:29], v[160:163], v[200:203], v[26:29]
	v_mfma_f32_16x16x32_bf16 v[18:21], v[152:155], v[208:211], v[18:21]
	v_mfma_f32_16x16x32_bf16 v[10:13], v[160:163], v[208:211], v[10:13]
	v_mfma_f32_16x16x32_bf16 v[54:57], v[164:167], v[180:183], v[54:57]
	v_mfma_f32_16x16x32_bf16 v[46:49], v[172:175], v[180:183], v[46:49]
	v_mfma_f32_16x16x32_bf16 v[38:41], v[164:167], v[188:191], v[38:41]
	v_mfma_f32_16x16x32_bf16 v[30:33], v[172:175], v[188:191], v[30:33]
	v_mfma_f32_16x16x32_bf16 v[22:25], v[164:167], v[196:199], v[22:25]
	v_mfma_f32_16x16x32_bf16 v[14:17], v[172:175], v[196:199], v[14:17]
	v_mfma_f32_16x16x32_bf16 v[6:9], v[164:167], v[204:207], v[6:9]
	v_mfma_f32_16x16x32_bf16 v[2:5], v[172:175], v[204:207], v[2:5]
	v_mfma_f32_16x16x32_bf16 v[54:57], v[168:171], v[184:187], v[54:57]
	v_mfma_f32_16x16x32_bf16 v[46:49], v[176:179], v[184:187], v[46:49]
	v_mfma_f32_16x16x32_bf16 v[38:41], v[168:171], v[192:195], v[38:41]
	v_mfma_f32_16x16x32_bf16 v[30:33], v[176:179], v[192:195], v[30:33]
	v_mfma_f32_16x16x32_bf16 v[22:25], v[168:171], v[200:203], v[22:25]
	v_mfma_f32_16x16x32_bf16 v[14:17], v[176:179], v[200:203], v[14:17]
	v_mfma_f32_16x16x32_bf16 v[6:9], v[168:171], v[208:211], v[6:9]
	v_mfma_f32_16x16x32_bf16 v[2:5], v[176:179], v[208:211], v[2:5]
	s_setprio 0
	s_barrier
	v_add_u32_e32 v138, s78, v142
	ds_read_b128 v[148:151], v138
	ds_read_b128 v[152:155], v138 offset:1024
	ds_read_b128 v[156:159], v138 offset:2048
	ds_read_b128 v[160:163], v138 offset:3072
	v_add_u32_e32 v138, s77, v142
	ds_read_b128 v[164:167], v138
	ds_read_b128 v[168:171], v138 offset:1024
	ds_read_b128 v[172:175], v138 offset:2048
	ds_read_b128 v[176:179], v138 offset:3072
	s_mov_b32 m0, s60
	v_lshl_add_u64 v[218:219], s[46:47], 0, v[130:131]
	ds_read_b128 v[180:183], v146 offset:32768
	ds_read_b128 v[184:187], v146 offset:33792
	ds_read_b128 v[188:191], v146 offset:34816
	ds_read_b128 v[192:195], v146 offset:35840
	ds_read_b128 v[196:199], v146 offset:36864
	ds_read_b128 v[200:203], v146 offset:37888
	ds_read_b128 v[204:207], v146 offset:38912
	ds_read_b128 v[208:211], v146 offset:39936
	global_load_lds_dwordx4 v[218:219], off
	v_lshl_add_u64 v[218:219], s[46:47], 0, v[134:135]
	s_mov_b32 m0, s61
	s_nop 0
	global_load_lds_dwordx4 v[218:219], off
	s_waitcnt vmcnt(8)
	s_waitcnt lgkmcnt(0)
	s_barrier
	s_setprio 1
	v_mfma_f32_16x16x32_bf16 v[126:129], v[148:151], v[180:183], v[126:129]
	v_mfma_f32_16x16x32_bf16 v[122:125], v[156:159], v[180:183], v[122:125]
	v_mfma_f32_16x16x32_bf16 v[114:117], v[148:151], v[188:191], v[114:117]
	v_mfma_f32_16x16x32_bf16 v[106:109], v[156:159], v[188:191], v[106:109]
	v_mfma_f32_16x16x32_bf16 v[98:101], v[148:151], v[196:199], v[98:101]
	v_mfma_f32_16x16x32_bf16 v[90:93], v[156:159], v[196:199], v[90:93]
	v_mfma_f32_16x16x32_bf16 v[82:85], v[148:151], v[204:207], v[82:85]
	v_mfma_f32_16x16x32_bf16 v[74:77], v[156:159], v[204:207], v[74:77]
	v_mfma_f32_16x16x32_bf16 v[126:129], v[152:155], v[184:187], v[126:129]
	v_mfma_f32_16x16x32_bf16 v[122:125], v[160:163], v[184:187], v[122:125]
	v_mfma_f32_16x16x32_bf16 v[114:117], v[152:155], v[192:195], v[114:117]
	v_mfma_f32_16x16x32_bf16 v[106:109], v[160:163], v[192:195], v[106:109]
	v_mfma_f32_16x16x32_bf16 v[98:101], v[152:155], v[200:203], v[98:101]
	v_mfma_f32_16x16x32_bf16 v[90:93], v[160:163], v[200:203], v[90:93]
	v_mfma_f32_16x16x32_bf16 v[82:85], v[152:155], v[208:211], v[82:85]
	v_mfma_f32_16x16x32_bf16 v[74:77], v[160:163], v[208:211], v[74:77]
	v_mfma_f32_16x16x32_bf16 v[118:121], v[164:167], v[180:183], v[118:121]
	v_mfma_f32_16x16x32_bf16 v[110:113], v[172:175], v[180:183], v[110:113]
	v_mfma_f32_16x16x32_bf16 v[102:105], v[164:167], v[188:191], v[102:105]
	v_mfma_f32_16x16x32_bf16 v[94:97], v[172:175], v[188:191], v[94:97]
	v_mfma_f32_16x16x32_bf16 v[86:89], v[164:167], v[196:199], v[86:89]
	v_mfma_f32_16x16x32_bf16 v[78:81], v[172:175], v[196:199], v[78:81]
	v_mfma_f32_16x16x32_bf16 v[70:73], v[164:167], v[204:207], v[70:73]
	v_mfma_f32_16x16x32_bf16 v[66:69], v[172:175], v[204:207], v[66:69]
	v_mfma_f32_16x16x32_bf16 v[118:121], v[168:171], v[184:187], v[118:121]
	v_mfma_f32_16x16x32_bf16 v[110:113], v[176:179], v[184:187], v[110:113]
	v_mfma_f32_16x16x32_bf16 v[102:105], v[168:171], v[192:195], v[102:105]
	v_mfma_f32_16x16x32_bf16 v[94:97], v[176:179], v[192:195], v[94:97]
	v_mfma_f32_16x16x32_bf16 v[86:89], v[168:171], v[200:203], v[86:89]
	v_mfma_f32_16x16x32_bf16 v[78:81], v[176:179], v[200:203], v[78:81]
	v_mfma_f32_16x16x32_bf16 v[70:73], v[168:171], v[208:211], v[70:73]
	v_mfma_f32_16x16x32_bf16 v[66:69], v[176:179], v[208:211], v[66:69]
	s_setprio 0
	s_barrier
	s_mov_b32 m0, s76
	v_lshl_add_u64 v[140:141], v[140:141], 0, s[14:15]
	ds_read_b128 v[180:183], v146 offset:49152
	ds_read_b128 v[184:187], v146 offset:50176
	ds_read_b128 v[188:191], v146 offset:51200
	ds_read_b128 v[192:195], v146 offset:52224
	ds_read_b128 v[196:199], v146 offset:53248
	ds_read_b128 v[200:203], v146 offset:54272
	ds_read_b128 v[204:207], v146 offset:55296
	ds_read_b128 v[208:211], v146 offset:56320
	global_load_lds_dwordx4 v[140:141], off
	v_lshl_add_u64 v[140:141], v[212:213], 0, s[14:15]
	s_mov_b32 m0, s72
	s_nop 0
	global_load_lds_dwordx4 v[140:141], off
	v_lshl_add_u64 v[140:141], s[44:45], 0, v[132:133]
	s_mov_b32 m0, s73
	s_nop 0
	global_load_lds_dwordx4 v[140:141], off
	v_lshl_add_u64 v[140:141], s[44:45], 0, v[136:137]
	s_mov_b32 m0, s71
	s_nop 0
	global_load_lds_dwordx4 v[140:141], off
	v_lshl_add_u64 v[140:141], v[214:215], 0, s[14:15]
	s_mov_b32 m0, s63
	s_nop 0
	global_load_lds_dwordx4 v[140:141], off
	v_lshl_add_u64 v[140:141], v[216:217], 0, s[14:15]
	s_mov_b32 m0, s64
	s_nop 0
	global_load_lds_dwordx4 v[140:141], off
	s_waitcnt vmcnt(8)
	s_waitcnt lgkmcnt(0)
	s_barrier
	s_setprio 1
	v_mfma_f32_16x16x32_bf16 v[62:65], v[148:151], v[180:183], v[62:65]
	v_mfma_f32_16x16x32_bf16 v[58:61], v[156:159], v[180:183], v[58:61]
	v_mfma_f32_16x16x32_bf16 v[50:53], v[148:151], v[188:191], v[50:53]
	v_mfma_f32_16x16x32_bf16 v[42:45], v[156:159], v[188:191], v[42:45]
	v_mfma_f32_16x16x32_bf16 v[34:37], v[148:151], v[196:199], v[34:37]
	v_mfma_f32_16x16x32_bf16 v[26:29], v[156:159], v[196:199], v[26:29]
	v_mfma_f32_16x16x32_bf16 v[18:21], v[148:151], v[204:207], v[18:21]
	v_mfma_f32_16x16x32_bf16 v[10:13], v[156:159], v[204:207], v[10:13]
	v_mfma_f32_16x16x32_bf16 v[62:65], v[152:155], v[184:187], v[62:65]
	v_mfma_f32_16x16x32_bf16 v[58:61], v[160:163], v[184:187], v[58:61]
	v_mfma_f32_16x16x32_bf16 v[50:53], v[152:155], v[192:195], v[50:53]
	v_mfma_f32_16x16x32_bf16 v[42:45], v[160:163], v[192:195], v[42:45]
	v_mfma_f32_16x16x32_bf16 v[34:37], v[152:155], v[200:203], v[34:37]
	v_mfma_f32_16x16x32_bf16 v[26:29], v[160:163], v[200:203], v[26:29]
	v_mfma_f32_16x16x32_bf16 v[18:21], v[152:155], v[208:211], v[18:21]
	v_mfma_f32_16x16x32_bf16 v[10:13], v[160:163], v[208:211], v[10:13]
	v_mfma_f32_16x16x32_bf16 v[54:57], v[164:167], v[180:183], v[54:57]
	v_mfma_f32_16x16x32_bf16 v[46:49], v[172:175], v[180:183], v[46:49]
	v_mfma_f32_16x16x32_bf16 v[38:41], v[164:167], v[188:191], v[38:41]
	v_mfma_f32_16x16x32_bf16 v[30:33], v[172:175], v[188:191], v[30:33]
	v_mfma_f32_16x16x32_bf16 v[22:25], v[164:167], v[196:199], v[22:25]
	v_mfma_f32_16x16x32_bf16 v[14:17], v[172:175], v[196:199], v[14:17]
	v_mfma_f32_16x16x32_bf16 v[6:9], v[164:167], v[204:207], v[6:9]
	v_mfma_f32_16x16x32_bf16 v[2:5], v[172:175], v[204:207], v[2:5]
	v_mfma_f32_16x16x32_bf16 v[54:57], v[168:171], v[184:187], v[54:57]
	v_mfma_f32_16x16x32_bf16 v[46:49], v[176:179], v[184:187], v[46:49]
	v_mfma_f32_16x16x32_bf16 v[38:41], v[168:171], v[192:195], v[38:41]
	v_mfma_f32_16x16x32_bf16 v[30:33], v[176:179], v[192:195], v[30:33]
	v_mfma_f32_16x16x32_bf16 v[22:25], v[168:171], v[200:203], v[22:25]
	v_mfma_f32_16x16x32_bf16 v[14:17], v[176:179], v[200:203], v[14:17]
	v_mfma_f32_16x16x32_bf16 v[6:9], v[168:171], v[208:211], v[6:9]
	v_mfma_f32_16x16x32_bf16 v[2:5], v[176:179], v[208:211], v[2:5]
	s_setprio 0
	s_barrier
	s_movk_i32 s46, 0x100
	s_andn2_b64 vcc, exec, s[42:43]
	s_mov_b64 s[44:45], -1
	s_mov_b64 s[42:43], 0
	s_cbranch_vccz .LBB0_1410
	s_and_b64 vcc, exec, s[16:17]
	s_cbranch_vccz .LBB0_1413
	s_barrier

.LBB0_2142:
	ds_read_b128 v[130:133], v199
	ds_read_b128 v[134:137], v199 offset:1024
	ds_read_b128 v[138:141], v199 offset:2048
	ds_read_b128 v[142:145], v199 offset:3072
	ds_read_b128 v[146:149], v200
	ds_read_b128 v[166:169], v200 offset:1024
	ds_read_b128 v[170:173], v200 offset:2048
	ds_read_b128 v[174:177], v200 offset:3072
	s_add_u32 s34, s30, 0xfff00080
	s_addc_u32 s35, s31, -1
	s_cmp_eq_u32 s52, 60
	s_cselect_b32 s37, s23, s35
	s_cselect_b32 s36, s48, s34
	s_cselect_b32 s35, s21, s51
	s_cselect_b32 s34, s49, s50
	v_lshl_add_u64 v[194:195], s[30:31], 0, v[158:159]
	s_add_i32 m0, s29, 0xc000
	ds_read_b128 v[178:181], v201
	ds_read_b128 v[182:185], v201 offset:1024
	ds_read_b128 v[186:189], v201 offset:2048
	ds_read_b128 v[190:193], v201 offset:3072
	ds_read_b128 v[202:205], v201 offset:4096
	ds_read_b128 v[206:209], v201 offset:5120
	ds_read_b128 v[210:213], v201 offset:6144
	ds_read_b128 v[214:217], v201 offset:7168
	global_load_lds_dwordx4 v[194:195], off
	v_lshl_add_u64 v[194:195], s[30:31], 0, v[160:161]
	s_add_i32 m0, s29, 0xe000
	s_nop 0
	global_load_lds_dwordx4 v[194:195], off
	s_waitcnt vmcnt(8)
	s_waitcnt lgkmcnt(0)
	s_barrier
	s_setprio 1
	v_mfma_f32_16x16x32_bf16 v[126:129], v[130:133], v[178:181], v[126:129]
	v_mfma_f32_16x16x32_bf16 v[122:125], v[138:141], v[178:181], v[122:125]
	v_mfma_f32_16x16x32_bf16 v[118:121], v[130:133], v[186:189], v[118:121]
	v_mfma_f32_16x16x32_bf16 v[114:117], v[138:141], v[186:189], v[114:117]
	v_mfma_f32_16x16x32_bf16 v[110:113], v[130:133], v[202:205], v[110:113]
	v_mfma_f32_16x16x32_bf16 v[106:109], v[138:141], v[202:205], v[106:109]
	v_mfma_f32_16x16x32_bf16 v[102:105], v[130:133], v[210:213], v[102:105]
	v_mfma_f32_16x16x32_bf16 v[98:101], v[138:141], v[210:213], v[98:101]
	v_mfma_f32_16x16x32_bf16 v[126:129], v[134:137], v[182:185], v[126:129]
	v_mfma_f32_16x16x32_bf16 v[122:125], v[142:145], v[182:185], v[122:125]
	v_mfma_f32_16x16x32_bf16 v[118:121], v[134:137], v[190:193], v[118:121]
	v_mfma_f32_16x16x32_bf16 v[114:117], v[142:145], v[190:193], v[114:117]
	v_mfma_f32_16x16x32_bf16 v[110:113], v[134:137], v[206:209], v[110:113]
	v_mfma_f32_16x16x32_bf16 v[106:109], v[142:145], v[206:209], v[106:109]
	v_mfma_f32_16x16x32_bf16 v[102:105], v[134:137], v[214:217], v[102:105]
	v_mfma_f32_16x16x32_bf16 v[98:101], v[142:145], v[214:217], v[98:101]
	v_mfma_f32_16x16x32_bf16 v[62:65], v[146:149], v[178:181], v[62:65]
	v_mfma_f32_16x16x32_bf16 v[58:61], v[170:173], v[178:181], v[58:61]
	v_mfma_f32_16x16x32_bf16 v[54:57], v[146:149], v[186:189], v[54:57]
	v_mfma_f32_16x16x32_bf16 v[50:53], v[170:173], v[186:189], v[50:53]
	v_mfma_f32_16x16x32_bf16 v[46:49], v[146:149], v[202:205], v[46:49]
	v_mfma_f32_16x16x32_bf16 v[42:45], v[170:173], v[202:205], v[42:45]
	v_mfma_f32_16x16x32_bf16 v[38:41], v[146:149], v[210:213], v[38:41]
	v_mfma_f32_16x16x32_bf16 v[34:37], v[170:173], v[210:213], v[34:37]
	v_mfma_f32_16x16x32_bf16 v[62:65], v[166:169], v[182:185], v[62:65]
	v_mfma_f32_16x16x32_bf16 v[58:61], v[174:177], v[182:185], v[58:61]
	v_mfma_f32_16x16x32_bf16 v[54:57], v[166:169], v[190:193], v[54:57]
	v_mfma_f32_16x16x32_bf16 v[50:53], v[174:177], v[190:193], v[50:53]
	v_mfma_f32_16x16x32_bf16 v[46:49], v[166:169], v[206:209], v[46:49]
	v_mfma_f32_16x16x32_bf16 v[42:45], v[174:177], v[206:209], v[42:45]
	v_mfma_f32_16x16x32_bf16 v[38:41], v[166:169], v[214:217], v[38:41]
	v_mfma_f32_16x16x32_bf16 v[34:37], v[174:177], v[214:217], v[34:37]
	s_setprio 0
	s_barrier
	s_add_i32 s53, s46, s38
	v_lshl_add_u64 v[194:195], s[34:35], 0, v[152:153]
	s_mov_b32 m0, s53
	ds_read_b128 v[178:181], v201 offset:16384
	ds_read_b128 v[182:185], v201 offset:17408
	ds_read_b128 v[186:189], v201 offset:18432
	ds_read_b128 v[190:193], v201 offset:19456
	ds_read_b128 v[202:205], v201 offset:20480
	ds_read_b128 v[206:209], v201 offset:21504
	ds_read_b128 v[210:213], v201 offset:22528
	ds_read_b128 v[214:217], v201 offset:23552
	global_load_lds_dwordx4 v[194:195], off
	s_add_i32 m0, s53, 0x2000
	s_add_u32 s54, s34, 0x100000
	v_lshl_add_u64 v[218:219], s[34:35], 0, v[156:157]
	s_addc_u32 s55, s35, 0
	s_add_i32 s53, s47, s38
	global_load_lds_dwordx4 v[218:219], off
	v_lshl_add_u64 v[220:221], s[54:55], 0, v[152:153]
	s_mov_b32 m0, s53
	v_lshl_add_u64 v[222:223], s[36:37], 0, v[154:155]
	global_load_lds_dwordx4 v[220:221], off
	v_lshl_add_u64 v[220:221], s[54:55], 0, v[156:157]
	s_add_i32 m0, s53, 0x2000
	s_nop 0
	global_load_lds_dwordx4 v[220:221], off
	v_lshl_add_u64 v[220:221], s[36:37], 0, v[150:151]
	s_mov_b32 m0, s29
	s_nop 0
	global_load_lds_dwordx4 v[220:221], off
	s_mov_b32 m0, s39
	s_nop 0
	global_load_lds_dwordx4 v[222:223], off
	s_waitcnt vmcnt(8)
	s_waitcnt lgkmcnt(0)
	s_barrier
	s_setprio 1
	v_mfma_f32_16x16x32_bf16 v[94:97], v[130:133], v[178:181], v[94:97]
	v_mfma_f32_16x16x32_bf16 v[90:93], v[138:141], v[178:181], v[90:93]
	v_mfma_f32_16x16x32_bf16 v[86:89], v[130:133], v[186:189], v[86:89]
	v_mfma_f32_16x16x32_bf16 v[82:85], v[138:141], v[186:189], v[82:85]
	v_mfma_f32_16x16x32_bf16 v[78:81], v[130:133], v[202:205], v[78:81]
	v_mfma_f32_16x16x32_bf16 v[74:77], v[138:141], v[202:205], v[74:77]
	v_mfma_f32_16x16x32_bf16 v[70:73], v[130:133], v[210:213], v[70:73]
	v_mfma_f32_16x16x32_bf16 v[66:69], v[138:141], v[210:213], v[66:69]
	v_mfma_f32_16x16x32_bf16 v[94:97], v[134:137], v[182:185], v[94:97]
	v_mfma_f32_16x16x32_bf16 v[90:93], v[142:145], v[182:185], v[90:93]
	v_mfma_f32_16x16x32_bf16 v[86:89], v[134:137], v[190:193], v[86:89]
	v_mfma_f32_16x16x32_bf16 v[82:85], v[142:145], v[190:193], v[82:85]
	v_mfma_f32_16x16x32_bf16 v[78:81], v[134:137], v[206:209], v[78:81]
	v_mfma_f32_16x16x32_bf16 v[74:77], v[142:145], v[206:209], v[74:77]
	v_mfma_f32_16x16x32_bf16 v[70:73], v[134:137], v[214:217], v[70:73]
	v_mfma_f32_16x16x32_bf16 v[66:69], v[142:145], v[214:217], v[66:69]
	v_mfma_f32_16x16x32_bf16 v[30:33], v[146:149], v[178:181], v[30:33]
	v_mfma_f32_16x16x32_bf16 v[26:29], v[170:173], v[178:181], v[26:29]
	v_mfma_f32_16x16x32_bf16 v[22:25], v[146:149], v[186:189], v[22:25]
	v_mfma_f32_16x16x32_bf16 v[18:21], v[170:173], v[186:189], v[18:21]
	v_mfma_f32_16x16x32_bf16 v[14:17], v[146:149], v[202:205], v[14:17]
	v_mfma_f32_16x16x32_bf16 v[10:13], v[170:173], v[202:205], v[10:13]
	v_mfma_f32_16x16x32_bf16 v[6:9], v[146:149], v[210:213], v[6:9]
	v_mfma_f32_16x16x32_bf16 v[2:5], v[170:173], v[210:213], v[2:5]
	v_mfma_f32_16x16x32_bf16 v[30:33], v[166:169], v[182:185], v[30:33]
	v_mfma_f32_16x16x32_bf16 v[26:29], v[174:177], v[182:185], v[26:29]
	v_mfma_f32_16x16x32_bf16 v[22:25], v[166:169], v[190:193], v[22:25]
	v_mfma_f32_16x16x32_bf16 v[18:21], v[174:177], v[190:193], v[18:21]
	v_mfma_f32_16x16x32_bf16 v[14:17], v[166:169], v[206:209], v[14:17]
	v_mfma_f32_16x16x32_bf16 v[10:13], v[174:177], v[206:209], v[10:13]
	v_mfma_f32_16x16x32_bf16 v[6:9], v[166:169], v[214:217], v[6:9]
	v_mfma_f32_16x16x32_bf16 v[2:5], v[174:177], v[214:217], v[2:5]
	s_setprio 0
	s_barrier
	s_add_i32 s53, 0, 0x18000
	s_add_i32 s54, 0, 0x1c000
	v_add_u32_e32 v142, s53, v197
	v_add_u32_e32 v174, s54, v197
	ds_read_b128 v[130:133], v142
	ds_read_b128 v[134:137], v142 offset:1024
	ds_read_b128 v[138:141], v142 offset:2048
	ds_read_b128 v[142:145], v142 offset:3072
	ds_read_b128 v[146:149], v174
	ds_read_b128 v[166:169], v174 offset:1024
	ds_read_b128 v[170:173], v174 offset:2048
	ds_read_b128 v[174:177], v174 offset:3072
	s_add_u32 s36, s36, 0x100000
	s_addc_u32 s37, s37, 0
	s_mov_b32 m0, s40
	v_lshl_add_u64 v[224:225], s[36:37], 0, v[150:151]
	ds_read_b128 v[178:181], v201 offset:32768
	ds_read_b128 v[182:185], v201 offset:33792
	ds_read_b128 v[186:189], v201 offset:34816
	ds_read_b128 v[190:193], v201 offset:35840
	ds_read_b128 v[202:205], v201 offset:36864
	ds_read_b128 v[206:209], v201 offset:37888
	ds_read_b128 v[210:213], v201 offset:38912
	ds_read_b128 v[214:217], v201 offset:39936
	global_load_lds_dwordx4 v[224:225], off
	v_lshl_add_u64 v[224:225], s[36:37], 0, v[154:155]
	s_mov_b32 m0, s41
	s_nop 0
	global_load_lds_dwordx4 v[224:225], off
	s_waitcnt vmcnt(8)
	s_waitcnt lgkmcnt(0)
	s_barrier
	s_setprio 1
	v_mfma_f32_16x16x32_bf16 v[126:129], v[130:133], v[178:181], v[126:129]
	v_mfma_f32_16x16x32_bf16 v[122:125], v[138:141], v[178:181], v[122:125]
	v_mfma_f32_16x16x32_bf16 v[118:121], v[130:133], v[186:189], v[118:121]
	v_mfma_f32_16x16x32_bf16 v[114:117], v[138:141], v[186:189], v[114:117]
	v_mfma_f32_16x16x32_bf16 v[110:113], v[130:133], v[202:205], v[110:113]
	v_mfma_f32_16x16x32_bf16 v[106:109], v[138:141], v[202:205], v[106:109]
	v_mfma_f32_16x16x32_bf16 v[102:105], v[130:133], v[210:213], v[102:105]
	v_mfma_f32_16x16x32_bf16 v[98:101], v[138:141], v[210:213], v[98:101]
	v_mfma_f32_16x16x32_bf16 v[126:129], v[134:137], v[182:185], v[126:129]
	v_mfma_f32_16x16x32_bf16 v[122:125], v[142:145], v[182:185], v[122:125]
	v_mfma_f32_16x16x32_bf16 v[118:121], v[134:137], v[190:193], v[118:121]
	v_mfma_f32_16x16x32_bf16 v[114:117], v[142:145], v[190:193], v[114:117]
	v_mfma_f32_16x16x32_bf16 v[110:113], v[134:137], v[206:209], v[110:113]
	v_mfma_f32_16x16x32_bf16 v[106:109], v[142:145], v[206:209], v[106:109]
	v_mfma_f32_16x16x32_bf16 v[102:105], v[134:137], v[214:217], v[102:105]
	v_mfma_f32_16x16x32_bf16 v[98:101], v[142:145], v[214:217], v[98:101]
	v_mfma_f32_16x16x32_bf16 v[62:65], v[146:149], v[178:181], v[62:65]
	v_mfma_f32_16x16x32_bf16 v[58:61], v[170:173], v[178:181], v[58:61]
	v_mfma_f32_16x16x32_bf16 v[54:57], v[146:149], v[186:189], v[54:57]
	v_mfma_f32_16x16x32_bf16 v[50:53], v[170:173], v[186:189], v[50:53]
	v_mfma_f32_16x16x32_bf16 v[46:49], v[146:149], v[202:205], v[46:49]
	v_mfma_f32_16x16x32_bf16 v[42:45], v[170:173], v[202:205], v[42:45]
	v_mfma_f32_16x16x32_bf16 v[38:41], v[146:149], v[210:213], v[38:41]
	v_mfma_f32_16x16x32_bf16 v[34:37], v[170:173], v[210:213], v[34:37]
	v_mfma_f32_16x16x32_bf16 v[62:65], v[166:169], v[182:185], v[62:65]
	v_mfma_f32_16x16x32_bf16 v[58:61], v[174:177], v[182:185], v[58:61]
	v_mfma_f32_16x16x32_bf16 v[54:57], v[166:169], v[190:193], v[54:57]
	v_mfma_f32_16x16x32_bf16 v[50:53], v[174:177], v[190:193], v[50:53]
	v_mfma_f32_16x16x32_bf16 v[46:49], v[166:169], v[206:209], v[46:49]
	v_mfma_f32_16x16x32_bf16 v[42:45], v[174:177], v[206:209], v[42:45]
	v_mfma_f32_16x16x32_bf16 v[38:41], v[166:169], v[214:217], v[38:41]
	v_mfma_f32_16x16x32_bf16 v[34:37], v[174:177], v[214:217], v[34:37]
	s_setprio 0
	s_barrier
	s_add_i32 s36, s53, s38
	v_lshl_add_u64 v[194:195], v[194:195], 0, s[14:15]
	s_mov_b32 m0, s36
	ds_read_b128 v[178:181], v201 offset:49152
	ds_read_b128 v[182:185], v201 offset:50176
	ds_read_b128 v[186:189], v201 offset:51200
	ds_read_b128 v[190:193], v201 offset:52224
	ds_read_b128 v[202:205], v201 offset:53248
	ds_read_b128 v[206:209], v201 offset:54272
	ds_read_b128 v[210:213], v201 offset:55296
	ds_read_b128 v[214:217], v201 offset:56320
	global_load_lds_dwordx4 v[194:195], off
	s_add_i32 m0, s36, 0x2000
	s_add_u32 s34, s34, 0x100080
	v_lshl_add_u64 v[194:195], v[218:219], 0, s[14:15]
	s_addc_u32 s35, s35, 0
	s_add_i32 s36, s54, s38
	global_load_lds_dwordx4 v[194:195], off
	v_lshl_add_u64 v[194:195], s[34:35], 0, v[152:153]
	s_mov_b32 m0, s36
	s_nop 0
	global_load_lds_dwordx4 v[194:195], off
	v_lshl_add_u64 v[194:195], s[34:35], 0, v[156:157]
	s_add_i32 m0, s36, 0x2000
	s_nop 0
	global_load_lds_dwordx4 v[194:195], off
	v_lshl_add_u64 v[194:195], v[220:221], 0, s[14:15]
	s_mov_b32 m0, s43
	s_nop 0
	global_load_lds_dwordx4 v[194:195], off
	v_lshl_add_u64 v[194:195], v[222:223], 0, s[14:15]
	s_mov_b32 m0, s44
	s_nop 0
	global_load_lds_dwordx4 v[194:195], off
	s_waitcnt vmcnt(8)
	s_waitcnt lgkmcnt(0)
	s_barrier
	s_setprio 1
	v_mfma_f32_16x16x32_bf16 v[94:97], v[130:133], v[178:181], v[94:97]
	v_mfma_f32_16x16x32_bf16 v[90:93], v[138:141], v[178:181], v[90:93]
	v_mfma_f32_16x16x32_bf16 v[86:89], v[130:133], v[186:189], v[86:89]
	v_mfma_f32_16x16x32_bf16 v[82:85], v[138:141], v[186:189], v[82:85]
	v_mfma_f32_16x16x32_bf16 v[78:81], v[130:133], v[202:205], v[78:81]
	v_mfma_f32_16x16x32_bf16 v[74:77], v[138:141], v[202:205], v[74:77]
	v_mfma_f32_16x16x32_bf16 v[70:73], v[130:133], v[210:213], v[70:73]
	v_mfma_f32_16x16x32_bf16 v[66:69], v[138:141], v[210:213], v[66:69]
	v_mfma_f32_16x16x32_bf16 v[94:97], v[134:137], v[182:185], v[94:97]
	v_mfma_f32_16x16x32_bf16 v[90:93], v[142:145], v[182:185], v[90:93]
	v_mfma_f32_16x16x32_bf16 v[86:89], v[134:137], v[190:193], v[86:89]
	v_mfma_f32_16x16x32_bf16 v[82:85], v[142:145], v[190:193], v[82:85]
	v_mfma_f32_16x16x32_bf16 v[78:81], v[134:137], v[206:209], v[78:81]
	v_mfma_f32_16x16x32_bf16 v[74:77], v[142:145], v[206:209], v[74:77]
	v_mfma_f32_16x16x32_bf16 v[70:73], v[134:137], v[214:217], v[70:73]
	v_mfma_f32_16x16x32_bf16 v[66:69], v[142:145], v[214:217], v[66:69]
	v_mfma_f32_16x16x32_bf16 v[30:33], v[146:149], v[178:181], v[30:33]
	v_mfma_f32_16x16x32_bf16 v[26:29], v[170:173], v[178:181], v[26:29]
	v_mfma_f32_16x16x32_bf16 v[22:25], v[146:149], v[186:189], v[22:25]
	v_mfma_f32_16x16x32_bf16 v[18:21], v[170:173], v[186:189], v[18:21]
	v_mfma_f32_16x16x32_bf16 v[14:17], v[146:149], v[202:205], v[14:17]
	v_mfma_f32_16x16x32_bf16 v[10:13], v[170:173], v[202:205], v[10:13]
	v_mfma_f32_16x16x32_bf16 v[6:9], v[146:149], v[210:213], v[6:9]
	v_mfma_f32_16x16x32_bf16 v[2:5], v[170:173], v[210:213], v[2:5]
	v_mfma_f32_16x16x32_bf16 v[30:33], v[166:169], v[182:185], v[30:33]
	v_mfma_f32_16x16x32_bf16 v[26:29], v[174:177], v[182:185], v[26:29]
	v_mfma_f32_16x16x32_bf16 v[22:25], v[166:169], v[190:193], v[22:25]
	v_mfma_f32_16x16x32_bf16 v[18:21], v[174:177], v[190:193], v[18:21]
	v_mfma_f32_16x16x32_bf16 v[14:17], v[166:169], v[206:209], v[14:17]
	v_mfma_f32_16x16x32_bf16 v[10:13], v[174:177], v[206:209], v[10:13]
	v_mfma_f32_16x16x32_bf16 v[6:9], v[166:169], v[214:217], v[6:9]
	v_mfma_f32_16x16x32_bf16 v[2:5], v[174:177], v[214:217], v[2:5]
	s_setprio 0
	s_barrier
	s_add_i32 s52, s52, 2
	s_add_u32 s30, s30, 0x100
	s_addc_u32 s31, s31, 0
	s_add_u32 s50, s50, 0x100
	s_addc_u32 s51, s51, 0
	s_cmp_gt_u32 s52, 61
	s_cbranch_scc0 .LBB0_2142
	s_and_b64 vcc, exec, s[16:17]
	s_cbranch_vccz .LBB0_2145
	s_barrier

.LBB0_2369:
	ds_read_b128 v[130:133], v197
	ds_read_b128 v[134:137], v197 offset:1024
	ds_read_b128 v[138:141], v197 offset:2048
	ds_read_b128 v[142:145], v197 offset:3072
	ds_read_b128 v[146:149], v198
	ds_read_b128 v[166:169], v198 offset:1024
	ds_read_b128 v[170:173], v198 offset:2048
	ds_read_b128 v[174:177], v198 offset:3072
	s_add_u32 s28, s26, 0xffd50080
	s_addc_u32 s29, s27, -1
	s_cmpk_eq_i32 s52, 0xa8
	s_cselect_b32 s31, s9, s29
	s_cselect_b32 s30, s8, s28
	s_cselect_b32 s29, s25, s51
	s_cselect_b32 s28, s24, s50
	v_lshl_add_u64 v[216:217], s[26:27], 0, v[158:159]
	s_add_i32 m0, s37, 0xc000
	ds_read_b128 v[178:181], v199
	ds_read_b128 v[182:185], v199 offset:1024
	ds_read_b128 v[186:189], v199 offset:2048
	ds_read_b128 v[190:193], v199 offset:3072
	ds_read_b128 v[200:203], v199 offset:4096
	ds_read_b128 v[204:207], v199 offset:5120
	ds_read_b128 v[208:211], v199 offset:6144
	ds_read_b128 v[212:215], v199 offset:7168
	global_load_lds_dwordx4 v[216:217], off
	v_lshl_add_u64 v[216:217], s[26:27], 0, v[160:161]
	s_add_i32 m0, s37, 0xe000
	s_nop 0
	global_load_lds_dwordx4 v[216:217], off
	s_waitcnt vmcnt(8)
	s_waitcnt lgkmcnt(0)
	s_barrier
	s_setprio 1
	v_mfma_f32_16x16x32_bf16 v[126:129], v[130:133], v[178:181], v[126:129]
	v_mfma_f32_16x16x32_bf16 v[122:125], v[138:141], v[178:181], v[122:125]
	v_mfma_f32_16x16x32_bf16 v[118:121], v[130:133], v[186:189], v[118:121]
	v_mfma_f32_16x16x32_bf16 v[114:117], v[138:141], v[186:189], v[114:117]
	v_mfma_f32_16x16x32_bf16 v[110:113], v[130:133], v[200:203], v[110:113]
	v_mfma_f32_16x16x32_bf16 v[106:109], v[138:141], v[200:203], v[106:109]
	v_mfma_f32_16x16x32_bf16 v[102:105], v[130:133], v[208:211], v[102:105]
	v_mfma_f32_16x16x32_bf16 v[98:101], v[138:141], v[208:211], v[98:101]
	v_mfma_f32_16x16x32_bf16 v[126:129], v[134:137], v[182:185], v[126:129]
	v_mfma_f32_16x16x32_bf16 v[122:125], v[142:145], v[182:185], v[122:125]
	v_mfma_f32_16x16x32_bf16 v[118:121], v[134:137], v[190:193], v[118:121]
	v_mfma_f32_16x16x32_bf16 v[114:117], v[142:145], v[190:193], v[114:117]
	v_mfma_f32_16x16x32_bf16 v[110:113], v[134:137], v[204:207], v[110:113]
	v_mfma_f32_16x16x32_bf16 v[106:109], v[142:145], v[204:207], v[106:109]
	v_mfma_f32_16x16x32_bf16 v[102:105], v[134:137], v[212:215], v[102:105]
	v_mfma_f32_16x16x32_bf16 v[98:101], v[142:145], v[212:215], v[98:101]
	v_mfma_f32_16x16x32_bf16 v[62:65], v[146:149], v[178:181], v[62:65]
	v_mfma_f32_16x16x32_bf16 v[58:61], v[170:173], v[178:181], v[58:61]
	v_mfma_f32_16x16x32_bf16 v[54:57], v[146:149], v[186:189], v[54:57]
	v_mfma_f32_16x16x32_bf16 v[50:53], v[170:173], v[186:189], v[50:53]
	v_mfma_f32_16x16x32_bf16 v[46:49], v[146:149], v[200:203], v[46:49]
	v_mfma_f32_16x16x32_bf16 v[42:45], v[170:173], v[200:203], v[42:45]
	v_mfma_f32_16x16x32_bf16 v[38:41], v[146:149], v[208:211], v[38:41]
	v_mfma_f32_16x16x32_bf16 v[34:37], v[170:173], v[208:211], v[34:37]
	v_mfma_f32_16x16x32_bf16 v[62:65], v[166:169], v[182:185], v[62:65]
	v_mfma_f32_16x16x32_bf16 v[58:61], v[174:177], v[182:185], v[58:61]
	v_mfma_f32_16x16x32_bf16 v[54:57], v[166:169], v[190:193], v[54:57]
	v_mfma_f32_16x16x32_bf16 v[50:53], v[174:177], v[190:193], v[50:53]
	v_mfma_f32_16x16x32_bf16 v[46:49], v[166:169], v[204:207], v[46:49]
	v_mfma_f32_16x16x32_bf16 v[42:45], v[174:177], v[204:207], v[42:45]
	v_mfma_f32_16x16x32_bf16 v[38:41], v[166:169], v[212:215], v[38:41]
	v_mfma_f32_16x16x32_bf16 v[34:37], v[174:177], v[212:215], v[34:37]
	s_setprio 0
	s_barrier
	s_add_i32 s53, s45, s36
	v_lshl_add_u64 v[216:217], s[28:29], 0, v[152:153]
	s_mov_b32 m0, s53
	ds_read_b128 v[178:181], v199 offset:16384
	ds_read_b128 v[182:185], v199 offset:17408
	ds_read_b128 v[186:189], v199 offset:18432
	ds_read_b128 v[190:193], v199 offset:19456
	ds_read_b128 v[200:203], v199 offset:20480
	ds_read_b128 v[204:207], v199 offset:21504
	ds_read_b128 v[208:211], v199 offset:22528
	ds_read_b128 v[212:215], v199 offset:23552
	global_load_lds_dwordx4 v[216:217], off
	s_add_i32 m0, s53, 0x2000
	s_add_u32 s54, s28, 0x2b0000
	v_lshl_add_u64 v[218:219], s[28:29], 0, v[156:157]
	s_addc_u32 s55, s29, 0
	s_add_i32 s53, s46, s36
	global_load_lds_dwordx4 v[218:219], off
	v_lshl_add_u64 v[220:221], s[54:55], 0, v[152:153]
	s_mov_b32 m0, s53
	v_lshl_add_u64 v[222:223], s[30:31], 0, v[154:155]
	global_load_lds_dwordx4 v[220:221], off
	v_lshl_add_u64 v[220:221], s[54:55], 0, v[156:157]
	s_add_i32 m0, s53, 0x2000
	s_nop 0
	global_load_lds_dwordx4 v[220:221], off
	v_lshl_add_u64 v[220:221], s[30:31], 0, v[150:151]
	s_mov_b32 m0, s37
	s_nop 0
	global_load_lds_dwordx4 v[220:221], off
	s_mov_b32 m0, s38
	s_nop 0
	global_load_lds_dwordx4 v[222:223], off
	s_waitcnt vmcnt(8)
	s_waitcnt lgkmcnt(0)
	s_barrier
	s_setprio 1
	v_mfma_f32_16x16x32_bf16 v[94:97], v[130:133], v[178:181], v[94:97]
	v_mfma_f32_16x16x32_bf16 v[90:93], v[138:141], v[178:181], v[90:93]
	v_mfma_f32_16x16x32_bf16 v[86:89], v[130:133], v[186:189], v[86:89]
	v_mfma_f32_16x16x32_bf16 v[82:85], v[138:141], v[186:189], v[82:85]
	v_mfma_f32_16x16x32_bf16 v[78:81], v[130:133], v[200:203], v[78:81]
	v_mfma_f32_16x16x32_bf16 v[74:77], v[138:141], v[200:203], v[74:77]
	v_mfma_f32_16x16x32_bf16 v[70:73], v[130:133], v[208:211], v[70:73]
	v_mfma_f32_16x16x32_bf16 v[66:69], v[138:141], v[208:211], v[66:69]
	v_mfma_f32_16x16x32_bf16 v[94:97], v[134:137], v[182:185], v[94:97]
	v_mfma_f32_16x16x32_bf16 v[90:93], v[142:145], v[182:185], v[90:93]
	v_mfma_f32_16x16x32_bf16 v[86:89], v[134:137], v[190:193], v[86:89]
	v_mfma_f32_16x16x32_bf16 v[82:85], v[142:145], v[190:193], v[82:85]
	v_mfma_f32_16x16x32_bf16 v[78:81], v[134:137], v[204:207], v[78:81]
	v_mfma_f32_16x16x32_bf16 v[74:77], v[142:145], v[204:207], v[74:77]
	v_mfma_f32_16x16x32_bf16 v[70:73], v[134:137], v[212:215], v[70:73]
	v_mfma_f32_16x16x32_bf16 v[66:69], v[142:145], v[212:215], v[66:69]
	v_mfma_f32_16x16x32_bf16 v[30:33], v[146:149], v[178:181], v[30:33]
	v_mfma_f32_16x16x32_bf16 v[26:29], v[170:173], v[178:181], v[26:29]
	v_mfma_f32_16x16x32_bf16 v[22:25], v[146:149], v[186:189], v[22:25]
	v_mfma_f32_16x16x32_bf16 v[18:21], v[170:173], v[186:189], v[18:21]
	v_mfma_f32_16x16x32_bf16 v[14:17], v[146:149], v[200:203], v[14:17]
	v_mfma_f32_16x16x32_bf16 v[10:13], v[170:173], v[200:203], v[10:13]
	v_mfma_f32_16x16x32_bf16 v[6:9], v[146:149], v[208:211], v[6:9]
	v_mfma_f32_16x16x32_bf16 v[2:5], v[170:173], v[208:211], v[2:5]
	v_mfma_f32_16x16x32_bf16 v[30:33], v[166:169], v[182:185], v[30:33]
	v_mfma_f32_16x16x32_bf16 v[26:29], v[174:177], v[182:185], v[26:29]
	v_mfma_f32_16x16x32_bf16 v[22:25], v[166:169], v[190:193], v[22:25]
	v_mfma_f32_16x16x32_bf16 v[18:21], v[174:177], v[190:193], v[18:21]
	v_mfma_f32_16x16x32_bf16 v[14:17], v[166:169], v[204:207], v[14:17]
	v_mfma_f32_16x16x32_bf16 v[10:13], v[174:177], v[204:207], v[10:13]
	v_mfma_f32_16x16x32_bf16 v[6:9], v[166:169], v[212:215], v[6:9]
	v_mfma_f32_16x16x32_bf16 v[2:5], v[174:177], v[212:215], v[2:5]
	s_setprio 0
	s_barrier
	s_add_i32 s53, 0, 0x18000
	s_add_i32 s54, 0, 0x1c000
	v_add_u32_e32 v142, s53, v195
	v_add_u32_e32 v174, s54, v195
	ds_read_b128 v[130:133], v142
	ds_read_b128 v[134:137], v142 offset:1024
	ds_read_b128 v[138:141], v142 offset:2048
	ds_read_b128 v[142:145], v142 offset:3072
	ds_read_b128 v[146:149], v174
	ds_read_b128 v[166:169], v174 offset:1024
	ds_read_b128 v[170:173], v174 offset:2048
	ds_read_b128 v[174:177], v174 offset:3072
	s_add_u32 s30, s30, 0x2b0000
	s_addc_u32 s31, s31, 0
	s_mov_b32 m0, s39
	v_lshl_add_u64 v[224:225], s[30:31], 0, v[150:151]
	ds_read_b128 v[178:181], v199 offset:32768
	ds_read_b128 v[182:185], v199 offset:33792
	ds_read_b128 v[186:189], v199 offset:34816
	ds_read_b128 v[190:193], v199 offset:35840
	ds_read_b128 v[200:203], v199 offset:36864
	ds_read_b128 v[204:207], v199 offset:37888
	ds_read_b128 v[208:211], v199 offset:38912
	ds_read_b128 v[212:215], v199 offset:39936
	global_load_lds_dwordx4 v[224:225], off
	v_lshl_add_u64 v[224:225], s[30:31], 0, v[154:155]
	s_mov_b32 m0, s40
	s_nop 0
	global_load_lds_dwordx4 v[224:225], off
	s_waitcnt vmcnt(8)
	s_waitcnt lgkmcnt(0)
	s_barrier
	s_setprio 1
	v_mfma_f32_16x16x32_bf16 v[126:129], v[130:133], v[178:181], v[126:129]
	v_mfma_f32_16x16x32_bf16 v[122:125], v[138:141], v[178:181], v[122:125]
	v_mfma_f32_16x16x32_bf16 v[118:121], v[130:133], v[186:189], v[118:121]
	v_mfma_f32_16x16x32_bf16 v[114:117], v[138:141], v[186:189], v[114:117]
	v_mfma_f32_16x16x32_bf16 v[110:113], v[130:133], v[200:203], v[110:113]
	v_mfma_f32_16x16x32_bf16 v[106:109], v[138:141], v[200:203], v[106:109]
	v_mfma_f32_16x16x32_bf16 v[102:105], v[130:133], v[208:211], v[102:105]
	v_mfma_f32_16x16x32_bf16 v[98:101], v[138:141], v[208:211], v[98:101]
	v_mfma_f32_16x16x32_bf16 v[126:129], v[134:137], v[182:185], v[126:129]
	v_mfma_f32_16x16x32_bf16 v[122:125], v[142:145], v[182:185], v[122:125]
	v_mfma_f32_16x16x32_bf16 v[118:121], v[134:137], v[190:193], v[118:121]
	v_mfma_f32_16x16x32_bf16 v[114:117], v[142:145], v[190:193], v[114:117]
	v_mfma_f32_16x16x32_bf16 v[110:113], v[134:137], v[204:207], v[110:113]
	v_mfma_f32_16x16x32_bf16 v[106:109], v[142:145], v[204:207], v[106:109]
	v_mfma_f32_16x16x32_bf16 v[102:105], v[134:137], v[212:215], v[102:105]
	v_mfma_f32_16x16x32_bf16 v[98:101], v[142:145], v[212:215], v[98:101]
	v_mfma_f32_16x16x32_bf16 v[62:65], v[146:149], v[178:181], v[62:65]
	v_mfma_f32_16x16x32_bf16 v[58:61], v[170:173], v[178:181], v[58:61]
	v_mfma_f32_16x16x32_bf16 v[54:57], v[146:149], v[186:189], v[54:57]
	v_mfma_f32_16x16x32_bf16 v[50:53], v[170:173], v[186:189], v[50:53]
	v_mfma_f32_16x16x32_bf16 v[46:49], v[146:149], v[200:203], v[46:49]
	v_mfma_f32_16x16x32_bf16 v[42:45], v[170:173], v[200:203], v[42:45]
	v_mfma_f32_16x16x32_bf16 v[38:41], v[146:149], v[208:211], v[38:41]
	v_mfma_f32_16x16x32_bf16 v[34:37], v[170:173], v[208:211], v[34:37]
	v_mfma_f32_16x16x32_bf16 v[62:65], v[166:169], v[182:185], v[62:65]
	v_mfma_f32_16x16x32_bf16 v[58:61], v[174:177], v[182:185], v[58:61]
	v_mfma_f32_16x16x32_bf16 v[54:57], v[166:169], v[190:193], v[54:57]
	v_mfma_f32_16x16x32_bf16 v[50:53], v[174:177], v[190:193], v[50:53]
	v_mfma_f32_16x16x32_bf16 v[46:49], v[166:169], v[204:207], v[46:49]
	v_mfma_f32_16x16x32_bf16 v[42:45], v[174:177], v[204:207], v[42:45]
	v_mfma_f32_16x16x32_bf16 v[38:41], v[166:169], v[212:215], v[38:41]
	v_mfma_f32_16x16x32_bf16 v[34:37], v[174:177], v[212:215], v[34:37]
	s_setprio 0
	s_barrier
	s_add_i32 s30, s53, s36
	v_lshl_add_u64 v[216:217], v[216:217], 0, s[18:19]
	s_mov_b32 m0, s30
	ds_read_b128 v[178:181], v199 offset:49152
	ds_read_b128 v[182:185], v199 offset:50176
	ds_read_b128 v[186:189], v199 offset:51200
	ds_read_b128 v[190:193], v199 offset:52224
	ds_read_b128 v[200:203], v199 offset:53248
	ds_read_b128 v[204:207], v199 offset:54272
	ds_read_b128 v[208:211], v199 offset:55296
	ds_read_b128 v[212:215], v199 offset:56320
	global_load_lds_dwordx4 v[216:217], off
	s_add_i32 m0, s30, 0x2000
	s_add_u32 s28, s28, 0x2b0080
	v_lshl_add_u64 v[216:217], v[218:219], 0, s[18:19]
	s_addc_u32 s29, s29, 0
	s_add_i32 s30, s54, s36
	global_load_lds_dwordx4 v[216:217], off
	v_lshl_add_u64 v[216:217], s[28:29], 0, v[152:153]
	s_mov_b32 m0, s30
	s_nop 0
	global_load_lds_dwordx4 v[216:217], off
	v_lshl_add_u64 v[216:217], s[28:29], 0, v[156:157]
	s_add_i32 m0, s30, 0x2000
	s_nop 0
	global_load_lds_dwordx4 v[216:217], off
	v_lshl_add_u64 v[216:217], v[220:221], 0, s[18:19]
	s_mov_b32 m0, s42
	s_nop 0
	global_load_lds_dwordx4 v[216:217], off
	v_lshl_add_u64 v[216:217], v[222:223], 0, s[18:19]
	s_mov_b32 m0, s43
	s_nop 0
	global_load_lds_dwordx4 v[216:217], off
	s_waitcnt vmcnt(8)
	s_waitcnt lgkmcnt(0)
	s_barrier
	s_setprio 1
	v_mfma_f32_16x16x32_bf16 v[94:97], v[130:133], v[178:181], v[94:97]
	v_mfma_f32_16x16x32_bf16 v[90:93], v[138:141], v[178:181], v[90:93]
	v_mfma_f32_16x16x32_bf16 v[86:89], v[130:133], v[186:189], v[86:89]
	v_mfma_f32_16x16x32_bf16 v[82:85], v[138:141], v[186:189], v[82:85]
	v_mfma_f32_16x16x32_bf16 v[78:81], v[130:133], v[200:203], v[78:81]
	v_mfma_f32_16x16x32_bf16 v[74:77], v[138:141], v[200:203], v[74:77]
	v_mfma_f32_16x16x32_bf16 v[70:73], v[130:133], v[208:211], v[70:73]
	v_mfma_f32_16x16x32_bf16 v[66:69], v[138:141], v[208:211], v[66:69]
	v_mfma_f32_16x16x32_bf16 v[94:97], v[134:137], v[182:185], v[94:97]
	v_mfma_f32_16x16x32_bf16 v[90:93], v[142:145], v[182:185], v[90:93]
	v_mfma_f32_16x16x32_bf16 v[86:89], v[134:137], v[190:193], v[86:89]
	v_mfma_f32_16x16x32_bf16 v[82:85], v[142:145], v[190:193], v[82:85]
	v_mfma_f32_16x16x32_bf16 v[78:81], v[134:137], v[204:207], v[78:81]
	v_mfma_f32_16x16x32_bf16 v[74:77], v[142:145], v[204:207], v[74:77]
	v_mfma_f32_16x16x32_bf16 v[70:73], v[134:137], v[212:215], v[70:73]
	v_mfma_f32_16x16x32_bf16 v[66:69], v[142:145], v[212:215], v[66:69]
	v_mfma_f32_16x16x32_bf16 v[30:33], v[146:149], v[178:181], v[30:33]
	v_mfma_f32_16x16x32_bf16 v[26:29], v[170:173], v[178:181], v[26:29]
	v_mfma_f32_16x16x32_bf16 v[22:25], v[146:149], v[186:189], v[22:25]
	v_mfma_f32_16x16x32_bf16 v[18:21], v[170:173], v[186:189], v[18:21]
	v_mfma_f32_16x16x32_bf16 v[14:17], v[146:149], v[200:203], v[14:17]
	v_mfma_f32_16x16x32_bf16 v[10:13], v[170:173], v[200:203], v[10:13]
	v_mfma_f32_16x16x32_bf16 v[6:9], v[146:149], v[208:211], v[6:9]
	v_mfma_f32_16x16x32_bf16 v[2:5], v[170:173], v[208:211], v[2:5]
	v_mfma_f32_16x16x32_bf16 v[30:33], v[166:169], v[182:185], v[30:33]
	v_mfma_f32_16x16x32_bf16 v[26:29], v[174:177], v[182:185], v[26:29]
	v_mfma_f32_16x16x32_bf16 v[22:25], v[166:169], v[190:193], v[22:25]
	v_mfma_f32_16x16x32_bf16 v[18:21], v[174:177], v[190:193], v[18:21]
	v_mfma_f32_16x16x32_bf16 v[14:17], v[166:169], v[204:207], v[14:17]
	v_mfma_f32_16x16x32_bf16 v[10:13], v[174:177], v[204:207], v[10:13]
	v_mfma_f32_16x16x32_bf16 v[6:9], v[166:169], v[212:215], v[6:9]
	v_mfma_f32_16x16x32_bf16 v[2:5], v[174:177], v[212:215], v[2:5]
	s_setprio 0
	s_barrier
	s_add_i32 s52, s52, 2
	s_add_u32 s26, s26, 0x100
	s_addc_u32 s27, s27, 0
	s_add_u32 s50, s50, 0x100
	s_addc_u32 s51, s51, 0
	s_cmpk_gt_u32 s52, 0xa9
	s_cbranch_scc0 .LBB0_2369
	s_and_b64 vcc, exec, s[20:21]
	s_cbranch_vccz .LBB0_2372
	s_barrier
